# t1 + K-loop counter/pointer update and exit compare moved from after the loop-back barrier into load segment 4; in-proj segment 1 address selects moved behind its DMAs
# speedup vs baseline: 1.0132x; 1.0023x over previous
; #define PG8_STAGE(bufoff, gbase, voff) do { _Pragma("unroll") for (int _i = 0; _i < 2; ++_i) \
;         __builtin_amdgcn_global_load_lds((const unsigned*)((const char*)(gbase) + (voff)[_i]), (LAS unsigned*)(lds + (bufoff) + ldsw + _i * 8192), 16, 0, 0); } while (0)
; #define PG8_LDA(dst, b, h) do { _Pragma("unroll") for (int m = 0; m < 4; ++m) _Pragma("unroll") for (int k = 0; k < 2; ++k) dst[m][k] = *(const LAS bf16x8*)(lds + PG8_SA(b, h) + aoff + m * 2048 + k * 1024); } while (0)
; #define PG8_LDB(dst, b, h) do { _Pragma("unroll") for (int n = 0; n < 2; ++n) _Pragma("unroll") for (int k = 0; k < 2; ++k) dst[n][k] = *(const LAS bf16x8*)(lds + PG8_SB(b, h) + boff + n * 2048 + k * 1024); } while (0)
; #define PG8_MMA(ai, bj, At, Bt) do { __builtin_amdgcn_s_setprio(1); _Pragma("unroll") for (int m = 0; m < 4; ++m) _Pragma("unroll") for (int n = 0; n < 2; ++n) _Pragma("unroll") for (int k = 0; k < 2; ++k) \
;         acc[ai][bj][m][n] = __builtin_amdgcn_mfma_f32_16x16x32_bf16(Bt[n][k], At[m][k], acc[ai][bj][m][n], 0, 0, 0); __builtin_amdgcn_s_setprio(0); } while (0)
; #define PG8_WAIT_V(n) asm volatile("s_waitcnt vmcnt(" #n ")" ::: "memory")
; #define PG8_WAIT_L(n) asm volatile("s_waitcnt lgkmcnt(" #n ")" ::: "memory")
; #define PG8_BAR __builtin_amdgcn_s_barrier()
; #define PG8_SCHED __builtin_amdgcn_sched_barrier(0)
; template <class Epi, class Sched, bool ALIGN_EPI, class Hook = NoHook>
; __device__ __forceinline__ void gemm_phase(LAS unsigned char* lds, const Gemm g, const Sched& S, const Epi& E, const Hook& H = Hook()) {
;     ...
;             const char* a1 = cA + (size_t)(t + 1) * kstep;
;             const char* a2 = last ? nA : cA + (size_t)(t + 2) * kstep; const char* b2 = last ? nB : cB + (size_t)(t + 2) * kstep;
;             const char* a3 = a2 + kstep; const char* b3 = b2 + kstep;
;             if (last && has_next) S.a_ready(nxt);
;             PG8_LDB(B0, 0, 0); PG8_LDB(B1, 0, 1); PG8_SCHED; PG8_LDA(At, 0, 0); PG8_STAGE(PG8_SA(1, 1), a1 + hA, voffA);
;             PG8_WAIT_V(8); PG8_WAIT_L(0); PG8_BAR; PG8_MMA(0, 0, At, B0); PG8_MMA(0, 1, At, B1); PG8_BAR; PG8_SCHED;
;             PG8_LDA(At, 0, 1); PG8_STAGE(PG8_SB(0, 0), b2, voffB); PG8_STAGE(PG8_SB(0, 1), b2 + hB, voffB); PG8_STAGE(PG8_SA(0, 0), a2, voffA);
;             PG8_WAIT_V(8); PG8_WAIT_L(0); PG8_BAR; PG8_MMA(1, 0, At, B0); PG8_MMA(1, 1, At, B1); PG8_BAR; PG8_SCHED;
.LBB0_199:
	ds_read_b128 v[130:133], v217
	ds_read_b128 v[134:137], v217 offset:1024
	s_add_i32 m0, s40, 0xc000
	s_nop 0
	global_load_lds_dwordx4 v172, s[4:5]
	ds_read_b128 v[138:141], v217 offset:2048
	ds_read_b128 v[142:145], v217 offset:3072
	ds_read_b128 v[146:149], v218
	ds_read_b128 v[150:153], v218 offset:1024
	ds_read_b128 v[154:157], v218 offset:2048
	ds_read_b128 v[158:161], v218 offset:3072
	ds_read_b128 v[180:183], v219
	s_add_i32 m0, s40, 0xe000
	s_nop 0
	global_load_lds_dwordx4 v174, s[4:5]
	s_add_u32 s34, s4, 0x100
	s_addc_u32 s35, s5, 0
	s_cmp_eq_u32 s64, 60
	s_cselect_b32 s39, s7, s35
	s_cselect_b32 s38, s8, s34
	s_cselect_b32 s37, s23, s63
	s_cselect_b32 s36, s25, s31
	ds_read_b128 v[184:187], v219 offset:1024
	ds_read_b128 v[188:191], v219 offset:2048
	ds_read_b128 v[192:195], v219 offset:3072
	ds_read_b128 v[196:199], v219 offset:4096
	ds_read_b128 v[200:203], v219 offset:5120
	ds_read_b128 v[204:207], v219 offset:6144
	ds_read_b128 v[208:211], v219 offset:7168
	s_barrier
	s_setprio 1
	s_waitcnt lgkmcnt(0)
	v_mfma_f32_16x16x32_bf16 v[126:129], v[130:133], v[180:183], v[126:129]
	v_mfma_f32_16x16x32_bf16 v[94:97], v[138:141], v[180:183], v[94:97]
	v_mfma_f32_16x16x32_bf16 v[122:125], v[130:133], v[188:191], v[122:125]
	v_mfma_f32_16x16x32_bf16 v[90:93], v[138:141], v[188:191], v[90:93]
	v_mfma_f32_16x16x32_bf16 v[118:121], v[130:133], v[196:199], v[118:121]
	v_mfma_f32_16x16x32_bf16 v[86:89], v[138:141], v[196:199], v[86:89]
	v_mfma_f32_16x16x32_bf16 v[114:117], v[130:133], v[204:207], v[114:117]
	v_mfma_f32_16x16x32_bf16 v[82:85], v[138:141], v[204:207], v[82:85]
	v_mfma_f32_16x16x32_bf16 v[126:129], v[134:137], v[184:187], v[126:129]
	v_mfma_f32_16x16x32_bf16 v[94:97], v[142:145], v[184:187], v[94:97]
	v_mfma_f32_16x16x32_bf16 v[122:125], v[134:137], v[192:195], v[122:125]
	v_mfma_f32_16x16x32_bf16 v[90:93], v[142:145], v[192:195], v[90:93]
	v_mfma_f32_16x16x32_bf16 v[118:121], v[134:137], v[200:203], v[118:121]
	v_mfma_f32_16x16x32_bf16 v[86:89], v[142:145], v[200:203], v[86:89]
	v_mfma_f32_16x16x32_bf16 v[114:117], v[134:137], v[208:211], v[114:117]
	v_mfma_f32_16x16x32_bf16 v[82:85], v[142:145], v[208:211], v[82:85]
	s_setprio 0
	s_setprio 1
	v_mfma_f32_16x16x32_bf16 v[62:65], v[146:149], v[180:183], v[62:65]
	v_mfma_f32_16x16x32_bf16 v[30:33], v[154:157], v[180:183], v[30:33]
	v_mfma_f32_16x16x32_bf16 v[58:61], v[146:149], v[188:191], v[58:61]
	v_mfma_f32_16x16x32_bf16 v[26:29], v[154:157], v[188:191], v[26:29]
	v_mfma_f32_16x16x32_bf16 v[54:57], v[146:149], v[196:199], v[54:57]
	v_mfma_f32_16x16x32_bf16 v[22:25], v[154:157], v[196:199], v[22:25]
	v_mfma_f32_16x16x32_bf16 v[50:53], v[146:149], v[204:207], v[50:53]
	v_mfma_f32_16x16x32_bf16 v[18:21], v[154:157], v[204:207], v[18:21]
	v_mfma_f32_16x16x32_bf16 v[62:65], v[150:153], v[184:187], v[62:65]
	v_mfma_f32_16x16x32_bf16 v[30:33], v[158:161], v[184:187], v[30:33]
	v_mfma_f32_16x16x32_bf16 v[58:61], v[150:153], v[192:195], v[58:61]
	v_mfma_f32_16x16x32_bf16 v[26:29], v[158:161], v[192:195], v[26:29]
	v_mfma_f32_16x16x32_bf16 v[54:57], v[150:153], v[200:203], v[54:57]
	v_mfma_f32_16x16x32_bf16 v[22:25], v[158:161], v[200:203], v[22:25]
	v_mfma_f32_16x16x32_bf16 v[50:53], v[150:153], v[208:211], v[50:53]
	v_mfma_f32_16x16x32_bf16 v[18:21], v[158:161], v[208:211], v[18:21]
	s_waitcnt vmcnt(8)
	s_barrier
	s_setprio 0
	s_add_i32 s4, s59, s21
	s_mov_b32 m0, s4
	ds_read_b128 v[180:183], v219 offset:16384
	ds_read_b128 v[184:187], v219 offset:17408
	global_load_lds_dwordx4 v164, s[36:37]
	ds_read_b128 v[188:191], v219 offset:18432
	s_add_i32 m0, s4, 0x2000
	s_add_u32 s4, s36, 0x100000
	s_addc_u32 s5, s37, 0
	s_add_i32 s65, s60, s21
	global_load_lds_dwordx4 v168, s[36:37]
	ds_read_b128 v[192:195], v219 offset:19456
	s_mov_b32 m0, s65
	s_nop 0
	global_load_lds_dwordx4 v164, s[4:5]
	ds_read_b128 v[196:199], v219 offset:20480
	s_add_i32 m0, s65, 0x2000
	s_nop 0
	global_load_lds_dwordx4 v168, s[4:5]
	ds_read_b128 v[200:203], v219 offset:21504
	s_mov_b32 m0, s40
	s_nop 0
	global_load_lds_dwordx4 v162, s[38:39]
	ds_read_b128 v[204:207], v219 offset:22528
	s_mov_b32 m0, s41
	s_nop 0
	global_load_lds_dwordx4 v166, s[38:39]
	ds_read_b128 v[208:211], v219 offset:23552
	s_barrier
	s_setprio 1
	s_waitcnt lgkmcnt(0)
	v_mfma_f32_16x16x32_bf16 v[110:113], v[130:133], v[180:183], v[110:113]
	v_mfma_f32_16x16x32_bf16 v[78:81], v[138:141], v[180:183], v[78:81]
	v_mfma_f32_16x16x32_bf16 v[106:109], v[130:133], v[188:191], v[106:109]
	v_mfma_f32_16x16x32_bf16 v[74:77], v[138:141], v[188:191], v[74:77]
	v_mfma_f32_16x16x32_bf16 v[102:105], v[130:133], v[196:199], v[102:105]
	v_mfma_f32_16x16x32_bf16 v[70:73], v[138:141], v[196:199], v[70:73]
	v_mfma_f32_16x16x32_bf16 v[98:101], v[130:133], v[204:207], v[98:101]
	v_mfma_f32_16x16x32_bf16 v[66:69], v[138:141], v[204:207], v[66:69]
	v_mfma_f32_16x16x32_bf16 v[110:113], v[134:137], v[184:187], v[110:113]
	v_mfma_f32_16x16x32_bf16 v[78:81], v[142:145], v[184:187], v[78:81]
	v_mfma_f32_16x16x32_bf16 v[106:109], v[134:137], v[192:195], v[106:109]
	v_mfma_f32_16x16x32_bf16 v[74:77], v[142:145], v[192:195], v[74:77]
	v_mfma_f32_16x16x32_bf16 v[102:105], v[134:137], v[200:203], v[102:105]
	v_mfma_f32_16x16x32_bf16 v[70:73], v[142:145], v[200:203], v[70:73]
	v_mfma_f32_16x16x32_bf16 v[98:101], v[134:137], v[208:211], v[98:101]
	v_mfma_f32_16x16x32_bf16 v[66:69], v[142:145], v[208:211], v[66:69]
	s_setprio 0
	s_setprio 1
	v_mfma_f32_16x16x32_bf16 v[46:49], v[146:149], v[180:183], v[46:49]
	v_mfma_f32_16x16x32_bf16 v[14:17], v[154:157], v[180:183], v[14:17]
	v_mfma_f32_16x16x32_bf16 v[42:45], v[146:149], v[188:191], v[42:45]
	v_mfma_f32_16x16x32_bf16 v[10:13], v[154:157], v[188:191], v[10:13]
	v_mfma_f32_16x16x32_bf16 v[38:41], v[146:149], v[196:199], v[38:41]
	v_mfma_f32_16x16x32_bf16 v[6:9], v[154:157], v[196:199], v[6:9]
	v_mfma_f32_16x16x32_bf16 v[34:37], v[146:149], v[204:207], v[34:37]
	v_mfma_f32_16x16x32_bf16 v[2:5], v[154:157], v[204:207], v[2:5]
	v_mfma_f32_16x16x32_bf16 v[46:49], v[150:153], v[184:187], v[46:49]
	v_mfma_f32_16x16x32_bf16 v[14:17], v[158:161], v[184:187], v[14:17]
	v_mfma_f32_16x16x32_bf16 v[42:45], v[150:153], v[192:195], v[42:45]
	v_mfma_f32_16x16x32_bf16 v[10:13], v[158:161], v[192:195], v[10:13]
	v_mfma_f32_16x16x32_bf16 v[38:41], v[150:153], v[200:203], v[38:41]
	v_mfma_f32_16x16x32_bf16 v[6:9], v[158:161], v[200:203], v[6:9]
	v_mfma_f32_16x16x32_bf16 v[34:37], v[150:153], v[208:211], v[34:37]
	v_mfma_f32_16x16x32_bf16 v[2:5], v[158:161], v[208:211], v[2:5]
	s_waitcnt vmcnt(8)
	s_barrier
; #define PG8_STAGE(bufoff, gbase, voff) do { _Pragma("unroll") for (int _i = 0; _i < 2; ++_i) \
;         __builtin_amdgcn_global_load_lds((const unsigned*)((const char*)(gbase) + (voff)[_i]), (LAS unsigned*)(lds + (bufoff) + ldsw + _i * 8192), 16, 0, 0); } while (0)
; #define PG8_LDA(dst, b, h) do { _Pragma("unroll") for (int m = 0; m < 4; ++m) _Pragma("unroll") for (int k = 0; k < 2; ++k) dst[m][k] = *(const LAS bf16x8*)(lds + PG8_SA(b, h) + aoff + m * 2048 + k * 1024); } while (0)
; #define PG8_LDB(dst, b, h) do { _Pragma("unroll") for (int n = 0; n < 2; ++n) _Pragma("unroll") for (int k = 0; k < 2; ++k) dst[n][k] = *(const LAS bf16x8*)(lds + PG8_SB(b, h) + boff + n * 2048 + k * 1024); } while (0)
; #define PG8_MMA(ai, bj, At, Bt) do { __builtin_amdgcn_s_setprio(1); _Pragma("unroll") for (int m = 0; m < 4; ++m) _Pragma("unroll") for (int n = 0; n < 2; ++n) _Pragma("unroll") for (int k = 0; k < 2; ++k) \
;         acc[ai][bj][m][n] = __builtin_amdgcn_mfma_f32_16x16x32_bf16(Bt[n][k], At[m][k], acc[ai][bj][m][n], 0, 0, 0); __builtin_amdgcn_s_setprio(0); } while (0)
; #define PG8_WAIT_V(n) asm volatile("s_waitcnt vmcnt(" #n ")" ::: "memory")
; #define PG8_WAIT_L(n) asm volatile("s_waitcnt lgkmcnt(" #n ")" ::: "memory")
; #define PG8_BAR __builtin_amdgcn_s_barrier()
; #define PG8_SCHED __builtin_amdgcn_sched_barrier(0)
; template <class Epi, class Sched, bool ALIGN_EPI, class Hook = NoHook>
; __device__ __forceinline__ void gemm_phase(LAS unsigned char* lds, const Gemm g, const Sched& S, const Epi& E, const Hook& H = Hook()) {
;     ...
;             PG8_LDB(B0, 1, 0); PG8_LDB(B1, 1, 1); PG8_SCHED; PG8_LDA(At, 1, 0); PG8_STAGE(PG8_SA(0, 1), a2 + hA, voffA);
;             PG8_WAIT_V(8); PG8_WAIT_L(0); PG8_BAR; PG8_MMA(0, 0, At, B0); PG8_MMA(0, 1, At, B1); PG8_BAR; PG8_SCHED;
;             PG8_LDA(At, 1, 1); PG8_STAGE(PG8_SB(1, 0), b3, voffB); PG8_STAGE(PG8_SB(1, 1), b3 + hB, voffB); PG8_STAGE(PG8_SA(1, 0), a3, voffA);
;             PG8_WAIT_V(8); PG8_WAIT_L(0); PG8_BAR; PG8_MMA(1, 0, At, B0); PG8_MMA(1, 1, At, B1); PG8_BAR; PG8_SCHED;
;         }
	s_setprio 0
	s_add_i32 s65, 0, 0x18000
	s_add_i32 s66, 0, 0x1c000
	v_add_u32_e32 v142, s65, v213
	v_add_u32_e32 v158, s66, v213
	ds_read_b128 v[130:133], v142
	ds_read_b128 v[134:137], v142 offset:1024
	s_add_u32 s4, s38, 0x8000
	s_addc_u32 s5, s39, 0
	s_mov_b32 m0, s42
	s_nop 0
	global_load_lds_dwordx4 v162, s[4:5]
	ds_read_b128 v[138:141], v142 offset:2048
	ds_read_b128 v[142:145], v142 offset:3072
	ds_read_b128 v[146:149], v158
	ds_read_b128 v[150:153], v158 offset:1024
	ds_read_b128 v[154:157], v158 offset:2048
	ds_read_b128 v[158:161], v158 offset:3072
	ds_read_b128 v[180:183], v219 offset:32768
	s_mov_b32 m0, s43
	s_nop 0
	global_load_lds_dwordx4 v166, s[4:5]
	ds_read_b128 v[184:187], v219 offset:33792
	ds_read_b128 v[188:191], v219 offset:34816
	ds_read_b128 v[192:195], v219 offset:35840
	ds_read_b128 v[196:199], v219 offset:36864
	ds_read_b128 v[200:203], v219 offset:37888
	ds_read_b128 v[204:207], v219 offset:38912
	ds_read_b128 v[208:211], v219 offset:39936
	s_barrier
	s_setprio 1
	s_waitcnt lgkmcnt(0)
	v_mfma_f32_16x16x32_bf16 v[126:129], v[130:133], v[180:183], v[126:129]
	v_mfma_f32_16x16x32_bf16 v[94:97], v[138:141], v[180:183], v[94:97]
	v_mfma_f32_16x16x32_bf16 v[122:125], v[130:133], v[188:191], v[122:125]
	v_mfma_f32_16x16x32_bf16 v[90:93], v[138:141], v[188:191], v[90:93]
	v_mfma_f32_16x16x32_bf16 v[118:121], v[130:133], v[196:199], v[118:121]
	v_mfma_f32_16x16x32_bf16 v[86:89], v[138:141], v[196:199], v[86:89]
	v_mfma_f32_16x16x32_bf16 v[114:117], v[130:133], v[204:207], v[114:117]
	v_mfma_f32_16x16x32_bf16 v[82:85], v[138:141], v[204:207], v[82:85]
	v_mfma_f32_16x16x32_bf16 v[126:129], v[134:137], v[184:187], v[126:129]
	v_mfma_f32_16x16x32_bf16 v[94:97], v[142:145], v[184:187], v[94:97]
	v_mfma_f32_16x16x32_bf16 v[122:125], v[134:137], v[192:195], v[122:125]
	v_mfma_f32_16x16x32_bf16 v[90:93], v[142:145], v[192:195], v[90:93]
	v_mfma_f32_16x16x32_bf16 v[118:121], v[134:137], v[200:203], v[118:121]
	v_mfma_f32_16x16x32_bf16 v[86:89], v[142:145], v[200:203], v[86:89]
	v_mfma_f32_16x16x32_bf16 v[114:117], v[134:137], v[208:211], v[114:117]
	v_mfma_f32_16x16x32_bf16 v[82:85], v[142:145], v[208:211], v[82:85]
	s_setprio 0
	s_setprio 1
	v_mfma_f32_16x16x32_bf16 v[62:65], v[146:149], v[180:183], v[62:65]
	v_mfma_f32_16x16x32_bf16 v[30:33], v[154:157], v[180:183], v[30:33]
	v_mfma_f32_16x16x32_bf16 v[58:61], v[146:149], v[188:191], v[58:61]
	v_mfma_f32_16x16x32_bf16 v[26:29], v[154:157], v[188:191], v[26:29]
	v_mfma_f32_16x16x32_bf16 v[54:57], v[146:149], v[196:199], v[54:57]
	v_mfma_f32_16x16x32_bf16 v[22:25], v[154:157], v[196:199], v[22:25]
	v_mfma_f32_16x16x32_bf16 v[50:53], v[146:149], v[204:207], v[50:53]
	v_mfma_f32_16x16x32_bf16 v[18:21], v[154:157], v[204:207], v[18:21]
	v_mfma_f32_16x16x32_bf16 v[62:65], v[150:153], v[184:187], v[62:65]
	v_mfma_f32_16x16x32_bf16 v[30:33], v[158:161], v[184:187], v[30:33]
	v_mfma_f32_16x16x32_bf16 v[58:61], v[150:153], v[192:195], v[58:61]
	v_mfma_f32_16x16x32_bf16 v[26:29], v[158:161], v[192:195], v[26:29]
	v_mfma_f32_16x16x32_bf16 v[54:57], v[150:153], v[200:203], v[54:57]
	v_mfma_f32_16x16x32_bf16 v[22:25], v[158:161], v[200:203], v[22:25]
	v_mfma_f32_16x16x32_bf16 v[50:53], v[150:153], v[208:211], v[50:53]
	v_mfma_f32_16x16x32_bf16 v[18:21], v[158:161], v[208:211], v[18:21]
	s_waitcnt vmcnt(8)
	s_barrier
	s_setprio 0
	s_add_i32 s4, s65, s21
	s_add_u32 s68, s36, s14
	s_addc_u32 s69, s37, s15
	s_mov_b32 m0, s4
	ds_read_b128 v[180:183], v219 offset:49152
	ds_read_b128 v[184:187], v219 offset:50176
	global_load_lds_dwordx4 v164, s[68:69]
	ds_read_b128 v[188:191], v219 offset:51200
	s_add_i32 m0, s4, 0x2000
	s_add_u32 s4, s36, 0x100080
	s_addc_u32 s5, s37, 0
	s_add_i32 s36, s66, s21
	global_load_lds_dwordx4 v168, s[68:69]
	ds_read_b128 v[192:195], v219 offset:52224
	s_mov_b32 m0, s36
	s_nop 0
	global_load_lds_dwordx4 v164, s[4:5]
	ds_read_b128 v[196:199], v219 offset:53248
	s_add_i32 m0, s36, 0x2000
	s_nop 0
	global_load_lds_dwordx4 v168, s[4:5]
	ds_read_b128 v[200:203], v219 offset:54272
	s_add_u32 s70, s38, s14
	s_addc_u32 s71, s39, s15
	s_mov_b32 m0, s51
	s_nop 0
	global_load_lds_dwordx4 v162, s[70:71]
	ds_read_b128 v[204:207], v219 offset:55296
	s_mov_b32 m0, s52
	s_nop 0
	global_load_lds_dwordx4 v166, s[70:71]
	s_add_i32 s64, s64, 2
	s_add_u32 s31, s31, 0x100
	s_addc_u32 s63, s63, 0
	s_cmp_gt_u32 s64, 61
	s_mov_b64 s[4:5], s[34:35]
	ds_read_b128 v[208:211], v219 offset:56320
	s_barrier
	s_setprio 1
	s_waitcnt lgkmcnt(0)
	v_mfma_f32_16x16x32_bf16 v[110:113], v[130:133], v[180:183], v[110:113]
	v_mfma_f32_16x16x32_bf16 v[78:81], v[138:141], v[180:183], v[78:81]
	v_mfma_f32_16x16x32_bf16 v[106:109], v[130:133], v[188:191], v[106:109]
	v_mfma_f32_16x16x32_bf16 v[74:77], v[138:141], v[188:191], v[74:77]
	v_mfma_f32_16x16x32_bf16 v[102:105], v[130:133], v[196:199], v[102:105]
	v_mfma_f32_16x16x32_bf16 v[70:73], v[138:141], v[196:199], v[70:73]
	v_mfma_f32_16x16x32_bf16 v[98:101], v[130:133], v[204:207], v[98:101]
	v_mfma_f32_16x16x32_bf16 v[66:69], v[138:141], v[204:207], v[66:69]
	v_mfma_f32_16x16x32_bf16 v[110:113], v[134:137], v[184:187], v[110:113]
	v_mfma_f32_16x16x32_bf16 v[78:81], v[142:145], v[184:187], v[78:81]
	v_mfma_f32_16x16x32_bf16 v[106:109], v[134:137], v[192:195], v[106:109]
	v_mfma_f32_16x16x32_bf16 v[74:77], v[142:145], v[192:195], v[74:77]
	v_mfma_f32_16x16x32_bf16 v[102:105], v[134:137], v[200:203], v[102:105]
	v_mfma_f32_16x16x32_bf16 v[70:73], v[142:145], v[200:203], v[70:73]
	v_mfma_f32_16x16x32_bf16 v[98:101], v[134:137], v[208:211], v[98:101]
	v_mfma_f32_16x16x32_bf16 v[66:69], v[142:145], v[208:211], v[66:69]
	s_setprio 0
	s_setprio 1
	v_mfma_f32_16x16x32_bf16 v[46:49], v[146:149], v[180:183], v[46:49]
	v_mfma_f32_16x16x32_bf16 v[14:17], v[154:157], v[180:183], v[14:17]
	v_mfma_f32_16x16x32_bf16 v[42:45], v[146:149], v[188:191], v[42:45]
	v_mfma_f32_16x16x32_bf16 v[10:13], v[154:157], v[188:191], v[10:13]
	v_mfma_f32_16x16x32_bf16 v[38:41], v[146:149], v[196:199], v[38:41]
	v_mfma_f32_16x16x32_bf16 v[6:9], v[154:157], v[196:199], v[6:9]
	v_mfma_f32_16x16x32_bf16 v[34:37], v[146:149], v[204:207], v[34:37]
	v_mfma_f32_16x16x32_bf16 v[2:5], v[154:157], v[204:207], v[2:5]
	v_mfma_f32_16x16x32_bf16 v[46:49], v[150:153], v[184:187], v[46:49]
	v_mfma_f32_16x16x32_bf16 v[14:17], v[158:161], v[184:187], v[14:17]
	v_mfma_f32_16x16x32_bf16 v[42:45], v[150:153], v[192:195], v[42:45]
	v_mfma_f32_16x16x32_bf16 v[10:13], v[158:161], v[192:195], v[10:13]
	v_mfma_f32_16x16x32_bf16 v[38:41], v[150:153], v[200:203], v[38:41]
	v_mfma_f32_16x16x32_bf16 v[6:9], v[158:161], v[200:203], v[6:9]
	v_mfma_f32_16x16x32_bf16 v[34:37], v[150:153], v[208:211], v[34:37]
	v_mfma_f32_16x16x32_bf16 v[2:5], v[158:161], v[208:211], v[2:5]
	s_waitcnt vmcnt(8)
	s_barrier
	s_setprio 0
	s_cbranch_scc0 .LBB0_199
	s_branch .Lmy_d199X
; #define PG8_STAGE(bufoff, gbase, voff) do { _Pragma("unroll") for (int _i = 0; _i < 2; ++_i) \
;         __builtin_amdgcn_global_load_lds((const unsigned*)((const char*)(gbase) + (voff)[_i]), (LAS unsigned*)(lds + (bufoff) + ldsw + _i * 8192), 16, 0, 0); } while (0)
; #define PG8_LDA(dst, b, h) do { _Pragma("unroll") for (int m = 0; m < 4; ++m) _Pragma("unroll") for (int k = 0; k < 2; ++k) dst[m][k] = *(const LAS bf16x8*)(lds + PG8_SA(b, h) + aoff + m * 2048 + k * 1024); } while (0)
; #define PG8_LDB(dst, b, h) do { _Pragma("unroll") for (int n = 0; n < 2; ++n) _Pragma("unroll") for (int k = 0; k < 2; ++k) dst[n][k] = *(const LAS bf16x8*)(lds + PG8_SB(b, h) + boff + n * 2048 + k * 1024); } while (0)
; #define PG8_MMA(ai, bj, At, Bt) do { __builtin_amdgcn_s_setprio(1); _Pragma("unroll") for (int m = 0; m < 4; ++m) _Pragma("unroll") for (int n = 0; n < 2; ++n) _Pragma("unroll") for (int k = 0; k < 2; ++k) \
;         acc[ai][bj][m][n] = __builtin_amdgcn_mfma_f32_16x16x32_bf16(Bt[n][k], At[m][k], acc[ai][bj][m][n], 0, 0, 0); __builtin_amdgcn_s_setprio(0); } while (0)
; #define PG8_WAIT_V(n) asm volatile("s_waitcnt vmcnt(" #n ")" ::: "memory")
; #define PG8_WAIT_L(n) asm volatile("s_waitcnt lgkmcnt(" #n ")" ::: "memory")
; #define PG8_BAR __builtin_amdgcn_s_barrier()
; #define PG8_SCHED __builtin_amdgcn_sched_barrier(0)
; template <class Epi, class Sched, bool ALIGN_EPI, class Hook = NoHook>
; __device__ __forceinline__ void gemm_phase(LAS unsigned char* lds, const Gemm g, const Sched& S, const Epi& E, const Hook& H = Hook()) {
;     ...
;             const char* a1 = cA + (size_t)(t + 1) * kstep;
;             const char* a2 = last ? nA : cA + (size_t)(t + 2) * kstep; const char* b2 = last ? nB : cB + (size_t)(t + 2) * kstep;
;             const char* a3 = a2 + kstep; const char* b3 = b2 + kstep;
;             if (last && has_next) S.a_ready(nxt);
;             PG8_LDB(B0, 0, 0); PG8_LDB(B1, 0, 1); PG8_SCHED; PG8_LDA(At, 0, 0); PG8_STAGE(PG8_SA(1, 1), a1 + hA, voffA);
;             PG8_WAIT_V(8); PG8_WAIT_L(0); PG8_BAR; PG8_MMA(0, 0, At, B0); PG8_MMA(0, 1, At, B1); PG8_BAR; PG8_SCHED;
;             PG8_LDA(At, 0, 1); PG8_STAGE(PG8_SB(0, 0), b2, voffB); PG8_STAGE(PG8_SB(0, 1), b2 + hB, voffB); PG8_STAGE(PG8_SA(0, 0), a2, voffA);
;             PG8_WAIT_V(8); PG8_WAIT_L(0); PG8_BAR; PG8_MMA(1, 0, At, B0); PG8_MMA(1, 1, At, B1); PG8_BAR; PG8_SCHED;
.Lmy_d199B:
	ds_read_b128 v[130:133], v217
	ds_read_b128 v[134:137], v217 offset:1024
	s_add_i32 m0, s40, 0xc000
	s_nop 0
	global_load_lds_dwordx4 v172, s[4:5]
	ds_read_b128 v[138:141], v217 offset:2048
	ds_read_b128 v[142:145], v217 offset:3072
	ds_read_b128 v[146:149], v218
	ds_read_b128 v[150:153], v218 offset:1024
	ds_read_b128 v[154:157], v218 offset:2048
	ds_read_b128 v[158:161], v218 offset:3072
	ds_read_b128 v[180:183], v219
	s_add_i32 m0, s40, 0xe000
	s_nop 0
	global_load_lds_dwordx4 v174, s[4:5]
	s_add_u32 s34, s4, 0x100
	s_addc_u32 s35, s5, 0
	s_cmp_eq_u32 s64, 60
	s_cselect_b32 s39, s7, s35
	s_cselect_b32 s38, s8, s34
	s_cselect_b32 s37, s23, s63
	s_cselect_b32 s36, s25, s31
	ds_read_b128 v[184:187], v219 offset:1024
	ds_read_b128 v[188:191], v219 offset:2048
	ds_read_b128 v[192:195], v219 offset:3072
	ds_read_b128 v[196:199], v219 offset:4096
	ds_read_b128 v[200:203], v219 offset:5120
	ds_read_b128 v[204:207], v219 offset:6144
	ds_read_b128 v[208:211], v219 offset:7168
	s_waitcnt vmcnt(8) lgkmcnt(0)
	s_barrier
	s_setprio 1
	v_mfma_f32_16x16x32_bf16 v[126:129], v[130:133], v[180:183], v[126:129]
	v_mfma_f32_16x16x32_bf16 v[94:97], v[138:141], v[180:183], v[94:97]
	v_mfma_f32_16x16x32_bf16 v[122:125], v[130:133], v[188:191], v[122:125]
	v_mfma_f32_16x16x32_bf16 v[90:93], v[138:141], v[188:191], v[90:93]
	v_mfma_f32_16x16x32_bf16 v[118:121], v[130:133], v[196:199], v[118:121]
	v_mfma_f32_16x16x32_bf16 v[86:89], v[138:141], v[196:199], v[86:89]
	v_mfma_f32_16x16x32_bf16 v[114:117], v[130:133], v[204:207], v[114:117]
	v_mfma_f32_16x16x32_bf16 v[82:85], v[138:141], v[204:207], v[82:85]
	v_mfma_f32_16x16x32_bf16 v[126:129], v[134:137], v[184:187], v[126:129]
	v_mfma_f32_16x16x32_bf16 v[94:97], v[142:145], v[184:187], v[94:97]
	v_mfma_f32_16x16x32_bf16 v[122:125], v[134:137], v[192:195], v[122:125]
	v_mfma_f32_16x16x32_bf16 v[90:93], v[142:145], v[192:195], v[90:93]
	v_mfma_f32_16x16x32_bf16 v[118:121], v[134:137], v[200:203], v[118:121]
	v_mfma_f32_16x16x32_bf16 v[86:89], v[142:145], v[200:203], v[86:89]
	v_mfma_f32_16x16x32_bf16 v[114:117], v[134:137], v[208:211], v[114:117]
	v_mfma_f32_16x16x32_bf16 v[82:85], v[142:145], v[208:211], v[82:85]
	s_setprio 0
	s_setprio 1
	v_mfma_f32_16x16x32_bf16 v[62:65], v[146:149], v[180:183], v[62:65]
	v_mfma_f32_16x16x32_bf16 v[30:33], v[154:157], v[180:183], v[30:33]
	v_mfma_f32_16x16x32_bf16 v[58:61], v[146:149], v[188:191], v[58:61]
	v_mfma_f32_16x16x32_bf16 v[26:29], v[154:157], v[188:191], v[26:29]
	v_mfma_f32_16x16x32_bf16 v[54:57], v[146:149], v[196:199], v[54:57]
	v_mfma_f32_16x16x32_bf16 v[22:25], v[154:157], v[196:199], v[22:25]
	v_mfma_f32_16x16x32_bf16 v[50:53], v[146:149], v[204:207], v[50:53]
	v_mfma_f32_16x16x32_bf16 v[18:21], v[154:157], v[204:207], v[18:21]
	v_mfma_f32_16x16x32_bf16 v[62:65], v[150:153], v[184:187], v[62:65]
	v_mfma_f32_16x16x32_bf16 v[30:33], v[158:161], v[184:187], v[30:33]
	v_mfma_f32_16x16x32_bf16 v[58:61], v[150:153], v[192:195], v[58:61]
	v_mfma_f32_16x16x32_bf16 v[26:29], v[158:161], v[192:195], v[26:29]
	v_mfma_f32_16x16x32_bf16 v[54:57], v[150:153], v[200:203], v[54:57]
	v_mfma_f32_16x16x32_bf16 v[22:25], v[158:161], v[200:203], v[22:25]
	v_mfma_f32_16x16x32_bf16 v[50:53], v[150:153], v[208:211], v[50:53]
	v_mfma_f32_16x16x32_bf16 v[18:21], v[158:161], v[208:211], v[18:21]
	s_barrier
	s_setprio 0
	s_add_i32 s4, s59, s21
	s_mov_b32 m0, s4
	ds_read_b128 v[180:183], v219 offset:16384
	ds_read_b128 v[184:187], v219 offset:17408
	global_load_lds_dwordx4 v164, s[36:37]
	ds_read_b128 v[188:191], v219 offset:18432
	s_add_i32 m0, s4, 0x2000
	s_add_u32 s4, s36, 0x100000
	s_addc_u32 s5, s37, 0
	s_add_i32 s65, s60, s21
	global_load_lds_dwordx4 v168, s[36:37]
	ds_read_b128 v[192:195], v219 offset:19456
	s_mov_b32 m0, s65
	s_nop 0
	global_load_lds_dwordx4 v164, s[4:5]
	ds_read_b128 v[196:199], v219 offset:20480
	s_add_i32 m0, s65, 0x2000
	s_nop 0
	global_load_lds_dwordx4 v168, s[4:5]
	ds_read_b128 v[200:203], v219 offset:21504
	s_mov_b32 m0, s40
	s_nop 0
	global_load_lds_dwordx4 v162, s[38:39]
	ds_read_b128 v[204:207], v219 offset:22528
	s_mov_b32 m0, s41
	s_nop 0
	global_load_lds_dwordx4 v166, s[38:39]
	ds_read_b128 v[208:211], v219 offset:23552
	s_waitcnt vmcnt(8) lgkmcnt(0)
	s_barrier
	s_setprio 1
	v_mfma_f32_16x16x32_bf16 v[110:113], v[130:133], v[180:183], v[110:113]
	v_mfma_f32_16x16x32_bf16 v[78:81], v[138:141], v[180:183], v[78:81]
	v_mfma_f32_16x16x32_bf16 v[106:109], v[130:133], v[188:191], v[106:109]
	v_mfma_f32_16x16x32_bf16 v[74:77], v[138:141], v[188:191], v[74:77]
	v_mfma_f32_16x16x32_bf16 v[102:105], v[130:133], v[196:199], v[102:105]
	v_mfma_f32_16x16x32_bf16 v[70:73], v[138:141], v[196:199], v[70:73]
	v_mfma_f32_16x16x32_bf16 v[98:101], v[130:133], v[204:207], v[98:101]
	v_mfma_f32_16x16x32_bf16 v[66:69], v[138:141], v[204:207], v[66:69]
	v_mfma_f32_16x16x32_bf16 v[110:113], v[134:137], v[184:187], v[110:113]
	v_mfma_f32_16x16x32_bf16 v[78:81], v[142:145], v[184:187], v[78:81]
	v_mfma_f32_16x16x32_bf16 v[106:109], v[134:137], v[192:195], v[106:109]
	v_mfma_f32_16x16x32_bf16 v[74:77], v[142:145], v[192:195], v[74:77]
	v_mfma_f32_16x16x32_bf16 v[102:105], v[134:137], v[200:203], v[102:105]
	v_mfma_f32_16x16x32_bf16 v[70:73], v[142:145], v[200:203], v[70:73]
	v_mfma_f32_16x16x32_bf16 v[98:101], v[134:137], v[208:211], v[98:101]
	v_mfma_f32_16x16x32_bf16 v[66:69], v[142:145], v[208:211], v[66:69]
	s_setprio 0
	s_setprio 1
	v_mfma_f32_16x16x32_bf16 v[46:49], v[146:149], v[180:183], v[46:49]
	v_mfma_f32_16x16x32_bf16 v[14:17], v[154:157], v[180:183], v[14:17]
	v_mfma_f32_16x16x32_bf16 v[42:45], v[146:149], v[188:191], v[42:45]
	v_mfma_f32_16x16x32_bf16 v[10:13], v[154:157], v[188:191], v[10:13]
	v_mfma_f32_16x16x32_bf16 v[38:41], v[146:149], v[196:199], v[38:41]
	v_mfma_f32_16x16x32_bf16 v[6:9], v[154:157], v[196:199], v[6:9]
	v_mfma_f32_16x16x32_bf16 v[34:37], v[146:149], v[204:207], v[34:37]
	v_mfma_f32_16x16x32_bf16 v[2:5], v[154:157], v[204:207], v[2:5]
	v_mfma_f32_16x16x32_bf16 v[46:49], v[150:153], v[184:187], v[46:49]
	v_mfma_f32_16x16x32_bf16 v[14:17], v[158:161], v[184:187], v[14:17]
	v_mfma_f32_16x16x32_bf16 v[42:45], v[150:153], v[192:195], v[42:45]
	v_mfma_f32_16x16x32_bf16 v[10:13], v[158:161], v[192:195], v[10:13]
	v_mfma_f32_16x16x32_bf16 v[38:41], v[150:153], v[200:203], v[38:41]
	v_mfma_f32_16x16x32_bf16 v[6:9], v[158:161], v[200:203], v[6:9]
	v_mfma_f32_16x16x32_bf16 v[34:37], v[150:153], v[208:211], v[34:37]
	v_mfma_f32_16x16x32_bf16 v[2:5], v[158:161], v[208:211], v[2:5]
	s_barrier
; #define PG8_STAGE(bufoff, gbase, voff) do { _Pragma("unroll") for (int _i = 0; _i < 2; ++_i) \
;         __builtin_amdgcn_global_load_lds((const unsigned*)((const char*)(gbase) + (voff)[_i]), (LAS unsigned*)(lds + (bufoff) + ldsw + _i * 8192), 16, 0, 0); } while (0)
; #define PG8_LDA(dst, b, h) do { _Pragma("unroll") for (int m = 0; m < 4; ++m) _Pragma("unroll") for (int k = 0; k < 2; ++k) dst[m][k] = *(const LAS bf16x8*)(lds + PG8_SA(b, h) + aoff + m * 2048 + k * 1024); } while (0)
; #define PG8_LDB(dst, b, h) do { _Pragma("unroll") for (int n = 0; n < 2; ++n) _Pragma("unroll") for (int k = 0; k < 2; ++k) dst[n][k] = *(const LAS bf16x8*)(lds + PG8_SB(b, h) + boff + n * 2048 + k * 1024); } while (0)
; #define PG8_MMA(ai, bj, At, Bt) do { __builtin_amdgcn_s_setprio(1); _Pragma("unroll") for (int m = 0; m < 4; ++m) _Pragma("unroll") for (int n = 0; n < 2; ++n) _Pragma("unroll") for (int k = 0; k < 2; ++k) \
;         acc[ai][bj][m][n] = __builtin_amdgcn_mfma_f32_16x16x32_bf16(Bt[n][k], At[m][k], acc[ai][bj][m][n], 0, 0, 0); __builtin_amdgcn_s_setprio(0); } while (0)
; #define PG8_WAIT_V(n) asm volatile("s_waitcnt vmcnt(" #n ")" ::: "memory")
; #define PG8_WAIT_L(n) asm volatile("s_waitcnt lgkmcnt(" #n ")" ::: "memory")
; #define PG8_BAR __builtin_amdgcn_s_barrier()
; #define PG8_SCHED __builtin_amdgcn_sched_barrier(0)
; template <class Epi, class Sched, bool ALIGN_EPI, class Hook = NoHook>
; __device__ __forceinline__ void gemm_phase(LAS unsigned char* lds, const Gemm g, const Sched& S, const Epi& E, const Hook& H = Hook()) {
;     ...
;             PG8_LDB(B0, 1, 0); PG8_LDB(B1, 1, 1); PG8_SCHED; PG8_LDA(At, 1, 0); PG8_STAGE(PG8_SA(0, 1), a2 + hA, voffA);
;             PG8_WAIT_V(8); PG8_WAIT_L(0); PG8_BAR; PG8_MMA(0, 0, At, B0); PG8_MMA(0, 1, At, B1); PG8_BAR; PG8_SCHED;
;             PG8_LDA(At, 1, 1); PG8_STAGE(PG8_SB(1, 0), b3, voffB); PG8_STAGE(PG8_SB(1, 1), b3 + hB, voffB); PG8_STAGE(PG8_SA(1, 0), a3, voffA);
;             PG8_WAIT_V(8); PG8_WAIT_L(0); PG8_BAR; PG8_MMA(1, 0, At, B0); PG8_MMA(1, 1, At, B1); PG8_BAR; PG8_SCHED;
;         }
	s_setprio 0
	s_add_i32 s65, 0, 0x18000
	s_add_i32 s66, 0, 0x1c000
	v_add_u32_e32 v142, s65, v213
	v_add_u32_e32 v158, s66, v213
	ds_read_b128 v[130:133], v142
	ds_read_b128 v[134:137], v142 offset:1024
	s_add_u32 s4, s38, 0x8000
	s_addc_u32 s5, s39, 0
	s_mov_b32 m0, s42
	s_nop 0
	global_load_lds_dwordx4 v162, s[4:5]
	ds_read_b128 v[138:141], v142 offset:2048
	ds_read_b128 v[142:145], v142 offset:3072
	ds_read_b128 v[146:149], v158
	ds_read_b128 v[150:153], v158 offset:1024
	ds_read_b128 v[154:157], v158 offset:2048
	ds_read_b128 v[158:161], v158 offset:3072
	ds_read_b128 v[180:183], v219 offset:32768
	s_mov_b32 m0, s43
	s_nop 0
	global_load_lds_dwordx4 v166, s[4:5]
	ds_read_b128 v[184:187], v219 offset:33792
	ds_read_b128 v[188:191], v219 offset:34816
	ds_read_b128 v[192:195], v219 offset:35840
	ds_read_b128 v[196:199], v219 offset:36864
	ds_read_b128 v[200:203], v219 offset:37888
	ds_read_b128 v[204:207], v219 offset:38912
	ds_read_b128 v[208:211], v219 offset:39936
	s_waitcnt vmcnt(8) lgkmcnt(0)
	s_barrier
	s_setprio 1
	v_mfma_f32_16x16x32_bf16 v[126:129], v[130:133], v[180:183], v[126:129]
	v_mfma_f32_16x16x32_bf16 v[94:97], v[138:141], v[180:183], v[94:97]
	v_mfma_f32_16x16x32_bf16 v[122:125], v[130:133], v[188:191], v[122:125]
	v_mfma_f32_16x16x32_bf16 v[90:93], v[138:141], v[188:191], v[90:93]
	v_mfma_f32_16x16x32_bf16 v[118:121], v[130:133], v[196:199], v[118:121]
	v_mfma_f32_16x16x32_bf16 v[86:89], v[138:141], v[196:199], v[86:89]
	v_mfma_f32_16x16x32_bf16 v[114:117], v[130:133], v[204:207], v[114:117]
	v_mfma_f32_16x16x32_bf16 v[82:85], v[138:141], v[204:207], v[82:85]
	v_mfma_f32_16x16x32_bf16 v[126:129], v[134:137], v[184:187], v[126:129]
	v_mfma_f32_16x16x32_bf16 v[94:97], v[142:145], v[184:187], v[94:97]
	v_mfma_f32_16x16x32_bf16 v[122:125], v[134:137], v[192:195], v[122:125]
	v_mfma_f32_16x16x32_bf16 v[90:93], v[142:145], v[192:195], v[90:93]
	v_mfma_f32_16x16x32_bf16 v[118:121], v[134:137], v[200:203], v[118:121]
	v_mfma_f32_16x16x32_bf16 v[86:89], v[142:145], v[200:203], v[86:89]
	v_mfma_f32_16x16x32_bf16 v[114:117], v[134:137], v[208:211], v[114:117]
	v_mfma_f32_16x16x32_bf16 v[82:85], v[142:145], v[208:211], v[82:85]
	s_setprio 0
	s_setprio 1
	v_mfma_f32_16x16x32_bf16 v[62:65], v[146:149], v[180:183], v[62:65]
	v_mfma_f32_16x16x32_bf16 v[30:33], v[154:157], v[180:183], v[30:33]
	v_mfma_f32_16x16x32_bf16 v[58:61], v[146:149], v[188:191], v[58:61]
	v_mfma_f32_16x16x32_bf16 v[26:29], v[154:157], v[188:191], v[26:29]
	v_mfma_f32_16x16x32_bf16 v[54:57], v[146:149], v[196:199], v[54:57]
	v_mfma_f32_16x16x32_bf16 v[22:25], v[154:157], v[196:199], v[22:25]
	v_mfma_f32_16x16x32_bf16 v[50:53], v[146:149], v[204:207], v[50:53]
	v_mfma_f32_16x16x32_bf16 v[18:21], v[154:157], v[204:207], v[18:21]
	v_mfma_f32_16x16x32_bf16 v[62:65], v[150:153], v[184:187], v[62:65]
	v_mfma_f32_16x16x32_bf16 v[30:33], v[158:161], v[184:187], v[30:33]
	v_mfma_f32_16x16x32_bf16 v[58:61], v[150:153], v[192:195], v[58:61]
	v_mfma_f32_16x16x32_bf16 v[26:29], v[158:161], v[192:195], v[26:29]
	v_mfma_f32_16x16x32_bf16 v[54:57], v[150:153], v[200:203], v[54:57]
	v_mfma_f32_16x16x32_bf16 v[22:25], v[158:161], v[200:203], v[22:25]
	v_mfma_f32_16x16x32_bf16 v[50:53], v[150:153], v[208:211], v[50:53]
	v_mfma_f32_16x16x32_bf16 v[18:21], v[158:161], v[208:211], v[18:21]
	s_barrier
	s_setprio 0
	s_add_i32 s4, s65, s21
	s_add_u32 s68, s36, s14
	s_addc_u32 s69, s37, s15
	s_mov_b32 m0, s4
	ds_read_b128 v[180:183], v219 offset:49152
	ds_read_b128 v[184:187], v219 offset:50176
	global_load_lds_dwordx4 v164, s[68:69]
	ds_read_b128 v[188:191], v219 offset:51200
	s_add_i32 m0, s4, 0x2000
	s_add_u32 s4, s36, 0x100080
	s_addc_u32 s5, s37, 0
	s_add_i32 s36, s66, s21
	global_load_lds_dwordx4 v168, s[68:69]
	ds_read_b128 v[192:195], v219 offset:52224
	s_mov_b32 m0, s36
	s_nop 0
	global_load_lds_dwordx4 v164, s[4:5]
	ds_read_b128 v[196:199], v219 offset:53248
	s_add_i32 m0, s36, 0x2000
	s_nop 0
	global_load_lds_dwordx4 v168, s[4:5]
	ds_read_b128 v[200:203], v219 offset:54272
	s_add_u32 s70, s38, s14
	s_addc_u32 s71, s39, s15
	s_mov_b32 m0, s51
	s_nop 0
	global_load_lds_dwordx4 v162, s[70:71]
	ds_read_b128 v[204:207], v219 offset:55296
	s_mov_b32 m0, s52
	s_nop 0
	global_load_lds_dwordx4 v166, s[70:71]
	s_add_i32 s64, s64, 2
	s_add_u32 s31, s31, 0x100
	s_addc_u32 s63, s63, 0
	s_cmp_gt_u32 s64, 61
	s_mov_b64 s[4:5], s[34:35]
	ds_read_b128 v[208:211], v219 offset:56320
	s_waitcnt vmcnt(8) lgkmcnt(0)
	s_barrier
	s_setprio 1
	v_mfma_f32_16x16x32_bf16 v[110:113], v[130:133], v[180:183], v[110:113]
	v_mfma_f32_16x16x32_bf16 v[78:81], v[138:141], v[180:183], v[78:81]
	v_mfma_f32_16x16x32_bf16 v[106:109], v[130:133], v[188:191], v[106:109]
	v_mfma_f32_16x16x32_bf16 v[74:77], v[138:141], v[188:191], v[74:77]
	v_mfma_f32_16x16x32_bf16 v[102:105], v[130:133], v[196:199], v[102:105]
	v_mfma_f32_16x16x32_bf16 v[70:73], v[138:141], v[196:199], v[70:73]
	v_mfma_f32_16x16x32_bf16 v[98:101], v[130:133], v[204:207], v[98:101]
	v_mfma_f32_16x16x32_bf16 v[66:69], v[138:141], v[204:207], v[66:69]
	v_mfma_f32_16x16x32_bf16 v[110:113], v[134:137], v[184:187], v[110:113]
	v_mfma_f32_16x16x32_bf16 v[78:81], v[142:145], v[184:187], v[78:81]
	v_mfma_f32_16x16x32_bf16 v[106:109], v[134:137], v[192:195], v[106:109]
	v_mfma_f32_16x16x32_bf16 v[74:77], v[142:145], v[192:195], v[74:77]
	v_mfma_f32_16x16x32_bf16 v[102:105], v[134:137], v[200:203], v[102:105]
	v_mfma_f32_16x16x32_bf16 v[70:73], v[142:145], v[200:203], v[70:73]
	v_mfma_f32_16x16x32_bf16 v[98:101], v[134:137], v[208:211], v[98:101]
	v_mfma_f32_16x16x32_bf16 v[66:69], v[142:145], v[208:211], v[66:69]
	s_setprio 0
	s_setprio 1
	v_mfma_f32_16x16x32_bf16 v[46:49], v[146:149], v[180:183], v[46:49]
	v_mfma_f32_16x16x32_bf16 v[14:17], v[154:157], v[180:183], v[14:17]
	v_mfma_f32_16x16x32_bf16 v[42:45], v[146:149], v[188:191], v[42:45]
	v_mfma_f32_16x16x32_bf16 v[10:13], v[154:157], v[188:191], v[10:13]
	v_mfma_f32_16x16x32_bf16 v[38:41], v[146:149], v[196:199], v[38:41]
	v_mfma_f32_16x16x32_bf16 v[6:9], v[154:157], v[196:199], v[6:9]
	v_mfma_f32_16x16x32_bf16 v[34:37], v[146:149], v[204:207], v[34:37]
	v_mfma_f32_16x16x32_bf16 v[2:5], v[154:157], v[204:207], v[2:5]
	v_mfma_f32_16x16x32_bf16 v[46:49], v[150:153], v[184:187], v[46:49]
	v_mfma_f32_16x16x32_bf16 v[14:17], v[158:161], v[184:187], v[14:17]
	v_mfma_f32_16x16x32_bf16 v[42:45], v[150:153], v[192:195], v[42:45]
	v_mfma_f32_16x16x32_bf16 v[10:13], v[158:161], v[192:195], v[10:13]
	v_mfma_f32_16x16x32_bf16 v[38:41], v[150:153], v[200:203], v[38:41]
	v_mfma_f32_16x16x32_bf16 v[6:9], v[158:161], v[200:203], v[6:9]
	v_mfma_f32_16x16x32_bf16 v[34:37], v[150:153], v[208:211], v[34:37]
	v_mfma_f32_16x16x32_bf16 v[2:5], v[158:161], v[208:211], v[2:5]
	s_barrier
	s_setprio 0
	s_cbranch_scc0 .Lmy_d199B

; #define PG8_STAGE(bufoff, gbase, voff) do { _Pragma("unroll") for (int _i = 0; _i < 2; ++_i) \
;         __builtin_amdgcn_global_load_lds((const unsigned*)((const char*)(gbase) + (voff)[_i]), (LAS unsigned*)(lds + (bufoff) + ldsw + _i * 8192), 16, 0, 0); } while (0)
; #define PG8_LDA(dst, b, h) do { _Pragma("unroll") for (int m = 0; m < 4; ++m) _Pragma("unroll") for (int k = 0; k < 2; ++k) dst[m][k] = *(const LAS bf16x8*)(lds + PG8_SA(b, h) + aoff + m * 2048 + k * 1024); } while (0)
; #define PG8_LDB(dst, b, h) do { _Pragma("unroll") for (int n = 0; n < 2; ++n) _Pragma("unroll") for (int k = 0; k < 2; ++k) dst[n][k] = *(const LAS bf16x8*)(lds + PG8_SB(b, h) + boff + n * 2048 + k * 1024); } while (0)
; #define PG8_MMA(ai, bj, At, Bt) do { __builtin_amdgcn_s_setprio(1); _Pragma("unroll") for (int m = 0; m < 4; ++m) _Pragma("unroll") for (int n = 0; n < 2; ++n) _Pragma("unroll") for (int k = 0; k < 2; ++k) \
;         acc[ai][bj][m][n] = __builtin_amdgcn_mfma_f32_16x16x32_bf16(Bt[n][k], At[m][k], acc[ai][bj][m][n], 0, 0, 0); __builtin_amdgcn_s_setprio(0); } while (0)
; #define PG8_WAIT_V(n) asm volatile("s_waitcnt vmcnt(" #n ")" ::: "memory")
; #define PG8_WAIT_L(n) asm volatile("s_waitcnt lgkmcnt(" #n ")" ::: "memory")
; #define PG8_BAR __builtin_amdgcn_s_barrier()
; #define PG8_SCHED __builtin_amdgcn_sched_barrier(0)
; template <class Epi, class Sched, bool ALIGN_EPI, class Hook = NoHook>
; __device__ __forceinline__ void gemm_phase(LAS unsigned char* lds, const Gemm g, const Sched& S, const Epi& E, const Hook& H = Hook()) {
;     ...
;             const char* a1 = cA + (size_t)(t + 1) * kstep;
;             const char* a2 = last ? nA : cA + (size_t)(t + 2) * kstep; const char* b2 = last ? nB : cB + (size_t)(t + 2) * kstep;
;             const char* a3 = a2 + kstep; const char* b3 = b2 + kstep;
;             if (last && has_next) S.a_ready(nxt);
;             PG8_LDB(B0, 0, 0); PG8_LDB(B1, 0, 1); PG8_SCHED; PG8_LDA(At, 0, 0); PG8_STAGE(PG8_SA(1, 1), a1 + hA, voffA);
;             PG8_WAIT_V(8); PG8_WAIT_L(0); PG8_BAR; PG8_MMA(0, 0, At, B0); PG8_MMA(0, 1, At, B1); PG8_BAR; PG8_SCHED;
;             PG8_LDA(At, 0, 1); PG8_STAGE(PG8_SB(0, 0), b2, voffB); PG8_STAGE(PG8_SB(0, 1), b2 + hB, voffB); PG8_STAGE(PG8_SA(0, 0), a2, voffA);
;             PG8_WAIT_V(8); PG8_WAIT_L(0); PG8_BAR; PG8_MMA(1, 0, At, B0); PG8_MMA(1, 1, At, B1); PG8_BAR; PG8_SCHED;
.LBB0_262:
	ds_read_b128 v[148:151], v145
	ds_read_b128 v[152:155], v145 offset:1024
	s_add_u32 s22, s20, 0xfff00080
	s_addc_u32 s23, s21, -1
	s_cmp_eq_u32 s50, 4
	s_cselect_b32 s25, s11, s23
	s_cselect_b32 s24, s13, s22
	s_cselect_b32 s23, s40, s43
	s_cselect_b32 s22, s41, s42
	s_add_i32 m0, s5, 0xc000
	s_nop 0
	global_load_lds_dwordx4 v136, s[20:21]
	ds_read_b128 v[156:159], v145 offset:2048
	ds_read_b128 v[160:163], v145 offset:3072
	ds_read_b128 v[164:167], v146
	ds_read_b128 v[168:171], v146 offset:1024
	ds_read_b128 v[172:175], v146 offset:2048
	ds_read_b128 v[176:179], v146 offset:3072
	ds_read_b128 v[180:183], v147
	s_add_i32 m0, s5, 0xe000
	s_nop 0
	global_load_lds_dwordx4 v138, s[20:21]
	ds_read_b128 v[184:187], v147 offset:1024
	ds_read_b128 v[188:191], v147 offset:2048
	ds_read_b128 v[192:195], v147 offset:3072
	ds_read_b128 v[196:199], v147 offset:4096
	ds_read_b128 v[200:203], v147 offset:5120
	ds_read_b128 v[204:207], v147 offset:6144
	ds_read_b128 v[208:211], v147 offset:7168
	s_waitcnt vmcnt(8) lgkmcnt(0)
	s_barrier
	s_setprio 1
	v_mfma_f32_16x16x32_bf16 v[126:129], v[148:151], v[180:183], v[126:129]
	v_mfma_f32_16x16x32_bf16 v[122:125], v[156:159], v[180:183], v[122:125]
	v_mfma_f32_16x16x32_bf16 v[118:121], v[148:151], v[188:191], v[118:121]
	v_mfma_f32_16x16x32_bf16 v[114:117], v[156:159], v[188:191], v[114:117]
	v_mfma_f32_16x16x32_bf16 v[106:109], v[148:151], v[196:199], v[106:109]
	v_mfma_f32_16x16x32_bf16 v[98:101], v[156:159], v[196:199], v[98:101]
	v_mfma_f32_16x16x32_bf16 v[90:93], v[148:151], v[204:207], v[90:93]
	v_mfma_f32_16x16x32_bf16 v[82:85], v[156:159], v[204:207], v[82:85]
	v_mfma_f32_16x16x32_bf16 v[126:129], v[152:155], v[184:187], v[126:129]
	v_mfma_f32_16x16x32_bf16 v[122:125], v[160:163], v[184:187], v[122:125]
	v_mfma_f32_16x16x32_bf16 v[118:121], v[152:155], v[192:195], v[118:121]
	v_mfma_f32_16x16x32_bf16 v[114:117], v[160:163], v[192:195], v[114:117]
	v_mfma_f32_16x16x32_bf16 v[106:109], v[152:155], v[200:203], v[106:109]
	v_mfma_f32_16x16x32_bf16 v[98:101], v[160:163], v[200:203], v[98:101]
	v_mfma_f32_16x16x32_bf16 v[90:93], v[152:155], v[208:211], v[90:93]
	v_mfma_f32_16x16x32_bf16 v[82:85], v[160:163], v[208:211], v[82:85]
	s_setprio 0
	s_setprio 1
	v_mfma_f32_16x16x32_bf16 v[110:113], v[164:167], v[180:183], v[110:113]
	v_mfma_f32_16x16x32_bf16 v[102:105], v[172:175], v[180:183], v[102:105]
	v_mfma_f32_16x16x32_bf16 v[94:97], v[164:167], v[188:191], v[94:97]
	v_mfma_f32_16x16x32_bf16 v[86:89], v[172:175], v[188:191], v[86:89]
	v_mfma_f32_16x16x32_bf16 v[78:81], v[164:167], v[196:199], v[78:81]
	v_mfma_f32_16x16x32_bf16 v[74:77], v[172:175], v[196:199], v[74:77]
	v_mfma_f32_16x16x32_bf16 v[70:73], v[164:167], v[204:207], v[70:73]
	v_mfma_f32_16x16x32_bf16 v[66:69], v[172:175], v[204:207], v[66:69]
	v_mfma_f32_16x16x32_bf16 v[110:113], v[168:171], v[184:187], v[110:113]
	v_mfma_f32_16x16x32_bf16 v[102:105], v[176:179], v[184:187], v[102:105]
	v_mfma_f32_16x16x32_bf16 v[94:97], v[168:171], v[192:195], v[94:97]
	v_mfma_f32_16x16x32_bf16 v[86:89], v[176:179], v[192:195], v[86:89]
	v_mfma_f32_16x16x32_bf16 v[78:81], v[168:171], v[200:203], v[78:81]
	v_mfma_f32_16x16x32_bf16 v[74:77], v[176:179], v[200:203], v[74:77]
	v_mfma_f32_16x16x32_bf16 v[70:73], v[168:171], v[208:211], v[70:73]
	v_mfma_f32_16x16x32_bf16 v[66:69], v[176:179], v[208:211], v[66:69]
	s_barrier
	s_setprio 0
	s_add_i32 s51, s38, s29
	s_mov_b32 m0, s51
	ds_read_b128 v[180:183], v147 offset:16384
	ds_read_b128 v[184:187], v147 offset:17408
	global_load_lds_dwordx4 v132, s[22:23]
	ds_read_b128 v[188:191], v147 offset:18432
	s_add_i32 m0, s51, 0x2000
	s_add_u32 s52, s22, 0x100000
	s_addc_u32 s53, s23, 0
	s_add_i32 s51, s39, s29
	global_load_lds_dwordx4 v130, s[22:23]
	ds_read_b128 v[192:195], v147 offset:19456
	s_mov_b32 m0, s51
	s_nop 0
	global_load_lds_dwordx4 v132, s[52:53]
	ds_read_b128 v[196:199], v147 offset:20480
	s_add_i32 m0, s51, 0x2000
	s_nop 0
	global_load_lds_dwordx4 v130, s[52:53]
	ds_read_b128 v[200:203], v147 offset:21504
	s_add_u32 s56, s24, s8
	s_addc_u32 s57, s25, s9
	s_mov_b32 m0, s5
	s_nop 0
	global_load_lds_dwordx4 v132, s[24:25]
	ds_read_b128 v[204:207], v147 offset:22528
	s_mov_b32 m0, s7
	s_nop 0
	global_load_lds_dwordx4 v130, s[24:25]
	ds_read_b128 v[208:211], v147 offset:23552
	s_waitcnt vmcnt(8) lgkmcnt(0)
	s_barrier
	s_setprio 1
	v_mfma_f32_16x16x32_bf16 v[62:65], v[148:151], v[180:183], v[62:65]
	v_mfma_f32_16x16x32_bf16 v[58:61], v[156:159], v[180:183], v[58:61]
	v_mfma_f32_16x16x32_bf16 v[54:57], v[148:151], v[188:191], v[54:57]
	v_mfma_f32_16x16x32_bf16 v[50:53], v[156:159], v[188:191], v[50:53]
	v_mfma_f32_16x16x32_bf16 v[38:41], v[148:151], v[196:199], v[38:41]
	v_mfma_f32_16x16x32_bf16 v[34:37], v[156:159], v[196:199], v[34:37]
	v_mfma_f32_16x16x32_bf16 v[22:25], v[148:151], v[204:207], v[22:25]
	v_mfma_f32_16x16x32_bf16 v[18:21], v[156:159], v[204:207], v[18:21]
	v_mfma_f32_16x16x32_bf16 v[62:65], v[152:155], v[184:187], v[62:65]
	v_mfma_f32_16x16x32_bf16 v[58:61], v[160:163], v[184:187], v[58:61]
	v_mfma_f32_16x16x32_bf16 v[54:57], v[152:155], v[192:195], v[54:57]
	v_mfma_f32_16x16x32_bf16 v[50:53], v[160:163], v[192:195], v[50:53]
	v_mfma_f32_16x16x32_bf16 v[38:41], v[152:155], v[200:203], v[38:41]
	v_mfma_f32_16x16x32_bf16 v[34:37], v[160:163], v[200:203], v[34:37]
	v_mfma_f32_16x16x32_bf16 v[22:25], v[152:155], v[208:211], v[22:25]
	v_mfma_f32_16x16x32_bf16 v[18:21], v[160:163], v[208:211], v[18:21]
	s_setprio 0
	s_setprio 1
	v_mfma_f32_16x16x32_bf16 v[46:49], v[164:167], v[180:183], v[46:49]
	v_mfma_f32_16x16x32_bf16 v[42:45], v[172:175], v[180:183], v[42:45]
	v_mfma_f32_16x16x32_bf16 v[30:33], v[164:167], v[188:191], v[30:33]
	v_mfma_f32_16x16x32_bf16 v[26:29], v[172:175], v[188:191], v[26:29]
	v_mfma_f32_16x16x32_bf16 v[14:17], v[164:167], v[196:199], v[14:17]
	v_mfma_f32_16x16x32_bf16 v[10:13], v[172:175], v[196:199], v[10:13]
	v_mfma_f32_16x16x32_bf16 v[6:9], v[164:167], v[204:207], v[6:9]
	v_mfma_f32_16x16x32_bf16 v[2:5], v[172:175], v[204:207], v[2:5]
	v_mfma_f32_16x16x32_bf16 v[46:49], v[168:171], v[184:187], v[46:49]
	v_mfma_f32_16x16x32_bf16 v[42:45], v[176:179], v[184:187], v[42:45]
	v_mfma_f32_16x16x32_bf16 v[30:33], v[168:171], v[192:195], v[30:33]
	v_mfma_f32_16x16x32_bf16 v[26:29], v[176:179], v[192:195], v[26:29]
	v_mfma_f32_16x16x32_bf16 v[14:17], v[168:171], v[200:203], v[14:17]
	v_mfma_f32_16x16x32_bf16 v[10:13], v[176:179], v[200:203], v[10:13]
	v_mfma_f32_16x16x32_bf16 v[6:9], v[168:171], v[208:211], v[6:9]
	v_mfma_f32_16x16x32_bf16 v[2:5], v[176:179], v[208:211], v[2:5]
	s_barrier
; #define PG8_STAGE(bufoff, gbase, voff) do { _Pragma("unroll") for (int _i = 0; _i < 2; ++_i) \
;         __builtin_amdgcn_global_load_lds((const unsigned*)((const char*)(gbase) + (voff)[_i]), (LAS unsigned*)(lds + (bufoff) + ldsw + _i * 8192), 16, 0, 0); } while (0)
; #define PG8_LDA(dst, b, h) do { _Pragma("unroll") for (int m = 0; m < 4; ++m) _Pragma("unroll") for (int k = 0; k < 2; ++k) dst[m][k] = *(const LAS bf16x8*)(lds + PG8_SA(b, h) + aoff + m * 2048 + k * 1024); } while (0)
; #define PG8_LDB(dst, b, h) do { _Pragma("unroll") for (int n = 0; n < 2; ++n) _Pragma("unroll") for (int k = 0; k < 2; ++k) dst[n][k] = *(const LAS bf16x8*)(lds + PG8_SB(b, h) + boff + n * 2048 + k * 1024); } while (0)
; #define PG8_MMA(ai, bj, At, Bt) do { __builtin_amdgcn_s_setprio(1); _Pragma("unroll") for (int m = 0; m < 4; ++m) _Pragma("unroll") for (int n = 0; n < 2; ++n) _Pragma("unroll") for (int k = 0; k < 2; ++k) \
;         acc[ai][bj][m][n] = __builtin_amdgcn_mfma_f32_16x16x32_bf16(Bt[n][k], At[m][k], acc[ai][bj][m][n], 0, 0, 0); __builtin_amdgcn_s_setprio(0); } while (0)
; #define PG8_WAIT_V(n) asm volatile("s_waitcnt vmcnt(" #n ")" ::: "memory")
; #define PG8_WAIT_L(n) asm volatile("s_waitcnt lgkmcnt(" #n ")" ::: "memory")
; #define PG8_BAR __builtin_amdgcn_s_barrier()
; #define PG8_SCHED __builtin_amdgcn_sched_barrier(0)
; template <class Epi, class Sched, bool ALIGN_EPI, class Hook = NoHook>
; __device__ __forceinline__ void gemm_phase(LAS unsigned char* lds, const Gemm g, const Sched& S, const Epi& E, const Hook& H = Hook()) {
;     ...
;             PG8_LDB(B0, 1, 0); PG8_LDB(B1, 1, 1); PG8_SCHED; PG8_LDA(At, 1, 0); PG8_STAGE(PG8_SA(0, 1), a2 + hA, voffA);
;             PG8_WAIT_V(8); PG8_WAIT_L(0); PG8_BAR; PG8_MMA(0, 0, At, B0); PG8_MMA(0, 1, At, B1); PG8_BAR; PG8_SCHED;
;             PG8_LDA(At, 1, 1); PG8_STAGE(PG8_SB(1, 0), b3, voffB); PG8_STAGE(PG8_SB(1, 1), b3 + hB, voffB); PG8_STAGE(PG8_SA(1, 0), a3, voffA);
;             PG8_WAIT_V(8); PG8_WAIT_L(0); PG8_BAR; PG8_MMA(1, 0, At, B0); PG8_MMA(1, 1, At, B1); PG8_BAR; PG8_SCHED;
	s_setprio 0
	s_add_i32 s51, 0, 0x18000
	s_add_i32 s52, 0, 0x1c000
	v_add_u32_e32 v160, s51, v144
	v_add_u32_e32 v176, s52, v144
	ds_read_b128 v[148:151], v160
	ds_read_b128 v[152:155], v160 offset:1024
	s_add_u32 s24, s24, 0x100000
	s_addc_u32 s25, s25, 0
	s_mov_b32 m0, s30
	s_nop 0
	global_load_lds_dwordx4 v132, s[24:25]
	ds_read_b128 v[156:159], v160 offset:2048
	ds_read_b128 v[160:163], v160 offset:3072
	ds_read_b128 v[164:167], v176
	ds_read_b128 v[168:171], v176 offset:1024
	ds_read_b128 v[172:175], v176 offset:2048
	ds_read_b128 v[176:179], v176 offset:3072
	ds_read_b128 v[180:183], v147 offset:32768
	s_mov_b32 m0, s31
	s_nop 0
	global_load_lds_dwordx4 v130, s[24:25]
	ds_read_b128 v[184:187], v147 offset:33792
	ds_read_b128 v[188:191], v147 offset:34816
	ds_read_b128 v[192:195], v147 offset:35840
	ds_read_b128 v[196:199], v147 offset:36864
	ds_read_b128 v[200:203], v147 offset:37888
	ds_read_b128 v[204:207], v147 offset:38912
	ds_read_b128 v[208:211], v147 offset:39936
	s_waitcnt vmcnt(8) lgkmcnt(0)
	s_barrier
	s_setprio 1
	v_mfma_f32_16x16x32_bf16 v[126:129], v[148:151], v[180:183], v[126:129]
	v_mfma_f32_16x16x32_bf16 v[122:125], v[156:159], v[180:183], v[122:125]
	v_mfma_f32_16x16x32_bf16 v[118:121], v[148:151], v[188:191], v[118:121]
	v_mfma_f32_16x16x32_bf16 v[114:117], v[156:159], v[188:191], v[114:117]
	v_mfma_f32_16x16x32_bf16 v[106:109], v[148:151], v[196:199], v[106:109]
	v_mfma_f32_16x16x32_bf16 v[98:101], v[156:159], v[196:199], v[98:101]
	v_mfma_f32_16x16x32_bf16 v[90:93], v[148:151], v[204:207], v[90:93]
	v_mfma_f32_16x16x32_bf16 v[82:85], v[156:159], v[204:207], v[82:85]
	v_mfma_f32_16x16x32_bf16 v[126:129], v[152:155], v[184:187], v[126:129]
	v_mfma_f32_16x16x32_bf16 v[122:125], v[160:163], v[184:187], v[122:125]
	v_mfma_f32_16x16x32_bf16 v[118:121], v[152:155], v[192:195], v[118:121]
	v_mfma_f32_16x16x32_bf16 v[114:117], v[160:163], v[192:195], v[114:117]
	v_mfma_f32_16x16x32_bf16 v[106:109], v[152:155], v[200:203], v[106:109]
	v_mfma_f32_16x16x32_bf16 v[98:101], v[160:163], v[200:203], v[98:101]
	v_mfma_f32_16x16x32_bf16 v[90:93], v[152:155], v[208:211], v[90:93]
	v_mfma_f32_16x16x32_bf16 v[82:85], v[160:163], v[208:211], v[82:85]
	s_setprio 0
	s_setprio 1
	v_mfma_f32_16x16x32_bf16 v[110:113], v[164:167], v[180:183], v[110:113]
	v_mfma_f32_16x16x32_bf16 v[102:105], v[172:175], v[180:183], v[102:105]
	v_mfma_f32_16x16x32_bf16 v[94:97], v[164:167], v[188:191], v[94:97]
	v_mfma_f32_16x16x32_bf16 v[86:89], v[172:175], v[188:191], v[86:89]
	v_mfma_f32_16x16x32_bf16 v[78:81], v[164:167], v[196:199], v[78:81]
	v_mfma_f32_16x16x32_bf16 v[74:77], v[172:175], v[196:199], v[74:77]
	v_mfma_f32_16x16x32_bf16 v[70:73], v[164:167], v[204:207], v[70:73]
	v_mfma_f32_16x16x32_bf16 v[66:69], v[172:175], v[204:207], v[66:69]
	v_mfma_f32_16x16x32_bf16 v[110:113], v[168:171], v[184:187], v[110:113]
	v_mfma_f32_16x16x32_bf16 v[102:105], v[176:179], v[184:187], v[102:105]
	v_mfma_f32_16x16x32_bf16 v[94:97], v[168:171], v[192:195], v[94:97]
	v_mfma_f32_16x16x32_bf16 v[86:89], v[176:179], v[192:195], v[86:89]
	v_mfma_f32_16x16x32_bf16 v[78:81], v[168:171], v[200:203], v[78:81]
	v_mfma_f32_16x16x32_bf16 v[74:77], v[176:179], v[200:203], v[74:77]
	v_mfma_f32_16x16x32_bf16 v[70:73], v[168:171], v[208:211], v[70:73]
	v_mfma_f32_16x16x32_bf16 v[66:69], v[176:179], v[208:211], v[66:69]
	s_barrier
	s_setprio 0
	s_add_i32 s24, s51, s29
	s_add_u32 s54, s22, s8
	s_addc_u32 s55, s23, s9
	s_mov_b32 m0, s24
	ds_read_b128 v[180:183], v147 offset:49152
	ds_read_b128 v[184:187], v147 offset:50176
	global_load_lds_dwordx4 v132, s[54:55]
	ds_read_b128 v[188:191], v147 offset:51200
	s_add_i32 m0, s24, 0x2000
	s_add_u32 s22, s22, 0x100080
	s_addc_u32 s23, s23, 0
	s_add_i32 s24, s52, s29
	global_load_lds_dwordx4 v130, s[54:55]
	ds_read_b128 v[192:195], v147 offset:52224
	s_mov_b32 m0, s24
	s_nop 0
	global_load_lds_dwordx4 v132, s[22:23]
	ds_read_b128 v[196:199], v147 offset:53248
	s_add_i32 m0, s24, 0x2000
	s_nop 0
	global_load_lds_dwordx4 v130, s[22:23]
	ds_read_b128 v[200:203], v147 offset:54272
	s_mov_b32 m0, s35
	s_nop 0
	global_load_lds_dwordx4 v132, s[56:57]
	ds_read_b128 v[204:207], v147 offset:55296
	s_mov_b32 m0, s36
	s_nop 0
	global_load_lds_dwordx4 v130, s[56:57]
	s_add_i32 s50, s50, 2
	s_add_u32 s20, s20, 0x100
	s_addc_u32 s21, s21, 0
	s_add_u32 s42, s42, 0x100
	s_addc_u32 s43, s43, 0
	s_cmp_gt_u32 s50, 5
	ds_read_b128 v[208:211], v147 offset:56320
	s_waitcnt vmcnt(8) lgkmcnt(0)
	s_barrier
; #define PG8_MMA(ai, bj, At, Bt) do { __builtin_amdgcn_s_setprio(1); _Pragma("unroll") for (int m = 0; m < 4; ++m) _Pragma("unroll") for (int n = 0; n < 2; ++n) _Pragma("unroll") for (int k = 0; k < 2; ++k) \
;         acc[ai][bj][m][n] = __builtin_amdgcn_mfma_f32_16x16x32_bf16(Bt[n][k], At[m][k], acc[ai][bj][m][n], 0, 0, 0); __builtin_amdgcn_s_setprio(0); } while (0)
; #define PG8_WAIT_V(n) asm volatile("s_waitcnt vmcnt(" #n ")" ::: "memory")
; #define PG8_WAIT_L(n) asm volatile("s_waitcnt lgkmcnt(" #n ")" ::: "memory")
; #define PG8_BAR __builtin_amdgcn_s_barrier()
; #define PG8_SCHED __builtin_amdgcn_sched_barrier(0)
;     __device__ __forceinline__ void operator()(const f32x4 (&acc)[2][2][4][2], const Unit& u, int wr, int wc, int fr, int fq) const {
;         float* base = C + (size_t)(u.ka / kslab) * slab_stride;
;         const int row0 = u.pm * BM + wr * 64 + fr, col0 = wc * 32 + 4 * fq;
; #pragma unroll
;         for (int ai = 0; ai < 2; ++ai)
; #pragma unroll
;             for (int m = 0; m < 4; ++m) { float* rowp = base + (size_t)(row0 + ai * HALF + m * 16) * 256 + col0;
; #pragma unroll
;                 for (int bj = 0; bj < 2; ++bj)
; #pragma unroll
;                     for (int n = 0; n < 2; ++n) *(f32x4*)(rowp + bj * HALF + n * 16) = acc[ai][bj][m][n]; }
;     }
; template <class Epi, class Sched, bool ALIGN_EPI, class Hook = NoHook>
; __device__ __forceinline__ void gemm_phase(LAS unsigned char* lds, const Gemm g, const Sched& S, const Epi& E, const Hook& H = Hook()) {
;     ...
;             PG8_WAIT_V(8); PG8_WAIT_L(0); PG8_BAR; PG8_MMA(1, 0, At, B0); PG8_MMA(1, 1, At, B1); PG8_BAR; PG8_SCHED;
;         }
;         if constexpr (Hook::ON) H.after(te, acc, cur, wr, wc, fr, fq);
;         }
;         if constexpr (ALIGN_EPI) { if (wr == 0) PG8_BAR; }
;         if constexpr (!Epi::AFTER_DRAIN) { E(acc, cur, wr, wc, fr, fq); S.done(cur); }
;         if (!has_next) break;
	s_setprio 1
	v_mfma_f32_16x16x32_bf16 v[62:65], v[148:151], v[180:183], v[62:65]
	v_mfma_f32_16x16x32_bf16 v[58:61], v[156:159], v[180:183], v[58:61]
	v_mfma_f32_16x16x32_bf16 v[54:57], v[148:151], v[188:191], v[54:57]
	v_mfma_f32_16x16x32_bf16 v[50:53], v[156:159], v[188:191], v[50:53]
	v_mfma_f32_16x16x32_bf16 v[38:41], v[148:151], v[196:199], v[38:41]
	v_mfma_f32_16x16x32_bf16 v[34:37], v[156:159], v[196:199], v[34:37]
	v_mfma_f32_16x16x32_bf16 v[22:25], v[148:151], v[204:207], v[22:25]
	v_mfma_f32_16x16x32_bf16 v[18:21], v[156:159], v[204:207], v[18:21]
	v_mfma_f32_16x16x32_bf16 v[62:65], v[152:155], v[184:187], v[62:65]
	v_mfma_f32_16x16x32_bf16 v[58:61], v[160:163], v[184:187], v[58:61]
	v_mfma_f32_16x16x32_bf16 v[54:57], v[152:155], v[192:195], v[54:57]
	v_mfma_f32_16x16x32_bf16 v[50:53], v[160:163], v[192:195], v[50:53]
	v_mfma_f32_16x16x32_bf16 v[38:41], v[152:155], v[200:203], v[38:41]
	v_mfma_f32_16x16x32_bf16 v[34:37], v[160:163], v[200:203], v[34:37]
	v_mfma_f32_16x16x32_bf16 v[22:25], v[152:155], v[208:211], v[22:25]
	v_mfma_f32_16x16x32_bf16 v[18:21], v[160:163], v[208:211], v[18:21]
	s_setprio 0
	s_setprio 1
	v_mfma_f32_16x16x32_bf16 v[46:49], v[164:167], v[180:183], v[46:49]
	v_mfma_f32_16x16x32_bf16 v[42:45], v[172:175], v[180:183], v[42:45]
	v_mfma_f32_16x16x32_bf16 v[30:33], v[164:167], v[188:191], v[30:33]
	v_mfma_f32_16x16x32_bf16 v[26:29], v[172:175], v[188:191], v[26:29]
	v_mfma_f32_16x16x32_bf16 v[14:17], v[164:167], v[196:199], v[14:17]
	v_mfma_f32_16x16x32_bf16 v[10:13], v[172:175], v[196:199], v[10:13]
	v_mfma_f32_16x16x32_bf16 v[6:9], v[164:167], v[204:207], v[6:9]
	v_mfma_f32_16x16x32_bf16 v[2:5], v[172:175], v[204:207], v[2:5]
	v_mfma_f32_16x16x32_bf16 v[46:49], v[168:171], v[184:187], v[46:49]
	v_mfma_f32_16x16x32_bf16 v[42:45], v[176:179], v[184:187], v[42:45]
	v_mfma_f32_16x16x32_bf16 v[30:33], v[168:171], v[192:195], v[30:33]
	v_mfma_f32_16x16x32_bf16 v[26:29], v[176:179], v[192:195], v[26:29]
	v_mfma_f32_16x16x32_bf16 v[14:17], v[168:171], v[200:203], v[14:17]
	v_mfma_f32_16x16x32_bf16 v[10:13], v[176:179], v[200:203], v[10:13]
	v_mfma_f32_16x16x32_bf16 v[6:9], v[168:171], v[208:211], v[6:9]
	v_mfma_f32_16x16x32_bf16 v[2:5], v[176:179], v[208:211], v[2:5]
	s_barrier
	s_setprio 0
	s_cbranch_scc0 .LBB0_262
	s_ashr_i32 s11, s6, 31
	s_lshr_b32 s11, s11, 23
	s_add_i32 s6, s6, s11
	s_ashr_i32 s20, s6, 9
	s_ashr_i32 s21, s20, 31
	v_lshl_add_u32 v148, s4, 8, v1
	s_lshl_b64 s[20:21], s[20:21], 23
	v_ashrrev_i32_e32 v149, 31, v148
	v_lshl_add_u64 v[150:151], v[134:135], 0, s[20:21]
	v_lshlrev_b64 v[152:153], 10, v[148:149]
	v_lshl_add_u64 v[152:153], v[150:151], 0, v[152:153]
	global_store_dwordx4 v[152:153], v[126:129], off
	global_store_dwordx4 v[152:153], v[122:125], off offset:64
	global_store_dwordx4 v[152:153], v[110:113], off offset:512
	global_store_dwordx4 v[152:153], v[102:105], off offset:576
	s_mov_b32 s4, 0x20000
	s_mov_b64 s[20:21], 0x20000
	v_or_b32_e32 v102, 16, v148
	v_ashrrev_i32_e32 v103, 31, v102
	v_lshlrev_b64 v[102:103], 10, v[102:103]
	v_lshl_add_u64 v[102:103], v[150:151], 0, v[102:103]
	global_store_dwordx4 v[102:103], v[118:121], off
	global_store_dwordx4 v[102:103], v[114:117], off offset:64
	global_store_dwordx4 v[102:103], v[94:97], off offset:512
	global_store_dwordx4 v[102:103], v[86:89], off offset:576
	s_mov_b32 s6, s12
	s_mov_b64 s[22:23], s[18:19]
	v_or_b32_e32 v86, 32, v148
	v_ashrrev_i32_e32 v87, 31, v86
	v_lshlrev_b64 v[86:87], 10, v[86:87]
	v_lshl_add_u64 v[86:87], v[150:151], 0, v[86:87]
	global_store_dwordx4 v[86:87], v[106:109], off
	global_store_dwordx4 v[86:87], v[98:101], off offset:64
	global_store_dwordx4 v[86:87], v[78:81], off offset:512
	global_store_dwordx4 v[86:87], v[74:77], off offset:576
	s_nop 1
	v_or_b32_e32 v74, 48, v148
	v_ashrrev_i32_e32 v75, 31, v74
	v_lshlrev_b64 v[74:75], 10, v[74:75]
	v_lshl_add_u64 v[74:75], v[150:151], 0, v[74:75]
	global_store_dwordx4 v[74:75], v[90:93], off
	global_store_dwordx4 v[74:75], v[82:85], off offset:64
	global_store_dwordx4 v[74:75], v[70:73], off offset:512
	global_store_dwordx4 v[74:75], v[66:69], off offset:576
	s_nop 1
	v_add_co_u32_e32 v68, vcc, s4, v152
	s_mov_b32 s4, 0x24000
	s_nop 0
	v_addc_co_u32_e32 v69, vcc, 0, v153, vcc
	v_lshl_add_u64 v[66:67], v[152:153], 0, s[20:21]
	global_store_dwordx4 v[68:69], v[62:65], off
	global_store_dwordx4 v[66:67], v[58:61], off offset:64
	global_store_dwordx4 v[66:67], v[46:49], off offset:512
	global_store_dwordx4 v[66:67], v[42:45], off offset:576
	s_mov_b64 s[20:21], 0x24000
	s_nop 0
	v_add_co_u32_e32 v44, vcc, s4, v152
	s_mov_b32 s4, 0x28000
	s_nop 0
	v_addc_co_u32_e32 v45, vcc, 0, v153, vcc
	v_lshl_add_u64 v[42:43], v[152:153], 0, s[20:21]
	global_store_dwordx4 v[44:45], v[54:57], off
	global_store_dwordx4 v[42:43], v[50:53], off offset:64
	global_store_dwordx4 v[42:43], v[30:33], off offset:512
	global_store_dwordx4 v[42:43], v[26:29], off offset:576
	s_mov_b64 s[20:21], 0x28000
	s_nop 0
	v_add_co_u32_e32 v28, vcc, s4, v152
	v_lshl_add_u64 v[26:27], v[152:153], 0, s[20:21]
	s_nop 0
	v_addc_co_u32_e32 v29, vcc, 0, v153, vcc
	global_store_dwordx4 v[28:29], v[38:41], off
	global_store_dwordx4 v[26:27], v[34:37], off offset:64
	global_store_dwordx4 v[26:27], v[14:17], off offset:512
	global_store_dwordx4 v[26:27], v[10:13], off offset:576
	s_mov_b64 s[20:21], 0x2c000
	s_mov_b32 s4, s10
	v_add_co_u32_e32 v12, vcc, 0x2c000, v152
	v_lshl_add_u64 v[10:11], v[152:153], 0, s[20:21]
	s_nop 0
	v_addc_co_u32_e32 v13, vcc, 0, v153, vcc
	s_and_b64 vcc, exec, s[2:3]
	s_mov_b64 s[20:21], s[14:15]
	global_store_dwordx4 v[12:13], v[22:25], off
	global_store_dwordx4 v[10:11], v[18:21], off offset:64
	global_store_dwordx4 v[10:11], v[6:9], off offset:512
	global_store_dwordx4 v[10:11], v[2:5], off offset:576
	s_cbranch_vccz .LBB0_259
	s_waitcnt vmcnt(0)
	s_cmpk_gt_u32 s26, 0xff
	s_cbranch_scc1 .LBB0_266
	s_barrier

; #define PG8_STAGE(bufoff, gbase, voff) do { _Pragma("unroll") for (int _i = 0; _i < 2; ++_i) \
;         __builtin_amdgcn_global_load_lds((const unsigned*)((const char*)(gbase) + (voff)[_i]), (LAS unsigned*)(lds + (bufoff) + ldsw + _i * 8192), 16, 0, 0); } while (0)
; #define PG8_LDA(dst, b, h) do { _Pragma("unroll") for (int m = 0; m < 4; ++m) _Pragma("unroll") for (int k = 0; k < 2; ++k) dst[m][k] = *(const LAS bf16x8*)(lds + PG8_SA(b, h) + aoff + m * 2048 + k * 1024); } while (0)
; #define PG8_LDB(dst, b, h) do { _Pragma("unroll") for (int n = 0; n < 2; ++n) _Pragma("unroll") for (int k = 0; k < 2; ++k) dst[n][k] = *(const LAS bf16x8*)(lds + PG8_SB(b, h) + boff + n * 2048 + k * 1024); } while (0)
; #define PG8_MMA(ai, bj, At, Bt) do { __builtin_amdgcn_s_setprio(1); _Pragma("unroll") for (int m = 0; m < 4; ++m) _Pragma("unroll") for (int n = 0; n < 2; ++n) _Pragma("unroll") for (int k = 0; k < 2; ++k) \
;         acc[ai][bj][m][n] = __builtin_amdgcn_mfma_f32_16x16x32_bf16(Bt[n][k], At[m][k], acc[ai][bj][m][n], 0, 0, 0); __builtin_amdgcn_s_setprio(0); } while (0)
; #define PG8_WAIT_V(n) asm volatile("s_waitcnt vmcnt(" #n ")" ::: "memory")
; #define PG8_WAIT_L(n) asm volatile("s_waitcnt lgkmcnt(" #n ")" ::: "memory")
; template <class Epi, class Sched, bool ALIGN_EPI, class Hook = NoHook>
; __device__ __forceinline__ void gemm_phase(LAS unsigned char* lds, const Gemm g, const Sched& S, const Epi& E, const Hook& H = Hook()) {
;     ...
;         for (int t = tb; t < te; t += 2) {
;             const bool last = (t == nt - 2);
;             const char* a1 = cA + (size_t)(t + 1) * kstep;
;             const char* a2 = last ? nA : cA + (size_t)(t + 2) * kstep; const char* b2 = last ? nB : cB + (size_t)(t + 2) * kstep;
;             const char* a3 = a2 + kstep; const char* b3 = b2 + kstep;
;             if (last && has_next) S.a_ready(nxt);
;             PG8_LDB(B0, 0, 0); PG8_LDB(B1, 0, 1); PG8_SCHED; PG8_LDA(At, 0, 0); PG8_STAGE(PG8_SA(1, 1), a1 + hA, voffA);
;             PG8_WAIT_V(8); PG8_WAIT_L(0); PG8_BAR; PG8_MMA(0, 0, At, B0); PG8_MMA(0, 1, At, B1); PG8_BAR; PG8_SCHED;
;             PG8_LDA(At, 0, 1); PG8_STAGE(PG8_SB(0, 0), b2, voffB); PG8_STAGE(PG8_SB(0, 1), b2 + hB, voffB); PG8_STAGE(PG8_SA(0, 0), a2, voffA);
;             PG8_WAIT_V(8); PG8_WAIT_L(0); PG8_BAR; PG8_MMA(1, 0, At, B0); PG8_MMA(1, 1, At, B1); PG8_BAR; PG8_SCHED;
.LBB0_783:
	v_add_u32_e32 v3, s56, v222
	s_add_i32 s67, s67, 2
	ds_read_b128 v[126:129], v3
	ds_read_b128 v[130:133], v3 offset:1024
	ds_read_b128 v[142:145], v3 offset:2048
	ds_read_b128 v[146:149], v3 offset:3072
	v_add_u32_e32 v3, s57, v222
	s_add_u32 s28, s22, s26
	s_addc_u32 s29, s23, s27
	s_add_u32 s28, s28, 0x100
	s_addc_u32 s29, s29, 0
	s_add_u32 s68, s63, s26
	s_addc_u32 s69, s64, s27
	s_cmpk_eq_i32 s26, 0x5f00
	s_cselect_b32 s31, s5, s29
	s_cselect_b32 s30, s4, s28
	s_cselect_b32 s29, s21, s69
	s_cselect_b32 s28, s20, s68
	ds_read_b128 v[150:153], v3
	ds_read_b128 v[154:157], v3 offset:1024
	ds_read_b128 v[158:161], v3 offset:2048
	ds_read_b128 v[162:165], v3 offset:3072
	v_lshl_add_u64 v[4:5], v[182:183], 0, s[26:27]
	s_add_i32 m0, s37, 0xc000
	s_nop 0
	global_load_lds_dwordx4 v[4:5], off
	ds_read_b128 v[186:189], v224
	ds_read_b128 v[190:193], v224 offset:1024
	ds_read_b128 v[194:197], v224 offset:2048
	ds_read_b128 v[198:201], v224 offset:3072
	ds_read_b128 v[202:205], v224 offset:4096
	ds_read_b128 v[206:209], v224 offset:5120
	ds_read_b128 v[210:213], v224 offset:6144
	ds_read_b128 v[214:217], v224 offset:7168
	v_lshl_add_u64 v[4:5], v[184:185], 0, s[26:27]
	s_add_i32 m0, s37, 0xe000
	s_nop 0
	global_load_lds_dwordx4 v[4:5], off
	s_waitcnt vmcnt(8) lgkmcnt(0)
	s_barrier
	s_setprio 1
	v_mfma_f32_16x16x32_bf16 v[138:141], v[126:129], v[186:189], v[138:141]
	v_mfma_f32_16x16x32_bf16 v[134:137], v[142:145], v[186:189], v[134:137]
	v_mfma_f32_16x16x32_bf16 v[122:125], v[126:129], v[194:197], v[122:125]
	v_mfma_f32_16x16x32_bf16 v[118:121], v[142:145], v[194:197], v[118:121]
	v_mfma_f32_16x16x32_bf16 v[114:117], v[126:129], v[202:205], v[114:117]
	v_mfma_f32_16x16x32_bf16 v[110:113], v[142:145], v[202:205], v[110:113]
	v_mfma_f32_16x16x32_bf16 v[106:109], v[126:129], v[210:213], v[106:109]
	v_mfma_f32_16x16x32_bf16 v[102:105], v[142:145], v[210:213], v[102:105]
	v_mfma_f32_16x16x32_bf16 v[138:141], v[130:133], v[190:193], v[138:141]
	v_mfma_f32_16x16x32_bf16 v[134:137], v[146:149], v[190:193], v[134:137]
	v_mfma_f32_16x16x32_bf16 v[122:125], v[130:133], v[198:201], v[122:125]
	v_mfma_f32_16x16x32_bf16 v[118:121], v[146:149], v[198:201], v[118:121]
	v_mfma_f32_16x16x32_bf16 v[114:117], v[130:133], v[206:209], v[114:117]
	v_mfma_f32_16x16x32_bf16 v[110:113], v[146:149], v[206:209], v[110:113]
	v_mfma_f32_16x16x32_bf16 v[106:109], v[130:133], v[214:217], v[106:109]
	v_mfma_f32_16x16x32_bf16 v[102:105], v[146:149], v[214:217], v[102:105]
	s_setprio 0
	s_setprio 1
	v_mfma_f32_16x16x32_bf16 v[66:69], v[150:153], v[186:189], v[66:69]
	v_mfma_f32_16x16x32_bf16 v[62:65], v[158:161], v[186:189], v[62:65]
	v_mfma_f32_16x16x32_bf16 v[58:61], v[150:153], v[194:197], v[58:61]
	v_mfma_f32_16x16x32_bf16 v[54:57], v[158:161], v[194:197], v[54:57]
	v_mfma_f32_16x16x32_bf16 v[50:53], v[150:153], v[202:205], v[50:53]
	v_mfma_f32_16x16x32_bf16 v[46:49], v[158:161], v[202:205], v[46:49]
	v_mfma_f32_16x16x32_bf16 v[42:45], v[150:153], v[210:213], v[42:45]
	v_mfma_f32_16x16x32_bf16 v[38:41], v[158:161], v[210:213], v[38:41]
	v_mfma_f32_16x16x32_bf16 v[66:69], v[154:157], v[190:193], v[66:69]
	v_mfma_f32_16x16x32_bf16 v[62:65], v[162:165], v[190:193], v[62:65]
	v_mfma_f32_16x16x32_bf16 v[58:61], v[154:157], v[198:201], v[58:61]
	v_mfma_f32_16x16x32_bf16 v[54:57], v[162:165], v[198:201], v[54:57]
	v_mfma_f32_16x16x32_bf16 v[50:53], v[154:157], v[206:209], v[50:53]
	v_mfma_f32_16x16x32_bf16 v[46:49], v[162:165], v[206:209], v[46:49]
	v_mfma_f32_16x16x32_bf16 v[42:45], v[154:157], v[214:217], v[42:45]
	v_mfma_f32_16x16x32_bf16 v[38:41], v[162:165], v[214:217], v[38:41]
	s_barrier
	s_setprio 0
	s_add_i32 s68, s56, s35
	s_mov_b32 m0, s68
	ds_read_b128 v[186:189], v224 offset:16384
	ds_read_b128 v[190:193], v224 offset:17408
	global_load_lds_dwordx4 v168, s[28:29]
	ds_read_b128 v[194:197], v224 offset:18432
	s_add_i32 m0, s68, 0x2000
	s_add_u32 s68, s28, 0x300000
	s_addc_u32 s69, s29, 0
	s_add_i32 s70, s57, s35
	global_load_lds_dwordx4 v172, s[28:29]
	ds_read_b128 v[198:201], v224 offset:19456
	s_mov_b32 m0, s70
	s_add_u32 s74, s30, s14
	s_addc_u32 s75, s31, s15
	global_load_lds_dwordx4 v168, s[68:69]
	ds_read_b128 v[202:205], v224 offset:20480
	s_add_i32 m0, s70, 0x2000
	s_nop 0
	global_load_lds_dwordx4 v172, s[68:69]
	ds_read_b128 v[206:209], v224 offset:21504
	s_mov_b32 m0, s37
	s_nop 0
	global_load_lds_dwordx4 v166, s[30:31]
	ds_read_b128 v[210:213], v224 offset:22528
	s_mov_b32 m0, s38
	s_nop 0
	global_load_lds_dwordx4 v170, s[30:31]
	ds_read_b128 v[214:217], v224 offset:23552
	s_waitcnt vmcnt(8) lgkmcnt(0)
	s_barrier
; #define PG8_STAGE(bufoff, gbase, voff) do { _Pragma("unroll") for (int _i = 0; _i < 2; ++_i) \
;         __builtin_amdgcn_global_load_lds((const unsigned*)((const char*)(gbase) + (voff)[_i]), (LAS unsigned*)(lds + (bufoff) + ldsw + _i * 8192), 16, 0, 0); } while (0)
; #define PG8_LDA(dst, b, h) do { _Pragma("unroll") for (int m = 0; m < 4; ++m) _Pragma("unroll") for (int k = 0; k < 2; ++k) dst[m][k] = *(const LAS bf16x8*)(lds + PG8_SA(b, h) + aoff + m * 2048 + k * 1024); } while (0)
; #define PG8_LDB(dst, b, h) do { _Pragma("unroll") for (int n = 0; n < 2; ++n) _Pragma("unroll") for (int k = 0; k < 2; ++k) dst[n][k] = *(const LAS bf16x8*)(lds + PG8_SB(b, h) + boff + n * 2048 + k * 1024); } while (0)
; #define PG8_MMA(ai, bj, At, Bt) do { __builtin_amdgcn_s_setprio(1); _Pragma("unroll") for (int m = 0; m < 4; ++m) _Pragma("unroll") for (int n = 0; n < 2; ++n) _Pragma("unroll") for (int k = 0; k < 2; ++k) \
;         acc[ai][bj][m][n] = __builtin_amdgcn_mfma_f32_16x16x32_bf16(Bt[n][k], At[m][k], acc[ai][bj][m][n], 0, 0, 0); __builtin_amdgcn_s_setprio(0); } while (0)
; #define PG8_WAIT_V(n) asm volatile("s_waitcnt vmcnt(" #n ")" ::: "memory")
; #define PG8_WAIT_L(n) asm volatile("s_waitcnt lgkmcnt(" #n ")" ::: "memory")
; #define PG8_BAR __builtin_amdgcn_s_barrier()
; #define PG8_SCHED __builtin_amdgcn_sched_barrier(0)
; template <class Epi, class Sched, bool ALIGN_EPI, class Hook = NoHook>
; __device__ __forceinline__ void gemm_phase(LAS unsigned char* lds, const Gemm g, const Sched& S, const Epi& E, const Hook& H = Hook()) {
;     ...
;             PG8_WAIT_V(8); PG8_WAIT_L(0); PG8_BAR; PG8_MMA(1, 0, At, B0); PG8_MMA(1, 1, At, B1); PG8_BAR; PG8_SCHED;
;             PG8_LDB(B0, 1, 0); PG8_LDB(B1, 1, 1); PG8_SCHED; PG8_LDA(At, 1, 0); PG8_STAGE(PG8_SA(0, 1), a2 + hA, voffA);
;             PG8_WAIT_V(8); PG8_WAIT_L(0); PG8_BAR; PG8_MMA(0, 0, At, B0); PG8_MMA(0, 1, At, B1); PG8_BAR; PG8_SCHED;
;             PG8_LDA(At, 1, 1); PG8_STAGE(PG8_SB(1, 0), b3, voffB); PG8_STAGE(PG8_SB(1, 1), b3 + hB, voffB); PG8_STAGE(PG8_SA(1, 0), a3, voffA);
	s_setprio 1
	v_mfma_f32_16x16x32_bf16 v[98:101], v[126:129], v[186:189], v[98:101]
	v_mfma_f32_16x16x32_bf16 v[94:97], v[142:145], v[186:189], v[94:97]
	v_mfma_f32_16x16x32_bf16 v[90:93], v[126:129], v[194:197], v[90:93]
	v_mfma_f32_16x16x32_bf16 v[86:89], v[142:145], v[194:197], v[86:89]
	v_mfma_f32_16x16x32_bf16 v[82:85], v[126:129], v[202:205], v[82:85]
	v_mfma_f32_16x16x32_bf16 v[78:81], v[142:145], v[202:205], v[78:81]
	v_mfma_f32_16x16x32_bf16 v[74:77], v[126:129], v[210:213], v[74:77]
	v_mfma_f32_16x16x32_bf16 v[70:73], v[142:145], v[210:213], v[70:73]
	v_mfma_f32_16x16x32_bf16 v[98:101], v[130:133], v[190:193], v[98:101]
	v_mfma_f32_16x16x32_bf16 v[94:97], v[146:149], v[190:193], v[94:97]
	v_mfma_f32_16x16x32_bf16 v[90:93], v[130:133], v[198:201], v[90:93]
	v_mfma_f32_16x16x32_bf16 v[86:89], v[146:149], v[198:201], v[86:89]
	v_mfma_f32_16x16x32_bf16 v[82:85], v[130:133], v[206:209], v[82:85]
	v_mfma_f32_16x16x32_bf16 v[78:81], v[146:149], v[206:209], v[78:81]
	v_mfma_f32_16x16x32_bf16 v[74:77], v[130:133], v[214:217], v[74:77]
	v_mfma_f32_16x16x32_bf16 v[70:73], v[146:149], v[214:217], v[70:73]
	s_setprio 0
	s_setprio 1
	v_mfma_f32_16x16x32_bf16 v[34:37], v[150:153], v[186:189], v[34:37]
	v_mfma_f32_16x16x32_bf16 v[30:33], v[158:161], v[186:189], v[30:33]
	v_mfma_f32_16x16x32_bf16 v[26:29], v[150:153], v[194:197], v[26:29]
	v_mfma_f32_16x16x32_bf16 v[22:25], v[158:161], v[194:197], v[22:25]
	v_mfma_f32_16x16x32_bf16 v[18:21], v[150:153], v[202:205], v[18:21]
	v_mfma_f32_16x16x32_bf16 v[14:17], v[158:161], v[202:205], v[14:17]
	v_mfma_f32_16x16x32_bf16 v[10:13], v[150:153], v[210:213], v[10:13]
	v_mfma_f32_16x16x32_bf16 v[4:7], v[158:161], v[210:213], v[6:9]
	v_mfma_f32_16x16x32_bf16 v[34:37], v[154:157], v[190:193], v[34:37]
	v_mfma_f32_16x16x32_bf16 v[30:33], v[162:165], v[190:193], v[30:33]
	v_mfma_f32_16x16x32_bf16 v[26:29], v[154:157], v[198:201], v[26:29]
	v_mfma_f32_16x16x32_bf16 v[22:25], v[162:165], v[198:201], v[22:25]
	v_mfma_f32_16x16x32_bf16 v[18:21], v[154:157], v[206:209], v[18:21]
	v_mfma_f32_16x16x32_bf16 v[14:17], v[162:165], v[206:209], v[14:17]
	v_mfma_f32_16x16x32_bf16 v[10:13], v[154:157], v[214:217], v[10:13]
	v_mfma_f32_16x16x32_bf16 v[4:7], v[162:165], v[214:217], v[4:7]
	s_barrier
	s_setprio 0
	s_add_i32 s68, 0, 0x18000
	v_add_u32_e32 v3, s68, v222
	s_add_i32 s69, 0, 0x1c000
	ds_read_b128 v[126:129], v3
	ds_read_b128 v[130:133], v3 offset:1024
	ds_read_b128 v[142:145], v3 offset:2048
	ds_read_b128 v[146:149], v3 offset:3072
	v_add_u32_e32 v3, s69, v222
	s_add_u32 s30, s30, 0x300000
	s_addc_u32 s31, s31, 0
	s_mov_b32 m0, s39
	s_nop 0
	global_load_lds_dwordx4 v166, s[30:31]
	ds_read_b128 v[150:153], v3
	ds_read_b128 v[154:157], v3 offset:1024
	ds_read_b128 v[158:161], v3 offset:2048
	ds_read_b128 v[162:165], v3 offset:3072
	ds_read_b128 v[186:189], v224 offset:32768
	ds_read_b128 v[190:193], v224 offset:33792
	ds_read_b128 v[194:197], v224 offset:34816
	s_mov_b32 m0, s40
	s_nop 0
	global_load_lds_dwordx4 v170, s[30:31]
	ds_read_b128 v[198:201], v224 offset:35840
	ds_read_b128 v[202:205], v224 offset:36864
	ds_read_b128 v[206:209], v224 offset:37888
	ds_read_b128 v[210:213], v224 offset:38912
	ds_read_b128 v[214:217], v224 offset:39936
	s_waitcnt vmcnt(8) lgkmcnt(0)
	s_barrier
	s_setprio 1
	v_mfma_f32_16x16x32_bf16 v[138:141], v[126:129], v[186:189], v[138:141]
	v_mfma_f32_16x16x32_bf16 v[134:137], v[142:145], v[186:189], v[134:137]
	v_mfma_f32_16x16x32_bf16 v[122:125], v[126:129], v[194:197], v[122:125]
	v_mfma_f32_16x16x32_bf16 v[118:121], v[142:145], v[194:197], v[118:121]
	v_mfma_f32_16x16x32_bf16 v[114:117], v[126:129], v[202:205], v[114:117]
	v_mfma_f32_16x16x32_bf16 v[110:113], v[142:145], v[202:205], v[110:113]
	v_mfma_f32_16x16x32_bf16 v[106:109], v[126:129], v[210:213], v[106:109]
	v_mfma_f32_16x16x32_bf16 v[102:105], v[142:145], v[210:213], v[102:105]
	v_mfma_f32_16x16x32_bf16 v[138:141], v[130:133], v[190:193], v[138:141]
	v_mfma_f32_16x16x32_bf16 v[134:137], v[146:149], v[190:193], v[134:137]
	v_mfma_f32_16x16x32_bf16 v[122:125], v[130:133], v[198:201], v[122:125]
	v_mfma_f32_16x16x32_bf16 v[118:121], v[146:149], v[198:201], v[118:121]
	v_mfma_f32_16x16x32_bf16 v[114:117], v[130:133], v[206:209], v[114:117]
	v_mfma_f32_16x16x32_bf16 v[110:113], v[146:149], v[206:209], v[110:113]
	v_mfma_f32_16x16x32_bf16 v[106:109], v[130:133], v[214:217], v[106:109]
	v_mfma_f32_16x16x32_bf16 v[102:105], v[146:149], v[214:217], v[102:105]
	s_setprio 0
	s_setprio 1
	v_mfma_f32_16x16x32_bf16 v[66:69], v[150:153], v[186:189], v[66:69]
	v_mfma_f32_16x16x32_bf16 v[62:65], v[158:161], v[186:189], v[62:65]
	v_mfma_f32_16x16x32_bf16 v[58:61], v[150:153], v[194:197], v[58:61]
	v_mfma_f32_16x16x32_bf16 v[54:57], v[158:161], v[194:197], v[54:57]
	v_mfma_f32_16x16x32_bf16 v[50:53], v[150:153], v[202:205], v[50:53]
	v_mfma_f32_16x16x32_bf16 v[46:49], v[158:161], v[202:205], v[46:49]
	v_mfma_f32_16x16x32_bf16 v[42:45], v[150:153], v[210:213], v[42:45]
	v_mfma_f32_16x16x32_bf16 v[38:41], v[158:161], v[210:213], v[38:41]
	v_mfma_f32_16x16x32_bf16 v[66:69], v[154:157], v[190:193], v[66:69]
	v_mfma_f32_16x16x32_bf16 v[62:65], v[162:165], v[190:193], v[62:65]
	v_mfma_f32_16x16x32_bf16 v[58:61], v[154:157], v[198:201], v[58:61]
	v_mfma_f32_16x16x32_bf16 v[54:57], v[162:165], v[198:201], v[54:57]
	v_mfma_f32_16x16x32_bf16 v[50:53], v[154:157], v[206:209], v[50:53]
	v_mfma_f32_16x16x32_bf16 v[46:49], v[162:165], v[206:209], v[46:49]
	v_mfma_f32_16x16x32_bf16 v[42:45], v[154:157], v[214:217], v[42:45]
	v_mfma_f32_16x16x32_bf16 v[38:41], v[162:165], v[214:217], v[38:41]
	s_barrier
; #define PG8_STAGE(bufoff, gbase, voff) do { _Pragma("unroll") for (int _i = 0; _i < 2; ++_i) \
;         __builtin_amdgcn_global_load_lds((const unsigned*)((const char*)(gbase) + (voff)[_i]), (LAS unsigned*)(lds + (bufoff) + ldsw + _i * 8192), 16, 0, 0); } while (0)
; #define PG8_LDA(dst, b, h) do { _Pragma("unroll") for (int m = 0; m < 4; ++m) _Pragma("unroll") for (int k = 0; k < 2; ++k) dst[m][k] = *(const LAS bf16x8*)(lds + PG8_SA(b, h) + aoff + m * 2048 + k * 1024); } while (0)
; #define PG8_MMA(ai, bj, At, Bt) do { __builtin_amdgcn_s_setprio(1); _Pragma("unroll") for (int m = 0; m < 4; ++m) _Pragma("unroll") for (int n = 0; n < 2; ++n) _Pragma("unroll") for (int k = 0; k < 2; ++k) \
;         acc[ai][bj][m][n] = __builtin_amdgcn_mfma_f32_16x16x32_bf16(Bt[n][k], At[m][k], acc[ai][bj][m][n], 0, 0, 0); __builtin_amdgcn_s_setprio(0); } while (0)
; #define PG8_WAIT_V(n) asm volatile("s_waitcnt vmcnt(" #n ")" ::: "memory")
; #define PG8_WAIT_L(n) asm volatile("s_waitcnt lgkmcnt(" #n ")" ::: "memory")
; #define PG8_BAR __builtin_amdgcn_s_barrier()
; #define PG8_SCHED __builtin_amdgcn_sched_barrier(0)
;     __device__ __forceinline__ void after(int te, f32x4 (&acc)[2][2][4][2], const Unit& u, int wr, int wc, int fr, int fq) const {
;         if (te > D_INNER / BK) return;
;         const int g = (te >> 4) - 1;
;         asm volatile("" : "+v"(fr), "+v"(fq));
; #pragma unroll
;         for (int ai = 0; ai < 2; ++ai)
; #pragma unroll
;             for (int m = 0; m < 4; ++m) { const float f = tab[(ai * HALF + wr * 64 + m * 16 + fr) * 8 + g];
; #pragma unroll
;                 for (int bj = 0; bj < 2; ++bj)
; #pragma unroll
;                     for (int n = 0; n < 2; ++n) acc[ai][bj][m][n] *= f; }
; template <class Epi, class Sched, bool ALIGN_EPI, class Hook = NoHook>
; __device__ __forceinline__ void gemm_phase(LAS unsigned char* lds, const Gemm g, const Sched& S, const Epi& E, const Hook& H = Hook()) {
;     ...
;             PG8_LDA(At, 1, 1); PG8_STAGE(PG8_SB(1, 0), b3, voffB); PG8_STAGE(PG8_SB(1, 1), b3 + hB, voffB); PG8_STAGE(PG8_SA(1, 0), a3, voffA);
;             PG8_WAIT_V(8); PG8_WAIT_L(0); PG8_BAR; PG8_MMA(1, 0, At, B0); PG8_MMA(1, 1, At, B1); PG8_BAR; PG8_SCHED;
	s_setprio 0
	s_add_i32 s30, s68, s35
	s_add_u32 s72, s28, s14
	s_addc_u32 s73, s29, s15
	s_mov_b32 m0, s30
	ds_read_b128 v[186:189], v224 offset:49152
	ds_read_b128 v[190:193], v224 offset:50176
	global_load_lds_dwordx4 v168, s[72:73]
	ds_read_b128 v[194:197], v224 offset:51200
	s_add_i32 m0, s30, 0x2000
	s_add_u32 s28, s28, 0x300080
	s_addc_u32 s29, s29, 0
	s_add_i32 s30, s69, s35
	global_load_lds_dwordx4 v172, s[72:73]
	ds_read_b128 v[198:201], v224 offset:52224
	s_mov_b32 m0, s30
	s_nop 0
	global_load_lds_dwordx4 v168, s[28:29]
	ds_read_b128 v[202:205], v224 offset:53248
	s_add_i32 m0, s30, 0x2000
	s_nop 0
	global_load_lds_dwordx4 v172, s[28:29]
	ds_read_b128 v[206:209], v224 offset:54272
	s_mov_b32 m0, s45
	s_nop 0
	global_load_lds_dwordx4 v166, s[74:75]
	ds_read_b128 v[210:213], v224 offset:55296
	s_mov_b32 m0, s46
	s_nop 0
	global_load_lds_dwordx4 v170, s[74:75]
	s_add_u32 s26, s26, 0x100
	s_addc_u32 s27, s27, 0
	s_cmp_ge_u32 s67, s66
	ds_read_b128 v[214:217], v224 offset:56320
	s_waitcnt vmcnt(8) lgkmcnt(0)
	s_barrier
	s_setprio 1
	v_mfma_f32_16x16x32_bf16 v[98:101], v[126:129], v[186:189], v[98:101]
	v_mfma_f32_16x16x32_bf16 v[94:97], v[142:145], v[186:189], v[94:97]
	v_mfma_f32_16x16x32_bf16 v[90:93], v[126:129], v[194:197], v[90:93]
	v_mfma_f32_16x16x32_bf16 v[86:89], v[142:145], v[194:197], v[86:89]
	v_mfma_f32_16x16x32_bf16 v[82:85], v[126:129], v[202:205], v[82:85]
	v_mfma_f32_16x16x32_bf16 v[78:81], v[142:145], v[202:205], v[78:81]
	v_mfma_f32_16x16x32_bf16 v[74:77], v[126:129], v[210:213], v[74:77]
	v_mfma_f32_16x16x32_bf16 v[70:73], v[142:145], v[210:213], v[70:73]
	v_mfma_f32_16x16x32_bf16 v[98:101], v[130:133], v[190:193], v[98:101]
	v_mfma_f32_16x16x32_bf16 v[94:97], v[146:149], v[190:193], v[94:97]
	v_mfma_f32_16x16x32_bf16 v[90:93], v[130:133], v[198:201], v[90:93]
	v_mfma_f32_16x16x32_bf16 v[86:89], v[146:149], v[198:201], v[86:89]
	v_mfma_f32_16x16x32_bf16 v[82:85], v[130:133], v[206:209], v[82:85]
	v_mfma_f32_16x16x32_bf16 v[78:81], v[146:149], v[206:209], v[78:81]
	v_mfma_f32_16x16x32_bf16 v[74:77], v[130:133], v[214:217], v[74:77]
	v_mfma_f32_16x16x32_bf16 v[70:73], v[146:149], v[214:217], v[70:73]
	s_setprio 0
	s_setprio 1
	v_mfma_f32_16x16x32_bf16 v[34:37], v[150:153], v[186:189], v[34:37]
	v_mfma_f32_16x16x32_bf16 v[30:33], v[158:161], v[186:189], v[30:33]
	v_mfma_f32_16x16x32_bf16 v[26:29], v[150:153], v[194:197], v[26:29]
	v_mfma_f32_16x16x32_bf16 v[22:25], v[158:161], v[194:197], v[22:25]
	v_mfma_f32_16x16x32_bf16 v[18:21], v[150:153], v[202:205], v[18:21]
	v_mfma_f32_16x16x32_bf16 v[14:17], v[158:161], v[202:205], v[14:17]
	v_mfma_f32_16x16x32_bf16 v[8:11], v[150:153], v[210:213], v[10:13]
	v_mfma_f32_16x16x32_bf16 v[4:7], v[158:161], v[210:213], v[4:7]
	v_mfma_f32_16x16x32_bf16 v[34:37], v[154:157], v[190:193], v[34:37]
	v_mfma_f32_16x16x32_bf16 v[30:33], v[162:165], v[190:193], v[30:33]
	v_mfma_f32_16x16x32_bf16 v[26:29], v[154:157], v[198:201], v[26:29]
	v_mfma_f32_16x16x32_bf16 v[22:25], v[162:165], v[198:201], v[22:25]
	v_mfma_f32_16x16x32_bf16 v[18:21], v[154:157], v[206:209], v[18:21]
	v_mfma_f32_16x16x32_bf16 v[14:17], v[162:165], v[206:209], v[14:17]
	v_mfma_f32_16x16x32_bf16 v[10:13], v[154:157], v[214:217], v[8:11]
	v_mfma_f32_16x16x32_bf16 v[6:9], v[162:165], v[214:217], v[4:7]
	s_barrier
	s_setprio 0
	s_cbranch_scc0 .LBB0_783
	s_cmpk_gt_u32 s65, 0x7f
	s_cbranch_scc1 .LBB0_787
	s_lshr_b32 s26, s66, 4
	s_add_i32 s26, s26, -1
	v_mov_b32_e32 v3, v1
	v_mov_b32_e32 v4, v220
	s_lshl_b32 s27, s26, 2
	s_add_i32 s28, s27, s48
	v_lshlrev_b32_e32 v5, 5, v3
	v_add_u32_e32 v126, s28, v5
	ds_read_b32 v126, v126
	s_add_i32 s28, s27, s49
	s_waitcnt lgkmcnt(0)
	v_pk_mul_f32 v[140:141], v[140:141], v[126:127] op_sel_hi:[1,0]
	v_pk_mul_f32 v[138:139], v[138:139], v[126:127] op_sel_hi:[1,0]
	v_pk_mul_f32 v[136:137], v[136:137], v[126:127] op_sel_hi:[1,0]
	v_pk_mul_f32 v[134:135], v[134:135], v[126:127] op_sel_hi:[1,0]
	v_pk_mul_f32 v[68:69], v[68:69], v[126:127] op_sel_hi:[1,0]
	v_pk_mul_f32 v[66:67], v[66:67], v[126:127] op_sel_hi:[1,0]
	v_pk_mul_f32 v[64:65], v[64:65], v[126:127] op_sel_hi:[1,0]
	v_pk_mul_f32 v[62:63], v[62:63], v[126:127] op_sel_hi:[1,0]
	v_add_u32_e32 v126, s28, v5
	ds_read_b32 v126, v126
	s_add_i32 s28, s27, s50
	s_waitcnt lgkmcnt(0)
	v_pk_mul_f32 v[124:125], v[124:125], v[126:127] op_sel_hi:[1,0]
	v_pk_mul_f32 v[122:123], v[122:123], v[126:127] op_sel_hi:[1,0]
	v_pk_mul_f32 v[120:121], v[120:121], v[126:127] op_sel_hi:[1,0]
	v_pk_mul_f32 v[118:119], v[118:119], v[126:127] op_sel_hi:[1,0]
	v_pk_mul_f32 v[60:61], v[60:61], v[126:127] op_sel_hi:[1,0]
	v_pk_mul_f32 v[58:59], v[58:59], v[126:127] op_sel_hi:[1,0]
	v_pk_mul_f32 v[56:57], v[56:57], v[126:127] op_sel_hi:[1,0]
	v_pk_mul_f32 v[54:55], v[54:55], v[126:127] op_sel_hi:[1,0]
	v_add_u32_e32 v126, s28, v5
	ds_read_b32 v126, v126
	s_add_i32 s28, s27, s51
	s_waitcnt lgkmcnt(0)
	v_pk_mul_f32 v[116:117], v[116:117], v[126:127] op_sel_hi:[1,0]
	v_pk_mul_f32 v[114:115], v[114:115], v[126:127] op_sel_hi:[1,0]
	v_pk_mul_f32 v[112:113], v[112:113], v[126:127] op_sel_hi:[1,0]
	v_pk_mul_f32 v[110:111], v[110:111], v[126:127] op_sel_hi:[1,0]
	v_pk_mul_f32 v[52:53], v[52:53], v[126:127] op_sel_hi:[1,0]
	v_pk_mul_f32 v[50:51], v[50:51], v[126:127] op_sel_hi:[1,0]
	v_pk_mul_f32 v[48:49], v[48:49], v[126:127] op_sel_hi:[1,0]
	v_pk_mul_f32 v[46:47], v[46:47], v[126:127] op_sel_hi:[1,0]
	v_add_u32_e32 v126, s28, v5
	ds_read_b32 v126, v126
	s_add_i32 s28, s27, s52
	s_waitcnt lgkmcnt(0)
;     __device__ __forceinline__ void after(int te, f32x4 (&acc)[2][2][4][2], const Unit& u, int wr, int wc, int fr, int fq) const {
;     ...
;             for (int m = 0; m < 4; ++m) { const float f = tab[(ai * HALF + wr * 64 + m * 16 + fr) * 8 + g];
; #pragma unroll
;                 for (int bj = 0; bj < 2; ++bj)
; #pragma unroll
;                     for (int n = 0; n < 2; ++n) acc[ai][bj][m][n] *= f; }
;         if (g == 7) {
;             const int row0 = u.pm * BM + wr * 64 + fr, col0 = u.pn * BM + wc * 32 + 8 * fq;
; #pragma unroll
;             for (int bj = 0; bj < 2; ++bj) { const int c = col0 + bj * HALF;
;                 const f32x4 s0 = *(const f32x4*)(gb + c), s1 = *(const f32x4*)(gb + c + 4), a0 = *(const f32x4*)(gb + D_MODEL + c), a1 = *(const f32x4*)(gb + D_MODEL + c + 4);
; #pragma unroll
;                 for (int ai = 0; ai < 2; ++ai) {
;                     u32x4 gs[4], ga[4];
; #pragma unroll
;                     for (int m = 0; m < 4; ++m) { const size_t r = (size_t)(row0 + ai * HALF + m * 16); gs[m] = *(const u32x4*)(proj + r * LDP + PGS + c); ga[m] = *(const u32x4*)(proj + r * LDP + PGA + c); }
	v_pk_mul_f32 v[108:109], v[108:109], v[126:127] op_sel_hi:[1,0]
	v_pk_mul_f32 v[106:107], v[106:107], v[126:127] op_sel_hi:[1,0]
	v_pk_mul_f32 v[104:105], v[104:105], v[126:127] op_sel_hi:[1,0]
	v_pk_mul_f32 v[102:103], v[102:103], v[126:127] op_sel_hi:[1,0]
	v_pk_mul_f32 v[44:45], v[44:45], v[126:127] op_sel_hi:[1,0]
	v_pk_mul_f32 v[42:43], v[42:43], v[126:127] op_sel_hi:[1,0]
	v_pk_mul_f32 v[40:41], v[40:41], v[126:127] op_sel_hi:[1,0]
	v_pk_mul_f32 v[38:39], v[38:39], v[126:127] op_sel_hi:[1,0]
	v_add_u32_e32 v126, s28, v5
	ds_read_b32 v126, v126
	s_add_i32 s28, s27, s53
	s_waitcnt lgkmcnt(0)
	v_pk_mul_f32 v[100:101], v[100:101], v[126:127] op_sel_hi:[1,0]
	v_pk_mul_f32 v[98:99], v[98:99], v[126:127] op_sel_hi:[1,0]
	v_pk_mul_f32 v[96:97], v[96:97], v[126:127] op_sel_hi:[1,0]
	v_pk_mul_f32 v[94:95], v[94:95], v[126:127] op_sel_hi:[1,0]
	v_pk_mul_f32 v[36:37], v[36:37], v[126:127] op_sel_hi:[1,0]
	v_pk_mul_f32 v[34:35], v[34:35], v[126:127] op_sel_hi:[1,0]
	v_pk_mul_f32 v[32:33], v[32:33], v[126:127] op_sel_hi:[1,0]
	v_pk_mul_f32 v[30:31], v[30:31], v[126:127] op_sel_hi:[1,0]
	v_add_u32_e32 v126, s28, v5
	ds_read_b32 v126, v126
	s_add_i32 s28, s27, s54
	s_add_i32 s27, s27, s55
	s_cmp_lg_u32 s26, 7
	s_waitcnt lgkmcnt(0)
	v_pk_mul_f32 v[92:93], v[92:93], v[126:127] op_sel_hi:[1,0]
	v_pk_mul_f32 v[90:91], v[90:91], v[126:127] op_sel_hi:[1,0]
	v_pk_mul_f32 v[88:89], v[88:89], v[126:127] op_sel_hi:[1,0]
	v_pk_mul_f32 v[86:87], v[86:87], v[126:127] op_sel_hi:[1,0]
	v_pk_mul_f32 v[28:29], v[28:29], v[126:127] op_sel_hi:[1,0]
	v_pk_mul_f32 v[26:27], v[26:27], v[126:127] op_sel_hi:[1,0]
	v_pk_mul_f32 v[24:25], v[24:25], v[126:127] op_sel_hi:[1,0]
	v_pk_mul_f32 v[22:23], v[22:23], v[126:127] op_sel_hi:[1,0]
	v_add_u32_e32 v126, s28, v5
	ds_read_b32 v126, v126
	v_add_u32_e32 v5, s27, v5
	s_waitcnt lgkmcnt(0)
	v_pk_mul_f32 v[84:85], v[84:85], v[126:127] op_sel_hi:[1,0]
	v_pk_mul_f32 v[82:83], v[82:83], v[126:127] op_sel_hi:[1,0]
	v_pk_mul_f32 v[80:81], v[80:81], v[126:127] op_sel_hi:[1,0]
	v_pk_mul_f32 v[78:79], v[78:79], v[126:127] op_sel_hi:[1,0]
	v_pk_mul_f32 v[20:21], v[20:21], v[126:127] op_sel_hi:[1,0]
	v_pk_mul_f32 v[18:19], v[18:19], v[126:127] op_sel_hi:[1,0]
	v_pk_mul_f32 v[16:17], v[16:17], v[126:127] op_sel_hi:[1,0]
	v_pk_mul_f32 v[14:15], v[14:15], v[126:127] op_sel_hi:[1,0]
	ds_read_b32 v126, v5
	s_waitcnt lgkmcnt(0)
	v_pk_mul_f32 v[76:77], v[76:77], v[126:127] op_sel_hi:[1,0]
	v_pk_mul_f32 v[74:75], v[74:75], v[126:127] op_sel_hi:[1,0]
	v_pk_mul_f32 v[72:73], v[72:73], v[126:127] op_sel_hi:[1,0]
	v_pk_mul_f32 v[70:71], v[70:71], v[126:127] op_sel_hi:[1,0]
	v_pk_mul_f32 v[12:13], v[12:13], v[126:127] op_sel_hi:[1,0]
	v_pk_mul_f32 v[10:11], v[10:11], v[126:127] op_sel_hi:[1,0]
	v_pk_mul_f32 v[8:9], v[8:9], v[126:127] op_sel_hi:[1,0]
	v_pk_mul_f32 v[6:7], v[6:7], v[126:127] op_sel_hi:[1,0]
	s_cbranch_scc1 .LBB0_787
	v_add_u32_e32 v126, s62, v3
	v_ashrrev_i32_e32 v127, 31, v126
	v_lshl_add_u32 v4, v4, 3, s61
	v_lshlrev_b64 v[126:127], 14, v[126:127]
	v_ashrrev_i32_e32 v5, 31, v4
	v_lshl_add_u64 v[126:127], s[76:77], 0, v[126:127]
	v_lshl_add_u64 v[192:193], v[4:5], 1, v[126:127]
	v_readlane_b32 s68, v254, 20
	global_load_dwordx4 v[204:207], v[192:193], off
	v_add_co_u32_e32 v126, vcc, s41, v192
	v_lshlrev_b64 v[4:5], 2, v[4:5]
	v_readlane_b32 s70, v254, 22
	v_readlane_b32 s71, v254, 23
	v_addc_co_u32_e32 v127, vcc, 0, v193, vcc
	s_nop 0
	v_lshl_add_u64 v[196:197], s[70:71], 0, v[4:5]
	global_load_dwordx4 v[208:211], v[126:127], off
	global_load_dwordx4 v[142:145], v[196:197], off
	s_nop 0
	global_load_dwordx4 v[126:129], v[196:197], off offset:16
	v_lshl_add_u64 v[198:199], s[12:13], 0, v[4:5]
	global_load_dwordx4 v[146:149], v[198:199], off
	global_load_dwordx4 v[130:133], v[198:199], off offset:16
	s_mov_b64 s[26:27], 0x40000
	v_lshl_add_u64 v[4:5], v[192:193], 0, s[26:27]
	s_mov_b32 s26, 0x40000
	v_add_co_u32_e32 v150, vcc, s26, v192
	s_mov_b64 s[26:27], 0x42000
	s_nop 0
	v_addc_co_u32_e32 v151, vcc, 0, v193, vcc
	v_lshl_add_u64 v[186:187], v[192:193], 0, s[26:27]
	s_mov_b32 s26, 0x42000
	v_add_co_u32_e32 v152, vcc, s26, v192
	s_mov_b64 s[26:27], 0x80000
	s_nop 0
	v_addc_co_u32_e32 v153, vcc, 0, v193, vcc
	v_lshl_add_u64 v[188:189], v[192:193], 0, s[26:27]
	s_mov_b32 s26, 0x80000
	v_add_co_u32_e32 v154, vcc, s26, v192
	s_mov_b64 s[26:27], 0x82000
	s_nop 0
	v_addc_co_u32_e32 v155, vcc, 0, v193, vcc
	v_lshl_add_u64 v[190:191], v[192:193], 0, s[26:27]
	s_mov_b32 s26, 0x82000
	v_add_co_u32_e32 v156, vcc, s26, v192
	s_mov_b64 s[26:27], 0xc0000
	s_nop 0
	v_addc_co_u32_e32 v157, vcc, 0, v193, vcc
	v_lshl_add_u64 v[194:195], v[192:193], 0, s[26:27]
	s_mov_b32 s26, 0xc0000
	v_add_co_u32_e32 v228, vcc, s26, v192
	s_mov_b64 s[26:27], 0xc2000
	s_nop 0
	v_addc_co_u32_e32 v229, vcc, 0, v193, vcc
	v_lshl_add_u64 v[200:201], v[192:193], 0, s[26:27]
	s_mov_b32 s26, 0xc2000
	v_add_co_u32_e32 v230, vcc, s26, v192
	s_mov_b32 s26, 0x200000
	s_nop 0
	v_addc_co_u32_e32 v231, vcc, 0, v193, vcc
	global_load_dwordx4 v[212:215], v[150:151], off
	global_load_dwordx4 v[216:219], v[152:153], off
	global_load_dwordx4 v[162:165], v[154:155], off
	global_load_dwordx4 v[158:161], v[156:157], off
	s_nop 0
	global_load_dwordx4 v[154:157], v[228:229], off
	global_load_dwordx4 v[150:153], v[230:231], off
	v_lshl_add_u64 v[202:203], v[192:193], 0, s[18:19]
	v_readlane_b32 s76, v254, 28
	v_readlane_b32 s77, v254, 29
	v_readlane_b32 s76, v255, 8
	v_readlane_b32 s77, v255, 9
	v_readlane_b32 s69, v254, 21
	v_readlane_b32 s72, v254, 24
	v_readlane_b32 s73, v254, 25
	v_readlane_b32 s74, v254, 26
	v_readlane_b32 s75, v254, 27
	v_readlane_b32 s78, v254, 30
	v_readlane_b32 s79, v254, 31
	v_readlane_b32 s80, v254, 32
	v_readlane_b32 s81, v254, 33
	v_readlane_b32 s82, v254, 34
	v_readlane_b32 s83, v254, 35
	s_waitcnt vmcnt(0)
; __device__ __forceinline__ void unpack8(const u32x4 w, float (&v)[8]) { v[0] = bf_lo(w.x); v[1] = bf_hi(w.x); v[2] = bf_lo(w.y); v[3] = bf_hi(w.y); v[4] = bf_lo(w.z); v[5] = bf_hi(w.z); v[6] = bf_lo(w.w); v[7] = bf_hi(w.w); }
;     __device__ __forceinline__ void after(int te, f32x4 (&acc)[2][2][4][2], const Unit& u, int wr, int wc, int fr, int fq) const {
;     ...
;                     for (int m = 0; m < 4; ++m) { float vs[8], va[8]; unpack8(gs[m], vs); unpack8(ga[m], va);
; #pragma unroll
;                         for (int e = 0; e < 4; ++e) {
;                             acc[ai][bj][m][0][e] *= (1.f + __expf(-(va[e] + a0[e]))) * __builtin_amdgcn_rcpf(1.f + __expf(-(vs[e] + s0[e])));
;                             acc[ai][bj][m][1][e] *= (1.f + __expf(-(va[4 + e] + a1[e]))) * __builtin_amdgcn_rcpf(1.f + __expf(-(vs[4 + e] + s1[e]))); } }
	v_lshlrev_b32_e32 v3, 16, v204
	v_and_b32_e32 v204, 0xffff0000, v204
	v_lshlrev_b32_e32 v225, 16, v205
	v_and_b32_e32 v227, 0xffff0000, v205
	v_lshlrev_b32_e32 v205, 16, v206
	v_and_b32_e32 v228, 0xffff0000, v206
	v_lshlrev_b32_e32 v229, 16, v207
	v_and_b32_e32 v233, 0xffff0000, v207
	v_add_f32_e32 v3, v142, v3
	v_add_f32_e32 v204, v143, v204
	v_mul_f32_e32 v3, 0xbfb8aa3b, v3
	v_mul_f32_e32 v204, 0xbfb8aa3b, v204
	v_exp_f32_e32 v3, v3
	v_lshlrev_b32_e32 v230, 16, v209
	v_and_b32_e32 v231, 0xffff0000, v209
	v_exp_f32_e32 v209, v204
	v_lshlrev_b32_e32 v206, 16, v208
	v_and_b32_e32 v207, 0xffff0000, v208
	v_lshlrev_b32_e32 v208, 16, v210
	v_add_f32_e32 v206, v146, v206
	v_add_f32_e32 v208, v130, v208
	v_mul_f32_e32 v206, 0xbfb8aa3b, v206
	v_mul_f32_e32 v208, 0xbfb8aa3b, v208
	v_add_f32_e32 v3, 1.0, v3
	v_exp_f32_e32 v204, v206
	v_exp_f32_e32 v206, v208
	v_rcp_f32_e32 v208, v3
	v_add_f32_e32 v3, 1.0, v209
	v_rcp_f32_e32 v209, v3
	v_add_f32_e32 v3, v127, v228
	v_mul_f32_e32 v3, 0xbfb8aa3b, v3
	v_exp_f32_e32 v3, v3
	v_lshlrev_b32_e32 v234, 16, v211
	v_and_b32_e32 v235, 0xffff0000, v211
	v_add_f32_e32 v205, v126, v205
	v_add_f32_e32 v3, 1.0, v3
	v_rcp_f32_e32 v211, v3
	v_add_f32_e32 v3, v144, v225
	v_mul_f32_e32 v3, 0xbfb8aa3b, v3
	v_exp_f32_e32 v3, v3
	v_mul_f32_e32 v205, 0xbfb8aa3b, v205
	v_exp_f32_e32 v205, v205
	v_add_f32_e32 v225, v148, v230
	v_add_f32_e32 v3, 1.0, v3
	v_rcp_f32_e32 v230, v3
	v_add_f32_e32 v3, v128, v229
	v_mul_f32_e32 v3, 0xbfb8aa3b, v3
	v_add_f32_e32 v227, v145, v227
	v_mul_f32_e32 v225, 0xbfb8aa3b, v225
	v_exp_f32_e32 v3, v3
	v_mul_f32_e32 v227, 0xbfb8aa3b, v227
	v_add_f32_e32 v207, v147, v207
	v_exp_f32_e32 v228, v225
	v_add_f32_e32 v225, v132, v234
	v_exp_f32_e32 v227, v227
	v_and_b32_e32 v232, 0xffff0000, v210
	v_mul_f32_e32 v207, 0xbfb8aa3b, v207
	v_add_f32_e32 v205, 1.0, v205
	v_mul_f32_e32 v225, 0xbfb8aa3b, v225
	v_rcp_f32_e32 v210, v205
	v_exp_f32_e32 v205, v207
	v_add_f32_e32 v207, v131, v232
	v_exp_f32_e32 v232, v225
	v_add_f32_e32 v225, v149, v231
	v_add_f32_e32 v3, 1.0, v3
	v_mul_f32_e32 v225, 0xbfb8aa3b, v225
	v_exp_f32_e32 v229, v225
	v_rcp_f32_e32 v234, v3
	v_add_f32_e32 v3, 1.0, v227
	v_rcp_f32_e32 v231, v3
	v_pk_add_f32 v[228:229], v[228:229], 1.0 op_sel_hi:[1,0]
	v_pk_add_f32 v[204:205], v[204:205], 1.0 op_sel_hi:[1,0]
	v_add_f32_e32 v3, v133, v235
	v_pk_mul_f32 v[204:205], v[204:205], v[208:209]
	v_pk_mul_f32 v[208:209], v[228:229], v[230:231]
	v_mul_f32_e32 v3, 0xbfb8aa3b, v3
	v_pk_mul_f32 v[140:141], v[140:141], v[208:209]
	v_add_f32_e32 v208, v129, v233
	v_mul_f32_e32 v208, 0xbfb8aa3b, v208
	v_exp_f32_e32 v208, v208
	v_exp_f32_e32 v233, v3
	v_mul_f32_e32 v207, 0xbfb8aa3b, v207
	v_exp_f32_e32 v207, v207
	v_add_f32_e32 v3, 1.0, v208
	v_rcp_f32_e32 v235, v3
	v_lshlrev_b32_e32 v3, 16, v212
	v_add_f32_e32 v3, v142, v3
	v_mul_f32_e32 v3, 0xbfb8aa3b, v3
	v_exp_f32_e32 v3, v3
	v_pk_add_f32 v[206:207], v[206:207], 1.0 op_sel_hi:[1,0]
	v_pk_mul_f32 v[138:139], v[138:139], v[204:205]
	v_pk_mul_f32 v[206:207], v[206:207], v[210:211]
	v_add_f32_e32 v3, 1.0, v3
	v_pk_mul_f32 v[134:135], v[134:135], v[206:207]
	v_lshlrev_b32_e32 v207, 16, v214
	v_rcp_f32_e32 v206, v3
	v_add_f32_e32 v3, v126, v207
	v_mul_f32_e32 v3, 0xbfb8aa3b, v3
	v_exp_f32_e32 v3, v3
	v_pk_add_f32 v[204:205], v[232:233], 1.0 op_sel_hi:[1,0]
	v_lshlrev_b32_e32 v208, 16, v218
	v_pk_mul_f32 v[204:205], v[204:205], v[234:235]
	v_add_f32_e32 v3, 1.0, v3
	v_pk_mul_f32 v[136:137], v[136:137], v[204:205]
	v_and_b32_e32 v205, 0xffff0000, v212
	v_rcp_f32_e32 v210, v3
	v_add_f32_e32 v3, v143, v205
	v_mul_f32_e32 v3, 0xbfb8aa3b, v3
	v_exp_f32_e32 v3, v3
	v_add_f32_e32 v207, v130, v208
	v_and_b32_e32 v209, 0xffff0000, v214
	v_mul_f32_e32 v207, 0xbfb8aa3b, v207
	v_add_f32_e32 v3, 1.0, v3
	v_exp_f32_e32 v208, v207
	v_rcp_f32_e32 v207, v3
	v_add_f32_e32 v3, v127, v209
	v_mul_f32_e32 v3, 0xbfb8aa3b, v3
	v_exp_f32_e32 v3, v3
	v_lshlrev_b32_e32 v212, 16, v213
	v_and_b32_e32 v211, 0xffff0000, v216
	v_add_f32_e32 v205, v147, v211
	v_add_f32_e32 v3, 1.0, v3
	v_rcp_f32_e32 v211, v3
	v_add_f32_e32 v3, v144, v212
	v_mul_f32_e32 v3, 0xbfb8aa3b, v3
	v_exp_f32_e32 v3, v3
	v_lshlrev_b32_e32 v225, 16, v215
	v_lshlrev_b32_e32 v214, 16, v217
	v_and_b32_e32 v213, 0xffff0000, v213
	v_add_f32_e32 v3, 1.0, v3
	v_add_f32_e32 v212, v148, v214
	v_rcp_f32_e32 v214, v3
	v_add_f32_e32 v3, v128, v225
	v_mul_f32_e32 v3, 0xbfb8aa3b, v3
	v_add_f32_e32 v213, v145, v213
	v_and_b32_e32 v227, 0xffff0000, v215
	v_lshlrev_b32_e32 v204, 16, v216
	v_and_b32_e32 v215, 0xffff0000, v217
	v_and_b32_e32 v216, 0xffff0000, v218
	v_lshlrev_b32_e32 v217, 16, v219
	v_exp_f32_e32 v3, v3
	v_mul_f32_e32 v213, 0xbfb8aa3b, v213
	v_add_f32_e32 v209, v131, v216
	v_add_f32_e32 v216, v132, v217
	v_exp_f32_e32 v217, v213
	v_add_f32_e32 v204, v146, v204
	v_add_f32_e32 v215, v149, v215
	v_mul_f32_e32 v204, 0xbfb8aa3b, v204
	v_mul_f32_e32 v205, 0xbfb8aa3b, v205
	v_mul_f32_e32 v212, 0xbfb8aa3b, v212
	v_add_f32_e32 v3, 1.0, v3
	v_mul_f32_e32 v213, 0xbfb8aa3b, v215
	v_exp_f32_e32 v204, v204
	v_exp_f32_e32 v205, v205
	v_exp_f32_e32 v212, v212
	v_exp_f32_e32 v213, v213
	v_rcp_f32_e32 v218, v3
	v_add_f32_e32 v3, 1.0, v217
	v_rcp_f32_e32 v215, v3
	v_pk_add_f32 v[212:213], v[212:213], 1.0 op_sel_hi:[1,0]
	v_pk_add_f32 v[204:205], v[204:205], 1.0 op_sel_hi:[1,0]
	v_and_b32_e32 v219, 0xffff0000, v219
	v_pk_mul_f32 v[204:205], v[204:205], v[206:207]
	v_pk_mul_f32 v[206:207], v[212:213], v[214:215]
	v_add_f32_e32 v3, v133, v219
	v_pk_mul_f32 v[124:125], v[124:125], v[206:207]
	v_add_f32_e32 v206, v129, v227
	v_mul_f32_e32 v206, 0xbfb8aa3b, v206
	v_exp_f32_e32 v206, v206
	v_mul_f32_e32 v3, 0xbfb8aa3b, v3
	v_exp_f32_e32 v217, v3
; __device__ __forceinline__ void unpack8(const u32x4 w, float (&v)[8]) { v[0] = bf_lo(w.x); v[1] = bf_hi(w.x); v[2] = bf_lo(w.y); v[3] = bf_hi(w.y); v[4] = bf_lo(w.z); v[5] = bf_hi(w.z); v[6] = bf_lo(w.w); v[7] = bf_hi(w.w); }
;     __device__ __forceinline__ void after(int te, f32x4 (&acc)[2][2][4][2], const Unit& u, int wr, int wc, int fr, int fq) const {
;     ...
;                     for (int m = 0; m < 4; ++m) { const size_t r = (size_t)(row0 + ai * HALF + m * 16); gs[m] = *(const u32x4*)(proj + r * LDP + PGS + c); ga[m] = *(const u32x4*)(proj + r * LDP + PGA + c); }
; #pragma unroll
;                     for (int m = 0; m < 4; ++m) { float vs[8], va[8]; unpack8(gs[m], vs); unpack8(ga[m], va);
; #pragma unroll
;                         for (int e = 0; e < 4; ++e) {
;                             acc[ai][bj][m][0][e] *= (1.f + __expf(-(va[e] + a0[e]))) * __builtin_amdgcn_rcpf(1.f + __expf(-(vs[e] + s0[e])));
;                             acc[ai][bj][m][1][e] *= (1.f + __expf(-(va[4 + e] + a1[e]))) * __builtin_amdgcn_rcpf(1.f + __expf(-(vs[4 + e] + s1[e]))); } }
	v_mul_f32_e32 v216, 0xbfb8aa3b, v216
	v_add_f32_e32 v3, 1.0, v206
	v_rcp_f32_e32 v219, v3
	v_lshlrev_b32_e32 v3, 16, v162
	v_mul_f32_e32 v209, 0xbfb8aa3b, v209
	v_exp_f32_e32 v216, v216
	v_add_f32_e32 v3, v142, v3
	v_exp_f32_e32 v209, v209
	v_mul_f32_e32 v3, 0xbfb8aa3b, v3
	v_exp_f32_e32 v3, v3
	v_pk_mul_f32 v[122:123], v[122:123], v[204:205]
	v_pk_add_f32 v[204:205], v[216:217], 1.0 op_sel_hi:[1,0]
	v_pk_add_f32 v[206:207], v[208:209], 1.0 op_sel_hi:[1,0]
	v_pk_mul_f32 v[204:205], v[204:205], v[218:219]
	v_pk_mul_f32 v[206:207], v[206:207], v[210:211]
	v_pk_mul_f32 v[120:121], v[120:121], v[204:205]
	v_and_b32_e32 v204, 0xffff0000, v162
	v_lshlrev_b32_e32 v162, 16, v164
	v_add_f32_e32 v3, 1.0, v3
	v_pk_mul_f32 v[118:119], v[118:119], v[206:207]
	v_lshlrev_b32_e32 v206, 16, v159
	v_and_b32_e32 v210, 0xffff0000, v159
	v_lshlrev_b32_e32 v159, 16, v160
	v_and_b32_e32 v211, 0xffff0000, v160
	v_rcp_f32_e32 v160, v3
	v_add_f32_e32 v3, v126, v162
	v_mul_f32_e32 v3, 0xbfb8aa3b, v3
	v_exp_f32_e32 v3, v3
	v_lshlrev_b32_e32 v205, 16, v163
	v_and_b32_e32 v207, 0xffff0000, v163
	v_and_b32_e32 v163, 0xffff0000, v164
	v_lshlrev_b32_e32 v164, 16, v158
	v_add_f32_e32 v3, 1.0, v3
	v_lshlrev_b32_e32 v208, 16, v165
	v_and_b32_e32 v209, 0xffff0000, v165
	v_and_b32_e32 v165, 0xffff0000, v158
	v_add_f32_e32 v158, v146, v164
	v_rcp_f32_e32 v164, v3
	v_add_f32_e32 v3, v143, v204
	v_mul_f32_e32 v3, 0xbfb8aa3b, v3
	v_exp_f32_e32 v3, v3
	v_lshlrev_b32_e32 v212, 16, v161
	v_and_b32_e32 v213, 0xffff0000, v161
	v_add_f32_e32 v159, v130, v159
	v_add_f32_e32 v3, 1.0, v3
	v_rcp_f32_e32 v161, v3
	v_add_f32_e32 v3, v127, v163
	v_mul_f32_e32 v3, 0xbfb8aa3b, v3
	v_exp_f32_e32 v3, v3
	v_mul_f32_e32 v159, 0xbfb8aa3b, v159
	v_exp_f32_e32 v162, v159
	v_add_f32_e32 v159, v147, v165
	v_add_f32_e32 v3, 1.0, v3
	v_rcp_f32_e32 v165, v3
	v_add_f32_e32 v3, v144, v205
	v_mul_f32_e32 v3, 0xbfb8aa3b, v3
	v_exp_f32_e32 v3, v3
	v_add_f32_e32 v204, v148, v206
	v_add_f32_e32 v207, v145, v207
	v_mul_f32_e32 v207, 0xbfb8aa3b, v207
	v_add_f32_e32 v3, 1.0, v3
	v_rcp_f32_e32 v206, v3
	v_add_f32_e32 v3, v128, v208
	v_mul_f32_e32 v3, 0xbfb8aa3b, v3
	v_exp_f32_e32 v3, v3
	v_add_f32_e32 v205, v132, v212
	v_exp_f32_e32 v207, v207
	v_mul_f32_e32 v205, 0xbfb8aa3b, v205
	v_exp_f32_e32 v208, v205
	v_add_f32_e32 v205, v149, v210
	v_mul_f32_e32 v158, 0xbfb8aa3b, v158
	v_mul_f32_e32 v159, 0xbfb8aa3b, v159
	v_mul_f32_e32 v204, 0xbfb8aa3b, v204
	v_add_f32_e32 v3, 1.0, v3
	v_mul_f32_e32 v205, 0xbfb8aa3b, v205
	v_exp_f32_e32 v158, v158
	v_exp_f32_e32 v159, v159
	v_exp_f32_e32 v204, v204
	v_exp_f32_e32 v205, v205
	v_rcp_f32_e32 v210, v3
	v_add_f32_e32 v3, 1.0, v207
	v_rcp_f32_e32 v207, v3
	v_pk_add_f32 v[204:205], v[204:205], 1.0 op_sel_hi:[1,0]
	v_pk_add_f32 v[158:159], v[158:159], 1.0 op_sel_hi:[1,0]
	v_add_f32_e32 v3, v133, v213
	v_pk_mul_f32 v[158:159], v[158:159], v[160:161]
	v_pk_mul_f32 v[160:161], v[204:205], v[206:207]
	v_mul_f32_e32 v3, 0xbfb8aa3b, v3
	v_pk_mul_f32 v[116:117], v[116:117], v[160:161]
	v_add_f32_e32 v160, v129, v209
	v_mul_f32_e32 v160, 0xbfb8aa3b, v160
	v_exp_f32_e32 v160, v160
	v_exp_f32_e32 v209, v3
	v_add_f32_e32 v163, v131, v211
	v_mul_f32_e32 v163, 0xbfb8aa3b, v163
	v_add_f32_e32 v3, 1.0, v160
	v_rcp_f32_e32 v211, v3
	v_lshlrev_b32_e32 v3, 16, v154
	v_add_f32_e32 v3, v142, v3
	v_exp_f32_e32 v163, v163
	v_mul_f32_e32 v3, 0xbfb8aa3b, v3
	v_exp_f32_e32 v3, v3
	v_pk_mul_f32 v[114:115], v[114:115], v[158:159]
	v_pk_add_f32 v[158:159], v[208:209], 1.0 op_sel_hi:[1,0]
	v_pk_add_f32 v[160:161], v[162:163], 1.0 op_sel_hi:[1,0]
	v_pk_mul_f32 v[158:159], v[158:159], v[210:211]
	v_pk_mul_f32 v[160:161], v[160:161], v[164:165]
	v_pk_mul_f32 v[112:113], v[112:113], v[158:159]
	v_and_b32_e32 v158, 0xffff0000, v154
	v_lshlrev_b32_e32 v154, 16, v156
	v_add_f32_e32 v3, 1.0, v3
	v_pk_mul_f32 v[110:111], v[110:111], v[160:161]
	v_lshlrev_b32_e32 v160, 16, v151
	v_and_b32_e32 v204, 0xffff0000, v151
	v_lshlrev_b32_e32 v151, 16, v152
	v_and_b32_e32 v162, 0xffff0000, v152
	v_rcp_f32_e32 v152, v3
	v_add_f32_e32 v3, v126, v154
	v_mul_f32_e32 v3, 0xbfb8aa3b, v3
	v_exp_f32_e32 v3, v3
	v_lshlrev_b32_e32 v159, 16, v155
	v_and_b32_e32 v161, 0xffff0000, v155
	v_and_b32_e32 v155, 0xffff0000, v156
	v_lshlrev_b32_e32 v156, 16, v150
	v_add_f32_e32 v3, 1.0, v3
	v_lshlrev_b32_e32 v164, 16, v157
	v_and_b32_e32 v165, 0xffff0000, v157
	v_and_b32_e32 v157, 0xffff0000, v150
	v_add_f32_e32 v150, v146, v156
	v_rcp_f32_e32 v156, v3
	v_add_f32_e32 v3, v143, v158
	v_mul_f32_e32 v3, 0xbfb8aa3b, v3
	v_exp_f32_e32 v3, v3
	v_lshlrev_b32_e32 v205, 16, v153
	v_and_b32_e32 v206, 0xffff0000, v153
	v_add_f32_e32 v151, v130, v151
	v_add_f32_e32 v3, 1.0, v3
	v_rcp_f32_e32 v153, v3
	v_add_f32_e32 v3, v127, v155
	v_add_f32_e32 v155, v131, v162
	v_add_co_u32_e32 v162, vcc, s26, v192
	v_mul_f32_e32 v3, 0xbfb8aa3b, v3
	s_nop 0
	v_addc_co_u32_e32 v163, vcc, 0, v193, vcc
	global_load_dwordx4 v[228:231], v[162:163], off
	v_exp_f32_e32 v3, v3
	v_mul_f32_e32 v151, 0xbfb8aa3b, v151
	s_mov_b32 s26, 0x202000
	v_exp_f32_e32 v154, v151
	v_add_f32_e32 v3, 1.0, v3
	v_add_f32_e32 v151, v147, v157
	v_rcp_f32_e32 v157, v3
	v_add_f32_e32 v3, v144, v159
	v_add_co_u32_e32 v162, vcc, s26, v192
	v_mul_f32_e32 v3, 0xbfb8aa3b, v3
	s_nop 0
	v_addc_co_u32_e32 v163, vcc, 0, v193, vcc
	v_exp_f32_e32 v3, v3
	global_load_dwordx4 v[232:235], v[162:163], off
	v_add_f32_e32 v158, v148, v160
	v_add_f32_e32 v161, v145, v161
	v_add_f32_e32 v3, 1.0, v3
	v_rcp_f32_e32 v160, v3
	v_add_f32_e32 v3, v128, v164
	v_mul_f32_e32 v3, 0xbfb8aa3b, v3
	v_exp_f32_e32 v3, v3
	v_mul_f32_e32 v161, 0xbfb8aa3b, v161
	v_add_f32_e32 v159, v132, v205
	v_exp_f32_e32 v161, v161
	v_mul_f32_e32 v159, 0xbfb8aa3b, v159
; __device__ __forceinline__ void unpack8(const u32x4 w, float (&v)[8]) { v[0] = bf_lo(w.x); v[1] = bf_hi(w.x); v[2] = bf_lo(w.y); v[3] = bf_hi(w.y); v[4] = bf_lo(w.z); v[5] = bf_hi(w.z); v[6] = bf_lo(w.w); v[7] = bf_hi(w.w); }
;     __device__ __forceinline__ void after(int te, f32x4 (&acc)[2][2][4][2], const Unit& u, int wr, int wc, int fr, int fq) const {
;     ...
;                     for (int m = 0; m < 4; ++m) { const size_t r = (size_t)(row0 + ai * HALF + m * 16); gs[m] = *(const u32x4*)(proj + r * LDP + PGS + c); ga[m] = *(const u32x4*)(proj + r * LDP + PGA + c); }
; #pragma unroll
;                     for (int m = 0; m < 4; ++m) { float vs[8], va[8]; unpack8(gs[m], vs); unpack8(ga[m], va);
; #pragma unroll
;                         for (int e = 0; e < 4; ++e) {
;                             acc[ai][bj][m][0][e] *= (1.f + __expf(-(va[e] + a0[e]))) * __builtin_amdgcn_rcpf(1.f + __expf(-(vs[e] + s0[e])));
;                             acc[ai][bj][m][1][e] *= (1.f + __expf(-(va[4 + e] + a1[e]))) * __builtin_amdgcn_rcpf(1.f + __expf(-(vs[4 + e] + s1[e]))); } }
	v_exp_f32_e32 v162, v159
	v_add_f32_e32 v159, v149, v204
	v_mul_f32_e32 v150, 0xbfb8aa3b, v150
	v_mul_f32_e32 v151, 0xbfb8aa3b, v151
	v_mul_f32_e32 v158, 0xbfb8aa3b, v158
	v_add_f32_e32 v3, 1.0, v3
	v_mul_f32_e32 v159, 0xbfb8aa3b, v159
	v_exp_f32_e32 v150, v150
	v_exp_f32_e32 v151, v151
	v_exp_f32_e32 v158, v158
	v_exp_f32_e32 v159, v159
	v_rcp_f32_e32 v164, v3
	v_add_f32_e32 v3, 1.0, v161
	v_rcp_f32_e32 v161, v3
	v_pk_add_f32 v[158:159], v[158:159], 1.0 op_sel_hi:[1,0]
	v_pk_add_f32 v[150:151], v[150:151], 1.0 op_sel_hi:[1,0]
	v_add_f32_e32 v3, v133, v206
	v_pk_mul_f32 v[150:151], v[150:151], v[152:153]
	v_pk_mul_f32 v[152:153], v[158:159], v[160:161]
	v_mul_f32_e32 v3, 0xbfb8aa3b, v3
	v_pk_mul_f32 v[108:109], v[108:109], v[152:153]
	v_add_f32_e32 v152, v129, v165
	v_mul_f32_e32 v152, 0xbfb8aa3b, v152
	v_exp_f32_e32 v152, v152
	v_exp_f32_e32 v163, v3
	v_mul_f32_e32 v155, 0xbfb8aa3b, v155
	v_exp_f32_e32 v155, v155
	v_add_f32_e32 v3, 1.0, v152
	v_rcp_f32_e32 v165, v3
	s_mov_b64 s[26:27], 0x200000
	v_lshl_add_u64 v[218:219], v[192:193], 0, s[26:27]
	s_mov_b64 s[26:27], 0x202000
	v_pk_mul_f32 v[106:107], v[106:107], v[150:151]
	v_pk_add_f32 v[150:151], v[162:163], 1.0 op_sel_hi:[1,0]
	v_lshl_add_u64 v[216:217], v[192:193], 0, s[26:27]
	s_mov_b64 s[26:27], 0x240000
	v_pk_mul_f32 v[150:151], v[150:151], v[164:165]
	v_lshl_add_u64 v[204:205], v[192:193], 0, s[26:27]
	s_mov_b32 s26, 0x240000
	v_pk_add_f32 v[152:153], v[154:155], 1.0 op_sel_hi:[1,0]
	v_pk_mul_f32 v[104:105], v[104:105], v[150:151]
	v_add_co_u32_e32 v150, vcc, s26, v192
	s_mov_b64 s[26:27], 0x242000
	v_pk_mul_f32 v[152:153], v[152:153], v[156:157]
	v_addc_co_u32_e32 v151, vcc, 0, v193, vcc
	v_lshl_add_u64 v[206:207], v[192:193], 0, s[26:27]
	s_mov_b32 s26, 0x242000
	v_pk_mul_f32 v[102:103], v[102:103], v[152:153]
	v_add_co_u32_e32 v152, vcc, s26, v192
	s_mov_b64 s[26:27], 0x280000
	s_nop 0
	v_addc_co_u32_e32 v153, vcc, 0, v193, vcc
	global_load_dwordx4 v[236:239], v[150:151], off
	global_load_dwordx4 v[240:243], v[152:153], off
	s_waitcnt vmcnt(3)
	v_lshlrev_b32_e32 v3, 16, v228
	v_add_f32_e32 v3, v142, v3
	v_mul_f32_e32 v3, 0xbfb8aa3b, v3
	v_exp_f32_e32 v3, v3
	v_lshlrev_b32_e32 v227, 16, v229
	v_and_b32_e32 v245, 0xffff0000, v229
	v_lshlrev_b32_e32 v229, 16, v230
	v_add_f32_e32 v3, 1.0, v3
	v_and_b32_e32 v246, 0xffff0000, v230
	v_rcp_f32_e32 v230, v3
	v_add_f32_e32 v3, v126, v229
	v_mul_f32_e32 v3, 0xbfb8aa3b, v3
	v_exp_f32_e32 v3, v3
	v_lshl_add_u64 v[208:209], v[192:193], 0, s[26:27]
	s_mov_b32 s26, 0x280000
	v_add_co_u32_e32 v150, vcc, s26, v192
	s_mov_b64 s[26:27], 0x282000
	s_nop 0
	v_addc_co_u32_e32 v151, vcc, 0, v193, vcc
	v_lshl_add_u64 v[210:211], v[192:193], 0, s[26:27]
	s_mov_b32 s26, 0x282000
	v_add_co_u32_e32 v152, vcc, s26, v192
	v_and_b32_e32 v225, 0xffff0000, v228
	v_add_f32_e32 v3, 1.0, v3
	v_addc_co_u32_e32 v153, vcc, 0, v193, vcc
	global_load_dwordx4 v[162:165], v[150:151], off
	global_load_dwordx4 v[158:161], v[152:153], off
	v_lshlrev_b32_e32 v247, 16, v231
	v_and_b32_e32 v251, 0xffff0000, v231
	s_waitcnt vmcnt(4)
	v_lshlrev_b32_e32 v228, 16, v232
	v_and_b32_e32 v231, 0xffff0000, v232
	v_lshlrev_b32_e32 v248, 16, v233
	v_and_b32_e32 v249, 0xffff0000, v233
	v_lshlrev_b32_e32 v232, 16, v234
	v_and_b32_e32 v233, 0xffff0000, v234
	v_rcp_f32_e32 v234, v3
	v_add_f32_e32 v3, v143, v225
	v_mul_f32_e32 v3, 0xbfb8aa3b, v3
	v_exp_f32_e32 v3, v3
	v_add_f32_e32 v225, v147, v231
	v_lshlrev_b32_e32 v250, 16, v235
	v_and_b32_e32 v253, 0xffff0000, v235
	v_add_f32_e32 v3, 1.0, v3
	v_rcp_f32_e32 v231, v3
	v_add_f32_e32 v3, v127, v246
	v_mul_f32_e32 v3, 0xbfb8aa3b, v3
	v_exp_f32_e32 v3, v3
	v_add_f32_e32 v229, v130, v232
	v_mul_f32_e32 v229, 0xbfb8aa3b, v229
	v_mul_f32_e32 v225, 0xbfb8aa3b, v225
	v_add_f32_e32 v3, 1.0, v3
	v_rcp_f32_e32 v235, v3
	v_add_f32_e32 v3, v144, v227
	v_mul_f32_e32 v3, 0xbfb8aa3b, v3
	v_exp_f32_e32 v3, v3
	v_exp_f32_e32 v232, v229
	v_exp_f32_e32 v229, v225
	v_add_f32_e32 v225, v131, v233
	v_mul_f32_e32 v225, 0xbfb8aa3b, v225
	v_exp_f32_e32 v233, v225
	v_add_f32_e32 v225, v148, v248
	v_mul_f32_e32 v225, 0xbfb8aa3b, v225
	v_add_f32_e32 v3, 1.0, v3
	v_exp_f32_e32 v246, v225
	v_rcp_f32_e32 v248, v3
	v_add_f32_e32 v3, v128, v247
	v_add_f32_e32 v225, v132, v250
	v_mul_f32_e32 v3, 0xbfb8aa3b, v3
	v_mul_f32_e32 v225, 0xbfb8aa3b, v225
	v_add_f32_e32 v227, v145, v245
	v_exp_f32_e32 v3, v3
	v_exp_f32_e32 v250, v225
	v_add_f32_e32 v225, v149, v249
	v_mul_f32_e32 v227, 0xbfb8aa3b, v227
	v_exp_f32_e32 v227, v227
	v_mul_f32_e32 v225, 0xbfb8aa3b, v225
	v_exp_f32_e32 v247, v225
	v_add_f32_e32 v225, v129, v251
	v_mul_f32_e32 v225, 0xbfb8aa3b, v225
	v_add_f32_e32 v3, 1.0, v3
	v_exp_f32_e32 v225, v225
	v_rcp_f32_e32 v252, v3
	v_add_f32_e32 v3, 1.0, v227
	v_add_f32_e32 v228, v146, v228
	v_rcp_f32_e32 v249, v3
	v_add_f32_e32 v3, v133, v253
	v_mul_f32_e32 v228, 0xbfb8aa3b, v228
	v_mul_f32_e32 v3, 0xbfb8aa3b, v3
	v_exp_f32_e32 v228, v228
	v_exp_f32_e32 v251, v3
	v_add_f32_e32 v3, 1.0, v225
	v_rcp_f32_e32 v253, v3
	s_waitcnt vmcnt(3)
; __device__ __forceinline__ void unpack8(const u32x4 w, float (&v)[8]) { v[0] = bf_lo(w.x); v[1] = bf_hi(w.x); v[2] = bf_lo(w.y); v[3] = bf_hi(w.y); v[4] = bf_lo(w.z); v[5] = bf_hi(w.z); v[6] = bf_lo(w.w); v[7] = bf_hi(w.w); }
;     __device__ __forceinline__ void after(int te, f32x4 (&acc)[2][2][4][2], const Unit& u, int wr, int wc, int fr, int fq) const {
;     ...
;                     for (int m = 0; m < 4; ++m) { float vs[8], va[8]; unpack8(gs[m], vs); unpack8(ga[m], va);
; #pragma unroll
;                         for (int e = 0; e < 4; ++e) {
;                             acc[ai][bj][m][0][e] *= (1.f + __expf(-(va[e] + a0[e]))) * __builtin_amdgcn_rcpf(1.f + __expf(-(vs[e] + s0[e])));
;                             acc[ai][bj][m][1][e] *= (1.f + __expf(-(va[4 + e] + a1[e]))) * __builtin_amdgcn_rcpf(1.f + __expf(-(vs[4 + e] + s1[e]))); } }
	v_lshlrev_b32_e32 v3, 16, v236
	v_add_f32_e32 v3, v142, v3
	v_mul_f32_e32 v3, 0xbfb8aa3b, v3
	v_pk_add_f32 v[228:229], v[228:229], 1.0 op_sel_hi:[1,0]
	v_exp_f32_e32 v3, v3
	v_pk_add_f32 v[246:247], v[246:247], 1.0 op_sel_hi:[1,0]
	v_pk_mul_f32 v[228:229], v[228:229], v[230:231]
	v_pk_mul_f32 v[230:231], v[246:247], v[248:249]
	v_pk_mul_f32 v[98:99], v[98:99], v[228:229]
	v_pk_add_f32 v[228:229], v[250:251], 1.0 op_sel_hi:[1,0]
	v_pk_mul_f32 v[100:101], v[100:101], v[230:231]
	v_pk_add_f32 v[230:231], v[232:233], 1.0 op_sel_hi:[1,0]
	v_pk_mul_f32 v[228:229], v[228:229], v[252:253]
	v_pk_mul_f32 v[230:231], v[230:231], v[234:235]
	v_pk_mul_f32 v[96:97], v[96:97], v[228:229]
	v_lshlrev_b32_e32 v229, 16, v238
	v_add_f32_e32 v3, 1.0, v3
	v_pk_mul_f32 v[94:95], v[94:95], v[230:231]
	v_rcp_f32_e32 v230, v3
	v_add_f32_e32 v3, v126, v229
	v_mul_f32_e32 v3, 0xbfb8aa3b, v3
	v_exp_f32_e32 v3, v3
	v_and_b32_e32 v225, 0xffff0000, v236
	s_mov_b64 s[26:27], 0x2c0000
	v_lshl_add_u64 v[212:213], v[192:193], 0, s[26:27]
	v_add_f32_e32 v3, 1.0, v3
	v_rcp_f32_e32 v234, v3
	v_add_f32_e32 v3, v143, v225
	v_mul_f32_e32 v3, 0xbfb8aa3b, v3
	v_exp_f32_e32 v3, v3
	s_mov_b32 s26, 0x2c0000
	v_add_co_u32_e32 v150, vcc, s26, v192
	s_mov_b64 s[26:27], 0x2c2000
	s_nop 0
	v_addc_co_u32_e32 v151, vcc, 0, v193, vcc
	v_lshl_add_u64 v[214:215], v[192:193], 0, s[26:27]
	s_mov_b32 s26, 0x2c2000
	v_and_b32_e32 v233, 0xffff0000, v238
	s_waitcnt vmcnt(2)
	v_and_b32_e32 v231, 0xffff0000, v240
	v_add_f32_e32 v3, 1.0, v3
	v_add_co_u32_e32 v152, vcc, s26, v192
	v_add_f32_e32 v225, v147, v231
	v_rcp_f32_e32 v231, v3
	v_add_f32_e32 v3, v127, v233
	v_addc_co_u32_e32 v153, vcc, 0, v193, vcc
	v_mul_f32_e32 v3, 0xbfb8aa3b, v3
	global_load_dwordx4 v[154:157], v[150:151], off
	s_nop 0
	global_load_dwordx4 v[150:153], v[152:153], off
	v_exp_f32_e32 v3, v3
	v_lshlrev_b32_e32 v232, 16, v242
	v_add_f32_e32 v229, v130, v232
	v_lshlrev_b32_e32 v227, 16, v237
	v_and_b32_e32 v235, 0xffff0000, v242
	v_mul_f32_e32 v229, 0xbfb8aa3b, v229
	v_mul_f32_e32 v225, 0xbfb8aa3b, v225
	v_add_f32_e32 v3, 1.0, v3
	v_exp_f32_e32 v232, v229
	v_exp_f32_e32 v229, v225
	v_add_f32_e32 v225, v131, v235
	v_rcp_f32_e32 v235, v3
	v_add_f32_e32 v3, v144, v227
	v_mul_f32_e32 v3, 0xbfb8aa3b, v3
	v_exp_f32_e32 v3, v3
	v_lshlrev_b32_e32 v236, 16, v241
	v_mul_f32_e32 v225, 0xbfb8aa3b, v225
	v_exp_f32_e32 v233, v225
	v_add_f32_e32 v225, v148, v236
	v_lshlrev_b32_e32 v245, 16, v239
	v_lshlrev_b32_e32 v228, 16, v240
	v_lshlrev_b32_e32 v240, 16, v243
	v_mul_f32_e32 v225, 0xbfb8aa3b, v225
	v_add_f32_e32 v3, 1.0, v3
	v_and_b32_e32 v237, 0xffff0000, v237
	v_exp_f32_e32 v236, v225
	v_rcp_f32_e32 v238, v3
	v_add_f32_e32 v3, v128, v245
	v_add_f32_e32 v225, v132, v240
	v_and_b32_e32 v246, 0xffff0000, v239
	v_and_b32_e32 v239, 0xffff0000, v241
	v_mul_f32_e32 v3, 0xbfb8aa3b, v3
	v_mul_f32_e32 v225, 0xbfb8aa3b, v225
	v_add_f32_e32 v227, v145, v237
	v_exp_f32_e32 v3, v3
	v_exp_f32_e32 v240, v225
	v_add_f32_e32 v225, v149, v239
	v_mul_f32_e32 v227, 0xbfb8aa3b, v227
	v_exp_f32_e32 v227, v227
	v_mul_f32_e32 v225, 0xbfb8aa3b, v225
	v_exp_f32_e32 v237, v225
	v_add_f32_e32 v225, v129, v246
	v_mul_f32_e32 v225, 0xbfb8aa3b, v225
	v_add_f32_e32 v3, 1.0, v3
	v_exp_f32_e32 v225, v225
	v_and_b32_e32 v241, 0xffff0000, v243
	v_rcp_f32_e32 v242, v3
	v_add_f32_e32 v3, 1.0, v227
	v_rcp_f32_e32 v239, v3
	v_add_f32_e32 v3, v133, v241
	v_add_f32_e32 v228, v146, v228
	v_mul_f32_e32 v3, 0xbfb8aa3b, v3
	v_mul_f32_e32 v228, 0xbfb8aa3b, v228
	v_exp_f32_e32 v241, v3
	v_add_f32_e32 v3, 1.0, v225
	v_exp_f32_e32 v228, v228
	v_rcp_f32_e32 v243, v3
	s_waitcnt vmcnt(3)
	v_lshlrev_b32_e32 v3, 16, v162
	v_add_f32_e32 v3, v142, v3
	v_mul_f32_e32 v3, 0xbfb8aa3b, v3
	v_exp_f32_e32 v3, v3
	v_pk_add_f32 v[236:237], v[236:237], 1.0 op_sel_hi:[1,0]
	v_pk_add_f32 v[228:229], v[228:229], 1.0 op_sel_hi:[1,0]
	v_and_b32_e32 v225, 0xffff0000, v162
	v_pk_mul_f32 v[228:229], v[228:229], v[230:231]
	v_pk_mul_f32 v[230:231], v[236:237], v[238:239]
	v_pk_mul_f32 v[90:91], v[90:91], v[228:229]
	v_pk_mul_f32 v[92:93], v[92:93], v[230:231]
	v_pk_add_f32 v[228:229], v[240:241], 1.0 op_sel_hi:[1,0]
	v_pk_add_f32 v[230:231], v[232:233], 1.0 op_sel_hi:[1,0]
	v_pk_mul_f32 v[228:229], v[228:229], v[242:243]
	v_pk_mul_f32 v[230:231], v[230:231], v[234:235]
	v_lshlrev_b32_e32 v162, 16, v164
	v_add_f32_e32 v3, 1.0, v3
	v_pk_mul_f32 v[88:89], v[88:89], v[228:229]
	v_pk_mul_f32 v[86:87], v[86:87], v[230:231]
	s_waitcnt vmcnt(2)
; __device__ __forceinline__ void unpack8(const u32x4 w, float (&v)[8]) { v[0] = bf_lo(w.x); v[1] = bf_hi(w.x); v[2] = bf_lo(w.y); v[3] = bf_hi(w.y); v[4] = bf_lo(w.z); v[5] = bf_hi(w.z); v[6] = bf_lo(w.w); v[7] = bf_hi(w.w); }
;     __device__ __forceinline__ void after(int te, f32x4 (&acc)[2][2][4][2], const Unit& u, int wr, int wc, int fr, int fq) const {
;     ...
;                     for (int m = 0; m < 4; ++m) { const size_t r = (size_t)(row0 + ai * HALF + m * 16); gs[m] = *(const u32x4*)(proj + r * LDP + PGS + c); ga[m] = *(const u32x4*)(proj + r * LDP + PGA + c); }
; #pragma unroll
;                     for (int m = 0; m < 4; ++m) { float vs[8], va[8]; unpack8(gs[m], vs); unpack8(ga[m], va);
; #pragma unroll
;                         for (int e = 0; e < 4; ++e) {
;                             acc[ai][bj][m][0][e] *= (1.f + __expf(-(va[e] + a0[e]))) * __builtin_amdgcn_rcpf(1.f + __expf(-(vs[e] + s0[e])));
;                             acc[ai][bj][m][1][e] *= (1.f + __expf(-(va[4 + e] + a1[e]))) * __builtin_amdgcn_rcpf(1.f + __expf(-(vs[4 + e] + s1[e]))); } }
	v_lshlrev_b32_e32 v228, 16, v159
	v_and_b32_e32 v234, 0xffff0000, v159
	v_lshlrev_b32_e32 v159, 16, v160
	v_and_b32_e32 v230, 0xffff0000, v160
	v_rcp_f32_e32 v160, v3
	v_add_f32_e32 v3, v126, v162
	v_mul_f32_e32 v3, 0xbfb8aa3b, v3
	v_exp_f32_e32 v3, v3
	v_lshlrev_b32_e32 v227, 16, v163
	v_and_b32_e32 v229, 0xffff0000, v163
	v_and_b32_e32 v163, 0xffff0000, v164
	v_lshlrev_b32_e32 v164, 16, v158
	v_add_f32_e32 v3, 1.0, v3
	v_lshlrev_b32_e32 v231, 16, v165
	v_and_b32_e32 v233, 0xffff0000, v165
	v_and_b32_e32 v165, 0xffff0000, v158
	v_add_f32_e32 v158, v146, v164
	v_rcp_f32_e32 v164, v3
	v_add_f32_e32 v3, v143, v225
	v_mul_f32_e32 v3, 0xbfb8aa3b, v3
	v_exp_f32_e32 v3, v3
	v_lshlrev_b32_e32 v232, 16, v161
	v_and_b32_e32 v235, 0xffff0000, v161
	v_add_f32_e32 v159, v130, v159
	v_add_f32_e32 v3, 1.0, v3
	v_rcp_f32_e32 v161, v3
	v_add_f32_e32 v3, v127, v163
	v_mul_f32_e32 v3, 0xbfb8aa3b, v3
	v_exp_f32_e32 v3, v3
	v_mul_f32_e32 v159, 0xbfb8aa3b, v159
	v_exp_f32_e32 v162, v159
	v_add_f32_e32 v159, v147, v165
	v_add_f32_e32 v3, 1.0, v3
	v_rcp_f32_e32 v165, v3
	v_add_f32_e32 v3, v144, v227
	v_mul_f32_e32 v3, 0xbfb8aa3b, v3
	v_exp_f32_e32 v3, v3
	v_add_f32_e32 v163, v131, v230
	v_add_f32_e32 v225, v148, v228
	v_add_f32_e32 v227, v145, v229
	v_add_f32_e32 v3, 1.0, v3
	v_rcp_f32_e32 v230, v3
	v_add_f32_e32 v3, v128, v231
	v_mul_f32_e32 v3, 0xbfb8aa3b, v3
	v_mul_f32_e32 v225, 0xbfb8aa3b, v225
	v_exp_f32_e32 v3, v3
	v_mul_f32_e32 v227, 0xbfb8aa3b, v227
	v_exp_f32_e32 v228, v225
	v_add_f32_e32 v225, v132, v232
	v_exp_f32_e32 v227, v227
	v_mul_f32_e32 v225, 0xbfb8aa3b, v225
	v_exp_f32_e32 v232, v225
	v_add_f32_e32 v225, v149, v234
	v_mul_f32_e32 v158, 0xbfb8aa3b, v158
	v_mul_f32_e32 v159, 0xbfb8aa3b, v159
	v_add_f32_e32 v3, 1.0, v3
	v_mul_f32_e32 v225, 0xbfb8aa3b, v225
	v_exp_f32_e32 v158, v158
	v_exp_f32_e32 v159, v159
	v_exp_f32_e32 v229, v225
	v_rcp_f32_e32 v234, v3
	v_add_f32_e32 v3, 1.0, v227
	v_rcp_f32_e32 v231, v3
	v_pk_add_f32 v[228:229], v[228:229], 1.0 op_sel_hi:[1,0]
	v_pk_add_f32 v[158:159], v[158:159], 1.0 op_sel_hi:[1,0]
	v_add_f32_e32 v3, v133, v235
	v_pk_mul_f32 v[158:159], v[158:159], v[160:161]
	v_pk_mul_f32 v[160:161], v[228:229], v[230:231]
	v_mul_f32_e32 v3, 0xbfb8aa3b, v3
	v_pk_mul_f32 v[84:85], v[84:85], v[160:161]
	v_add_f32_e32 v160, v129, v233
	v_mul_f32_e32 v160, 0xbfb8aa3b, v160
	v_exp_f32_e32 v160, v160
	v_exp_f32_e32 v233, v3
	s_waitcnt vmcnt(1)
	v_lshlrev_b32_e32 v225, 16, v155
	v_and_b32_e32 v227, 0xffff0000, v155
	v_add_f32_e32 v3, 1.0, v160
	v_rcp_f32_e32 v235, v3
	v_lshlrev_b32_e32 v3, 16, v154
	v_add_f32_e32 v3, v142, v3
	v_mul_f32_e32 v3, 0xbfb8aa3b, v3
	v_exp_f32_e32 v3, v3
	v_lshlrev_b32_e32 v155, 16, v156
	v_and_b32_e32 v236, 0xffff0000, v156
	s_waitcnt vmcnt(0)
	v_lshlrev_b32_e32 v156, 16, v150
	v_add_f32_e32 v3, 1.0, v3
	v_mul_f32_e32 v163, 0xbfb8aa3b, v163
	v_add_f32_e32 v142, v146, v156
	v_rcp_f32_e32 v146, v3
	v_add_f32_e32 v3, v126, v155
	v_exp_f32_e32 v163, v163
	v_mul_f32_e32 v3, 0xbfb8aa3b, v3
	v_exp_f32_e32 v3, v3
	v_pk_mul_f32 v[82:83], v[82:83], v[158:159]
	v_pk_add_f32 v[158:159], v[232:233], 1.0 op_sel_hi:[1,0]
	v_pk_add_f32 v[160:161], v[162:163], 1.0 op_sel_hi:[1,0]
	v_pk_mul_f32 v[158:159], v[158:159], v[234:235]
	v_pk_mul_f32 v[160:161], v[160:161], v[164:165]
	v_and_b32_e32 v150, 0xffff0000, v150
	v_lshlrev_b32_e32 v239, 16, v151
	v_and_b32_e32 v240, 0xffff0000, v151
	v_lshlrev_b32_e32 v151, 16, v152
	global_load_dwordx4 v[228:231], v[192:193], off offset:256
	global_load_dwordx4 v[232:235], v[202:203], off offset:256
	v_add_f32_e32 v3, 1.0, v3
	v_pk_mul_f32 v[80:81], v[80:81], v[158:159]
	v_pk_mul_f32 v[78:79], v[78:79], v[160:161]
	v_and_b32_e32 v241, 0xffff0000, v152
	v_lshlrev_b32_e32 v242, 16, v153
	v_and_b32_e32 v243, 0xffff0000, v153
	v_add_f32_e32 v126, v130, v151
	v_rcp_f32_e32 v130, v3
	v_add_f32_e32 v3, v147, v150
	global_load_dwordx4 v[150:153], v[196:197], off offset:528
	global_load_dwordx4 v[158:161], v[196:197], off offset:512
	v_and_b32_e32 v154, 0xffff0000, v154
	v_lshlrev_b32_e32 v237, 16, v157
	v_and_b32_e32 v238, 0xffff0000, v157
	v_add_f32_e32 v143, v143, v154
	global_load_dwordx4 v[154:157], v[198:199], off offset:528
	global_load_dwordx4 v[162:165], v[198:199], off offset:512
	v_mul_f32_e32 v143, 0xbfb8aa3b, v143
	v_exp_f32_e32 v147, v143
	v_mul_f32_e32 v3, 0xbfb8aa3b, v3
	v_exp_f32_e32 v143, v3
	v_add_f32_e32 v145, v145, v227
	v_add_f32_e32 v3, 1.0, v147
	v_rcp_f32_e32 v147, v3
	v_add_f32_e32 v3, v127, v236
	v_mul_f32_e32 v3, 0xbfb8aa3b, v3
	v_exp_f32_e32 v3, v3
	v_add_f32_e32 v127, v131, v241
	v_mul_f32_e32 v145, 0xbfb8aa3b, v145
	v_add_f32_e32 v129, v129, v238
	v_add_f32_e32 v3, 1.0, v3
	v_rcp_f32_e32 v131, v3
	v_add_f32_e32 v3, v144, v225
	v_mul_f32_e32 v3, 0xbfb8aa3b, v3
	v_exp_f32_e32 v3, v3
	v_add_f32_e32 v144, v148, v239
	v_mul_f32_e32 v129, 0xbfb8aa3b, v129
	v_mul_f32_e32 v142, 0xbfb8aa3b, v142
	v_add_f32_e32 v3, 1.0, v3
	v_rcp_f32_e32 v148, v3
	v_add_f32_e32 v3, v128, v237
	v_mul_f32_e32 v3, 0xbfb8aa3b, v3
	v_exp_f32_e32 v3, v3
	v_add_f32_e32 v128, v132, v242
	v_add_f32_e32 v132, v149, v240
	v_exp_f32_e32 v149, v145
	v_add_f32_e32 v3, 1.0, v3
	v_mul_f32_e32 v132, 0xbfb8aa3b, v132
	v_exp_f32_e32 v145, v132
	v_rcp_f32_e32 v132, v3
	v_add_f32_e32 v3, 1.0, v149
	v_rcp_f32_e32 v149, v3
	v_add_f32_e32 v3, v133, v243
	v_exp_f32_e32 v133, v129
	v_mul_f32_e32 v126, 0xbfb8aa3b, v126
	v_mul_f32_e32 v127, 0xbfb8aa3b, v127
	v_mul_f32_e32 v144, 0xbfb8aa3b, v144
	v_mul_f32_e32 v128, 0xbfb8aa3b, v128
	v_mul_f32_e32 v3, 0xbfb8aa3b, v3
	v_exp_f32_e32 v142, v142
	v_exp_f32_e32 v126, v126
	v_exp_f32_e32 v127, v127
	v_exp_f32_e32 v144, v144
	v_exp_f32_e32 v128, v128
	v_exp_f32_e32 v129, v3
	v_add_f32_e32 v3, 1.0, v133
	v_rcp_f32_e32 v133, v3
	v_pk_add_f32 v[144:145], v[144:145], 1.0 op_sel_hi:[1,0]
	v_pk_add_f32 v[142:143], v[142:143], 1.0 op_sel_hi:[1,0]
	v_pk_add_f32 v[128:129], v[128:129], 1.0 op_sel_hi:[1,0]
	v_pk_add_f32 v[126:127], v[126:127], 1.0 op_sel_hi:[1,0]
	v_pk_mul_f32 v[142:143], v[142:143], v[146:147]
	v_pk_mul_f32 v[144:145], v[144:145], v[148:149]
	v_pk_mul_f32 v[126:127], v[126:127], v[130:131]
	v_pk_mul_f32 v[128:129], v[128:129], v[132:133]
	v_pk_mul_f32 v[76:77], v[76:77], v[144:145]
	v_pk_mul_f32 v[74:75], v[74:75], v[142:143]
	v_pk_mul_f32 v[72:73], v[72:73], v[128:129]
	v_pk_mul_f32 v[70:71], v[70:71], v[126:127]
	global_load_dwordx4 v[196:199], v[4:5], off offset:256
	global_load_dwordx4 v[236:239], v[186:187], off offset:256
	global_load_dwordx4 v[146:149], v[188:189], off offset:256
	global_load_dwordx4 v[142:145], v[190:191], off offset:256
	global_load_dwordx4 v[130:133], v[194:195], off offset:256
	global_load_dwordx4 v[126:129], v[200:201], off offset:256
	s_waitcnt vmcnt(11)
; __device__ __forceinline__ void unpack8(const u32x4 w, float (&v)[8]) { v[0] = bf_lo(w.x); v[1] = bf_hi(w.x); v[2] = bf_lo(w.y); v[3] = bf_hi(w.y); v[4] = bf_lo(w.z); v[5] = bf_hi(w.z); v[6] = bf_lo(w.w); v[7] = bf_hi(w.w); }
;     __device__ __forceinline__ void after(int te, f32x4 (&acc)[2][2][4][2], const Unit& u, int wr, int wc, int fr, int fq) const {
;     ...
;                     for (int m = 0; m < 4; ++m) { float vs[8], va[8]; unpack8(gs[m], vs); unpack8(ga[m], va);
; #pragma unroll
;                         for (int e = 0; e < 4; ++e) {
;                             acc[ai][bj][m][0][e] *= (1.f + __expf(-(va[e] + a0[e]))) * __builtin_amdgcn_rcpf(1.f + __expf(-(vs[e] + s0[e])));
;                             acc[ai][bj][m][1][e] *= (1.f + __expf(-(va[4 + e] + a1[e]))) * __builtin_amdgcn_rcpf(1.f + __expf(-(vs[4 + e] + s1[e]))); } }
	v_lshlrev_b32_e32 v3, 16, v228
	v_lshlrev_b32_e32 v187, 16, v230
	v_and_b32_e32 v5, 0xffff0000, v228
	s_waitcnt vmcnt(10)
	v_lshlrev_b32_e32 v188, 16, v234
	v_and_b32_e32 v189, 0xffff0000, v230
	v_lshlrev_b32_e32 v192, 16, v229
	v_and_b32_e32 v191, 0xffff0000, v232
	v_lshlrev_b32_e32 v195, 16, v231
	v_lshlrev_b32_e32 v194, 16, v233
	v_and_b32_e32 v193, 0xffff0000, v229
	v_lshlrev_b32_e32 v203, 16, v235
	s_waitcnt vmcnt(8)
	v_add_f32_e32 v3, v158, v3
	v_mul_f32_e32 v3, 0xbfb8aa3b, v3
	v_exp_f32_e32 v3, v3
	v_add_f32_e32 v193, v161, v193
	v_mul_f32_e32 v193, 0xbfb8aa3b, v193
	v_lshlrev_b32_e32 v4, 16, v232
	v_add_f32_e32 v3, 1.0, v3
	v_rcp_f32_e32 v186, v3
	v_add_f32_e32 v3, v150, v187
	v_mul_f32_e32 v3, 0xbfb8aa3b, v3
	v_exp_f32_e32 v3, v3
	s_waitcnt vmcnt(7)
	v_add_f32_e32 v187, v154, v188
	v_mul_f32_e32 v187, 0xbfb8aa3b, v187
	v_exp_f32_e32 v188, v187
	v_add_f32_e32 v3, 1.0, v3
	v_rcp_f32_e32 v190, v3
	v_add_f32_e32 v3, v159, v5
	v_mul_f32_e32 v3, 0xbfb8aa3b, v3
	v_exp_f32_e32 v3, v3
	s_waitcnt vmcnt(6)
	v_add_f32_e32 v5, v163, v191
	v_and_b32_e32 v202, 0xffff0000, v233
	v_and_b32_e32 v200, 0xffff0000, v234
	v_add_f32_e32 v3, 1.0, v3
	v_rcp_f32_e32 v187, v3
	v_add_f32_e32 v3, v151, v189
	v_mul_f32_e32 v3, 0xbfb8aa3b, v3
	v_exp_f32_e32 v3, v3
	v_add_f32_e32 v4, v162, v4
	v_add_f32_e32 v189, v155, v200
	v_mul_f32_e32 v4, 0xbfb8aa3b, v4
	v_add_f32_e32 v3, 1.0, v3
	v_rcp_f32_e32 v191, v3
	v_add_f32_e32 v3, v160, v192
	v_mul_f32_e32 v3, 0xbfb8aa3b, v3
	v_exp_f32_e32 v3, v3
	v_add_f32_e32 v192, v164, v194
	v_mul_f32_e32 v5, 0xbfb8aa3b, v5
	v_mul_f32_e32 v192, 0xbfb8aa3b, v192
	v_add_f32_e32 v3, 1.0, v3
	v_rcp_f32_e32 v194, v3
	v_add_f32_e32 v3, v152, v195
	v_mul_f32_e32 v3, 0xbfb8aa3b, v3
	v_exp_f32_e32 v3, v3
	v_add_f32_e32 v195, v156, v203
	v_exp_f32_e32 v203, v193
	v_mul_f32_e32 v195, 0xbfb8aa3b, v195
	v_exp_f32_e32 v200, v195
	v_add_f32_e32 v195, v165, v202
	v_add_f32_e32 v3, 1.0, v3
	v_mul_f32_e32 v193, 0xbfb8aa3b, v195
	v_exp_f32_e32 v4, v4
	v_exp_f32_e32 v5, v5
	v_exp_f32_e32 v192, v192
	v_exp_f32_e32 v193, v193
	v_rcp_f32_e32 v202, v3
	v_add_f32_e32 v3, 1.0, v203
	v_rcp_f32_e32 v195, v3
	v_pk_add_f32 v[192:193], v[192:193], 1.0 op_sel_hi:[1,0]
	v_pk_add_f32 v[4:5], v[4:5], 1.0 op_sel_hi:[1,0]
	v_and_b32_e32 v201, 0xffff0000, v231
	v_pk_mul_f32 v[4:5], v[4:5], v[186:187]
	v_pk_mul_f32 v[186:187], v[192:193], v[194:195]
	v_and_b32_e32 v225, 0xffff0000, v235
	v_pk_mul_f32 v[68:69], v[68:69], v[186:187]
	v_add_f32_e32 v186, v153, v201
	v_mul_f32_e32 v186, 0xbfb8aa3b, v186
	v_exp_f32_e32 v186, v186
	v_add_f32_e32 v3, v157, v225
	v_mul_f32_e32 v3, 0xbfb8aa3b, v3
	v_exp_f32_e32 v201, v3
	v_add_f32_e32 v3, 1.0, v186
	v_mul_f32_e32 v189, 0xbfb8aa3b, v189
	v_rcp_f32_e32 v203, v3
	s_waitcnt vmcnt(5)
	v_lshlrev_b32_e32 v3, 16, v196
	v_exp_f32_e32 v189, v189
	v_add_f32_e32 v3, v158, v3
	v_mul_f32_e32 v3, 0xbfb8aa3b, v3
	v_exp_f32_e32 v3, v3
	v_pk_add_f32 v[186:187], v[188:189], 1.0 op_sel_hi:[1,0]
	v_pk_mul_f32 v[66:67], v[66:67], v[4:5]
	v_pk_mul_f32 v[186:187], v[186:187], v[190:191]
	v_add_f32_e32 v3, 1.0, v3
	v_pk_mul_f32 v[62:63], v[62:63], v[186:187]
	v_lshlrev_b32_e32 v187, 16, v198
	v_rcp_f32_e32 v186, v3
	v_add_f32_e32 v3, v150, v187
	v_mul_f32_e32 v3, 0xbfb8aa3b, v3
	v_exp_f32_e32 v3, v3
	v_pk_add_f32 v[4:5], v[200:201], 1.0 op_sel_hi:[1,0]
	s_waitcnt vmcnt(4)
	v_lshlrev_b32_e32 v188, 16, v238
	v_pk_mul_f32 v[4:5], v[4:5], v[202:203]
	v_add_f32_e32 v3, 1.0, v3
	v_pk_mul_f32 v[64:65], v[64:65], v[4:5]
	v_and_b32_e32 v5, 0xffff0000, v196
	v_rcp_f32_e32 v190, v3
	v_add_f32_e32 v3, v159, v5
	v_mul_f32_e32 v3, 0xbfb8aa3b, v3
	v_exp_f32_e32 v3, v3
	v_add_f32_e32 v187, v154, v188
	v_and_b32_e32 v189, 0xffff0000, v198
	v_mul_f32_e32 v187, 0xbfb8aa3b, v187
	v_add_f32_e32 v3, 1.0, v3
	v_exp_f32_e32 v188, v187
	v_rcp_f32_e32 v187, v3
	v_add_f32_e32 v3, v151, v189
	v_mul_f32_e32 v3, 0xbfb8aa3b, v3
	v_exp_f32_e32 v3, v3
	v_lshlrev_b32_e32 v192, 16, v197
	v_and_b32_e32 v191, 0xffff0000, v236
	v_add_f32_e32 v5, v163, v191
	v_add_f32_e32 v3, 1.0, v3
	v_rcp_f32_e32 v191, v3
	v_add_f32_e32 v3, v160, v192
	v_mul_f32_e32 v3, 0xbfb8aa3b, v3
	v_exp_f32_e32 v3, v3
	v_lshlrev_b32_e32 v195, 16, v199
	v_lshlrev_b32_e32 v194, 16, v237
	v_and_b32_e32 v193, 0xffff0000, v197
	v_add_f32_e32 v3, 1.0, v3
	v_add_f32_e32 v192, v164, v194
	v_rcp_f32_e32 v194, v3
	v_add_f32_e32 v3, v152, v195
	v_mul_f32_e32 v3, 0xbfb8aa3b, v3
	v_add_f32_e32 v193, v161, v193
	v_and_b32_e32 v197, 0xffff0000, v199
	v_lshlrev_b32_e32 v199, 16, v239
	v_exp_f32_e32 v3, v3
	v_mul_f32_e32 v193, 0xbfb8aa3b, v193
	v_add_f32_e32 v195, v156, v199
	v_exp_f32_e32 v199, v193
	v_lshlrev_b32_e32 v4, 16, v236
	v_and_b32_e32 v198, 0xffff0000, v237
	v_and_b32_e32 v196, 0xffff0000, v238
	v_mul_f32_e32 v195, 0xbfb8aa3b, v195
	v_add_f32_e32 v4, v162, v4
	v_add_f32_e32 v189, v155, v196
	v_exp_f32_e32 v196, v195
	v_add_f32_e32 v195, v165, v198
	v_mul_f32_e32 v4, 0xbfb8aa3b, v4
	v_mul_f32_e32 v5, 0xbfb8aa3b, v5
	v_mul_f32_e32 v192, 0xbfb8aa3b, v192
	v_add_f32_e32 v3, 1.0, v3
	v_mul_f32_e32 v193, 0xbfb8aa3b, v195
	v_exp_f32_e32 v4, v4
	v_exp_f32_e32 v5, v5
	v_exp_f32_e32 v192, v192
	v_exp_f32_e32 v193, v193
	v_rcp_f32_e32 v198, v3
	v_add_f32_e32 v3, 1.0, v199
	v_rcp_f32_e32 v195, v3
	v_pk_add_f32 v[192:193], v[192:193], 1.0 op_sel_hi:[1,0]
	v_pk_add_f32 v[4:5], v[4:5], 1.0 op_sel_hi:[1,0]
	v_and_b32_e32 v200, 0xffff0000, v239
	v_pk_mul_f32 v[4:5], v[4:5], v[186:187]
	v_pk_mul_f32 v[186:187], v[192:193], v[194:195]
	v_add_f32_e32 v3, v157, v200
	v_pk_mul_f32 v[60:61], v[60:61], v[186:187]
	v_add_f32_e32 v186, v153, v197
	v_mul_f32_e32 v186, 0xbfb8aa3b, v186
	v_exp_f32_e32 v186, v186
	v_mul_f32_e32 v3, 0xbfb8aa3b, v3
	v_exp_f32_e32 v197, v3
	v_mul_f32_e32 v189, 0xbfb8aa3b, v189
	v_add_f32_e32 v3, 1.0, v186
	v_rcp_f32_e32 v199, v3
	s_waitcnt vmcnt(3)
; __device__ __forceinline__ void unpack8(const u32x4 w, float (&v)[8]) { v[0] = bf_lo(w.x); v[1] = bf_hi(w.x); v[2] = bf_lo(w.y); v[3] = bf_hi(w.y); v[4] = bf_lo(w.z); v[5] = bf_hi(w.z); v[6] = bf_lo(w.w); v[7] = bf_hi(w.w); }
;     __device__ __forceinline__ void after(int te, f32x4 (&acc)[2][2][4][2], const Unit& u, int wr, int wc, int fr, int fq) const {
;     ...
;                     for (int m = 0; m < 4; ++m) { const size_t r = (size_t)(row0 + ai * HALF + m * 16); gs[m] = *(const u32x4*)(proj + r * LDP + PGS + c); ga[m] = *(const u32x4*)(proj + r * LDP + PGA + c); }
; #pragma unroll
;                     for (int m = 0; m < 4; ++m) { float vs[8], va[8]; unpack8(gs[m], vs); unpack8(ga[m], va);
; #pragma unroll
;                         for (int e = 0; e < 4; ++e) {
;                             acc[ai][bj][m][0][e] *= (1.f + __expf(-(va[e] + a0[e]))) * __builtin_amdgcn_rcpf(1.f + __expf(-(vs[e] + s0[e])));
;                             acc[ai][bj][m][1][e] *= (1.f + __expf(-(va[4 + e] + a1[e]))) * __builtin_amdgcn_rcpf(1.f + __expf(-(vs[4 + e] + s1[e]))); } }
	v_lshlrev_b32_e32 v3, 16, v146
	v_add_f32_e32 v3, v158, v3
	v_exp_f32_e32 v189, v189
	v_mul_f32_e32 v3, 0xbfb8aa3b, v3
	v_exp_f32_e32 v3, v3
	v_pk_mul_f32 v[58:59], v[58:59], v[4:5]
	v_pk_add_f32 v[4:5], v[196:197], 1.0 op_sel_hi:[1,0]
	v_pk_add_f32 v[186:187], v[188:189], 1.0 op_sel_hi:[1,0]
	v_pk_mul_f32 v[4:5], v[4:5], v[198:199]
	v_pk_mul_f32 v[186:187], v[186:187], v[190:191]
	v_pk_mul_f32 v[56:57], v[56:57], v[4:5]
	v_and_b32_e32 v5, 0xffff0000, v146
	v_lshlrev_b32_e32 v146, 16, v148
	v_add_f32_e32 v3, 1.0, v3
	v_pk_mul_f32 v[54:55], v[54:55], v[186:187]
	v_lshlrev_b32_e32 v186, 16, v147
	v_and_b32_e32 v187, 0xffff0000, v147
	v_and_b32_e32 v147, 0xffff0000, v148
	s_waitcnt vmcnt(2)
	v_lshlrev_b32_e32 v4, 16, v142
	v_and_b32_e32 v148, 0xffff0000, v142
	v_rcp_f32_e32 v142, v3
	v_add_f32_e32 v3, v150, v146
	v_mul_f32_e32 v3, 0xbfb8aa3b, v3
	v_exp_f32_e32 v3, v3
	v_lshlrev_b32_e32 v188, 16, v149
	v_and_b32_e32 v189, 0xffff0000, v149
	v_lshlrev_b32_e32 v149, 16, v143
	v_add_f32_e32 v3, 1.0, v3
	v_rcp_f32_e32 v146, v3
	v_add_f32_e32 v3, v159, v5
	v_mul_f32_e32 v3, 0xbfb8aa3b, v3
	v_exp_f32_e32 v3, v3
	v_and_b32_e32 v190, 0xffff0000, v143
	v_lshlrev_b32_e32 v143, 16, v144
	v_add_f32_e32 v143, v154, v143
	v_mul_f32_e32 v143, 0xbfb8aa3b, v143
	v_add_f32_e32 v3, 1.0, v3
	v_and_b32_e32 v191, 0xffff0000, v144
	v_exp_f32_e32 v144, v143
	v_rcp_f32_e32 v143, v3
	v_add_f32_e32 v3, v151, v147
	v_mul_f32_e32 v3, 0xbfb8aa3b, v3
	v_exp_f32_e32 v3, v3
	v_add_f32_e32 v187, v161, v187
	v_lshlrev_b32_e32 v192, 16, v145
	v_mul_f32_e32 v187, 0xbfb8aa3b, v187
	v_add_f32_e32 v3, 1.0, v3
	v_rcp_f32_e32 v147, v3
	v_add_f32_e32 v3, v160, v186
	v_mul_f32_e32 v3, 0xbfb8aa3b, v3
	v_exp_f32_e32 v3, v3
	v_add_f32_e32 v5, v163, v148
	v_add_f32_e32 v148, v164, v149
	v_add_f32_e32 v149, v156, v192
	v_add_f32_e32 v3, 1.0, v3
	v_rcp_f32_e32 v186, v3
	v_add_f32_e32 v3, v152, v188
	v_mul_f32_e32 v3, 0xbfb8aa3b, v3
	v_exp_f32_e32 v3, v3
	v_exp_f32_e32 v187, v187
	v_mul_f32_e32 v149, 0xbfb8aa3b, v149
	v_add_f32_e32 v4, v162, v4
	v_exp_f32_e32 v188, v149
	v_add_f32_e32 v149, v165, v190
	v_mul_f32_e32 v4, 0xbfb8aa3b, v4
	v_mul_f32_e32 v5, 0xbfb8aa3b, v5
	v_mul_f32_e32 v148, 0xbfb8aa3b, v148
	v_add_f32_e32 v3, 1.0, v3
	v_mul_f32_e32 v149, 0xbfb8aa3b, v149
	v_exp_f32_e32 v4, v4
	v_exp_f32_e32 v5, v5
	v_exp_f32_e32 v148, v148
	v_exp_f32_e32 v149, v149
	v_rcp_f32_e32 v190, v3
	v_add_f32_e32 v3, 1.0, v187
	v_rcp_f32_e32 v187, v3
	v_pk_add_f32 v[148:149], v[148:149], 1.0 op_sel_hi:[1,0]
	v_pk_add_f32 v[4:5], v[4:5], 1.0 op_sel_hi:[1,0]
	v_and_b32_e32 v193, 0xffff0000, v145
	v_pk_mul_f32 v[4:5], v[4:5], v[142:143]
	v_pk_mul_f32 v[142:143], v[148:149], v[186:187]
	v_add_f32_e32 v3, v157, v193
	v_pk_mul_f32 v[52:53], v[52:53], v[142:143]
	v_add_f32_e32 v142, v153, v189
	v_mul_f32_e32 v142, 0xbfb8aa3b, v142
	v_mul_f32_e32 v3, 0xbfb8aa3b, v3
	v_exp_f32_e32 v142, v142
	v_exp_f32_e32 v189, v3
	v_pk_mul_f32 v[50:51], v[50:51], v[4:5]
	v_add_f32_e32 v3, 1.0, v142
	v_pk_add_f32 v[4:5], v[188:189], 1.0 op_sel_hi:[1,0]
	global_load_dwordx4 v[186:189], v[218:219], off offset:256
	v_add_f32_e32 v145, v155, v191
	v_rcp_f32_e32 v191, v3
	s_waitcnt vmcnt(2)
	v_lshlrev_b32_e32 v3, 16, v130
	v_mul_f32_e32 v145, 0xbfb8aa3b, v145
	v_add_f32_e32 v3, v158, v3
	v_exp_f32_e32 v145, v145
	v_mul_f32_e32 v3, 0xbfb8aa3b, v3
	v_exp_f32_e32 v3, v3
	v_pk_mul_f32 v[4:5], v[4:5], v[190:191]
	v_pk_add_f32 v[142:143], v[144:145], 1.0 op_sel_hi:[1,0]
	v_pk_mul_f32 v[48:49], v[48:49], v[4:5]
	v_pk_mul_f32 v[142:143], v[142:143], v[146:147]
	v_and_b32_e32 v5, 0xffff0000, v130
	v_lshlrev_b32_e32 v130, 16, v132
	v_add_f32_e32 v3, 1.0, v3
	v_pk_mul_f32 v[46:47], v[46:47], v[142:143]
	v_lshlrev_b32_e32 v142, 16, v131
	v_and_b32_e32 v143, 0xffff0000, v131
	v_and_b32_e32 v131, 0xffff0000, v132
	s_waitcnt vmcnt(1)
	v_lshlrev_b32_e32 v4, 16, v126
	v_and_b32_e32 v132, 0xffff0000, v126
	v_rcp_f32_e32 v126, v3
	v_add_f32_e32 v3, v150, v130
	v_mul_f32_e32 v3, 0xbfb8aa3b, v3
	v_exp_f32_e32 v3, v3
	global_load_dwordx4 v[190:193], v[216:217], off offset:256
	v_lshlrev_b32_e32 v144, 16, v133
	v_and_b32_e32 v145, 0xffff0000, v133
	v_add_f32_e32 v3, 1.0, v3
	v_rcp_f32_e32 v130, v3
	v_add_f32_e32 v3, v159, v5
	v_mul_f32_e32 v3, 0xbfb8aa3b, v3
	v_exp_f32_e32 v3, v3
	v_lshlrev_b32_e32 v133, 16, v127
	v_and_b32_e32 v146, 0xffff0000, v127
	v_lshlrev_b32_e32 v127, 16, v128
	v_add_f32_e32 v127, v154, v127
	v_mul_f32_e32 v127, 0xbfb8aa3b, v127
	v_add_f32_e32 v3, 1.0, v3
	v_and_b32_e32 v147, 0xffff0000, v128
	v_exp_f32_e32 v128, v127
	v_rcp_f32_e32 v127, v3
	v_add_f32_e32 v3, v151, v131
	v_mul_f32_e32 v3, 0xbfb8aa3b, v3
	v_exp_f32_e32 v3, v3
	v_add_f32_e32 v143, v161, v143
	v_lshlrev_b32_e32 v148, 16, v129
	v_mul_f32_e32 v143, 0xbfb8aa3b, v143
	v_add_f32_e32 v3, 1.0, v3
	v_rcp_f32_e32 v131, v3
	v_add_f32_e32 v3, v160, v142
	v_mul_f32_e32 v3, 0xbfb8aa3b, v3
	v_exp_f32_e32 v3, v3
	v_add_f32_e32 v5, v163, v132
	v_add_f32_e32 v132, v164, v133
	v_add_f32_e32 v133, v156, v148
	v_add_f32_e32 v3, 1.0, v3
	v_rcp_f32_e32 v142, v3
	v_add_f32_e32 v3, v152, v144
	v_mul_f32_e32 v3, 0xbfb8aa3b, v3
	v_exp_f32_e32 v3, v3
	v_exp_f32_e32 v143, v143
	v_mul_f32_e32 v133, 0xbfb8aa3b, v133
	v_add_f32_e32 v4, v162, v4
	v_exp_f32_e32 v144, v133
	v_add_f32_e32 v133, v165, v146
	v_mul_f32_e32 v4, 0xbfb8aa3b, v4
	v_mul_f32_e32 v5, 0xbfb8aa3b, v5
	v_mul_f32_e32 v132, 0xbfb8aa3b, v132
	v_add_f32_e32 v3, 1.0, v3
	v_mul_f32_e32 v133, 0xbfb8aa3b, v133
	v_exp_f32_e32 v4, v4
	v_exp_f32_e32 v5, v5
	v_exp_f32_e32 v132, v132
	v_exp_f32_e32 v133, v133
	v_rcp_f32_e32 v146, v3
	v_add_f32_e32 v3, 1.0, v143
	v_rcp_f32_e32 v143, v3
	v_pk_add_f32 v[132:133], v[132:133], 1.0 op_sel_hi:[1,0]
	v_pk_add_f32 v[4:5], v[4:5], 1.0 op_sel_hi:[1,0]
	v_and_b32_e32 v149, 0xffff0000, v129
	v_pk_mul_f32 v[4:5], v[4:5], v[126:127]
	v_pk_mul_f32 v[126:127], v[132:133], v[142:143]
	v_add_f32_e32 v129, v155, v147
	v_pk_mul_f32 v[44:45], v[44:45], v[126:127]
	v_add_f32_e32 v126, v153, v145
	v_mul_f32_e32 v126, 0xbfb8aa3b, v126
	v_exp_f32_e32 v126, v126
	v_mul_f32_e32 v129, 0xbfb8aa3b, v129
	v_add_f32_e32 v3, v157, v149
	v_exp_f32_e32 v129, v129
	v_mul_f32_e32 v3, 0xbfb8aa3b, v3
	v_exp_f32_e32 v145, v3
	v_add_f32_e32 v3, 1.0, v126
	v_rcp_f32_e32 v147, v3
	v_pk_add_f32 v[126:127], v[128:129], 1.0 op_sel_hi:[1,0]
	v_pk_mul_f32 v[42:43], v[42:43], v[4:5]
	v_pk_add_f32 v[4:5], v[144:145], 1.0 op_sel_hi:[1,0]
	v_pk_mul_f32 v[126:127], v[126:127], v[130:131]
	v_pk_mul_f32 v[4:5], v[4:5], v[146:147]
	v_pk_mul_f32 v[38:39], v[38:39], v[126:127]
	global_load_dwordx4 v[194:197], v[204:205], off offset:256
	global_load_dwordx4 v[198:201], v[206:207], off offset:256
	global_load_dwordx4 v[146:149], v[208:209], off offset:256
	global_load_dwordx4 v[142:145], v[210:211], off offset:256
	global_load_dwordx4 v[130:133], v[212:213], off offset:256
	global_load_dwordx4 v[126:129], v[214:215], off offset:256
	s_waitcnt vmcnt(7)
; __device__ __forceinline__ void unpack8(const u32x4 w, float (&v)[8]) { v[0] = bf_lo(w.x); v[1] = bf_hi(w.x); v[2] = bf_lo(w.y); v[3] = bf_hi(w.y); v[4] = bf_lo(w.z); v[5] = bf_hi(w.z); v[6] = bf_lo(w.w); v[7] = bf_hi(w.w); }
;     __device__ __forceinline__ void after(int te, f32x4 (&acc)[2][2][4][2], const Unit& u, int wr, int wc, int fr, int fq) const {
;     ...
;                     for (int m = 0; m < 4; ++m) { float vs[8], va[8]; unpack8(gs[m], vs); unpack8(ga[m], va);
; #pragma unroll
;                         for (int e = 0; e < 4; ++e) {
;                             acc[ai][bj][m][0][e] *= (1.f + __expf(-(va[e] + a0[e]))) * __builtin_amdgcn_rcpf(1.f + __expf(-(vs[e] + s0[e])));
;                             acc[ai][bj][m][1][e] *= (1.f + __expf(-(va[4 + e] + a1[e]))) * __builtin_amdgcn_rcpf(1.f + __expf(-(vs[4 + e] + s1[e]))); } }
	v_lshlrev_b32_e32 v3, 16, v186
	v_add_f32_e32 v3, v158, v3
	v_mul_f32_e32 v3, 0xbfb8aa3b, v3
	v_exp_f32_e32 v3, v3
	v_lshlrev_b32_e32 v202, 16, v187
	v_and_b32_e32 v203, 0xffff0000, v187
	v_lshlrev_b32_e32 v187, 16, v188
	v_add_f32_e32 v3, 1.0, v3
	v_pk_mul_f32 v[40:41], v[40:41], v[4:5]
	v_and_b32_e32 v5, 0xffff0000, v186
	v_rcp_f32_e32 v186, v3
	v_add_f32_e32 v3, v150, v187
	v_mul_f32_e32 v3, 0xbfb8aa3b, v3
	v_exp_f32_e32 v3, v3
	v_lshlrev_b32_e32 v205, 16, v189
	v_and_b32_e32 v207, 0xffff0000, v189
	s_waitcnt vmcnt(6)
	v_lshlrev_b32_e32 v4, 16, v190
	v_add_f32_e32 v3, 1.0, v3
	v_and_b32_e32 v189, 0xffff0000, v190
	v_rcp_f32_e32 v190, v3
	v_add_f32_e32 v3, v159, v5
	v_mul_f32_e32 v3, 0xbfb8aa3b, v3
	v_exp_f32_e32 v3, v3
	v_and_b32_e32 v204, 0xffff0000, v188
	v_lshlrev_b32_e32 v188, 16, v192
	v_add_f32_e32 v187, v154, v188
	v_mul_f32_e32 v187, 0xbfb8aa3b, v187
	v_add_f32_e32 v3, 1.0, v3
	v_exp_f32_e32 v188, v187
	v_rcp_f32_e32 v187, v3
	v_add_f32_e32 v3, v151, v204
	v_mul_f32_e32 v3, 0xbfb8aa3b, v3
	v_exp_f32_e32 v3, v3
	v_lshlrev_b32_e32 v206, 16, v191
	v_and_b32_e32 v208, 0xffff0000, v191
	v_and_b32_e32 v191, 0xffff0000, v192
	v_add_f32_e32 v3, 1.0, v3
	v_add_f32_e32 v5, v163, v189
	v_add_f32_e32 v189, v155, v191
	v_rcp_f32_e32 v191, v3
	v_add_f32_e32 v3, v160, v202
	v_mul_f32_e32 v3, 0xbfb8aa3b, v3
	v_exp_f32_e32 v3, v3
	v_add_f32_e32 v203, v161, v203
	v_lshlrev_b32_e32 v209, 16, v193
	v_mul_f32_e32 v203, 0xbfb8aa3b, v203
	v_add_f32_e32 v3, 1.0, v3
	v_rcp_f32_e32 v202, v3
	v_add_f32_e32 v3, v152, v205
	v_mul_f32_e32 v3, 0xbfb8aa3b, v3
	v_exp_f32_e32 v3, v3
	v_and_b32_e32 v210, 0xffff0000, v193
	v_add_f32_e32 v193, v156, v209
	v_exp_f32_e32 v203, v203
	v_mul_f32_e32 v193, 0xbfb8aa3b, v193
	v_add_f32_e32 v4, v162, v4
	v_add_f32_e32 v192, v164, v206
	v_exp_f32_e32 v204, v193
	v_add_f32_e32 v193, v165, v208
	v_mul_f32_e32 v4, 0xbfb8aa3b, v4
	v_mul_f32_e32 v5, 0xbfb8aa3b, v5
	v_mul_f32_e32 v192, 0xbfb8aa3b, v192
	v_add_f32_e32 v3, 1.0, v3
	v_mul_f32_e32 v193, 0xbfb8aa3b, v193
	v_exp_f32_e32 v4, v4
	v_exp_f32_e32 v5, v5
	v_exp_f32_e32 v192, v192
	v_exp_f32_e32 v193, v193
	v_rcp_f32_e32 v206, v3
	v_add_f32_e32 v3, 1.0, v203
	v_rcp_f32_e32 v203, v3
	v_pk_add_f32 v[192:193], v[192:193], 1.0 op_sel_hi:[1,0]
	v_pk_add_f32 v[4:5], v[4:5], 1.0 op_sel_hi:[1,0]
	v_add_f32_e32 v3, v157, v210
	v_pk_mul_f32 v[4:5], v[4:5], v[186:187]
	v_pk_mul_f32 v[186:187], v[192:193], v[202:203]
	v_mul_f32_e32 v3, 0xbfb8aa3b, v3
	v_pk_mul_f32 v[36:37], v[36:37], v[186:187]
	v_add_f32_e32 v186, v153, v207
	v_mul_f32_e32 v186, 0xbfb8aa3b, v186
	v_exp_f32_e32 v186, v186
	v_exp_f32_e32 v205, v3
	v_mul_f32_e32 v189, 0xbfb8aa3b, v189
	v_exp_f32_e32 v189, v189
	v_add_f32_e32 v3, 1.0, v186
	v_rcp_f32_e32 v207, v3
	s_waitcnt vmcnt(5)
	v_lshlrev_b32_e32 v3, 16, v194
	v_add_f32_e32 v3, v158, v3
	v_mul_f32_e32 v3, 0xbfb8aa3b, v3
	v_exp_f32_e32 v3, v3
	v_pk_add_f32 v[186:187], v[188:189], 1.0 op_sel_hi:[1,0]
	v_pk_mul_f32 v[34:35], v[34:35], v[4:5]
	v_pk_mul_f32 v[186:187], v[186:187], v[190:191]
	v_add_f32_e32 v3, 1.0, v3
	v_pk_mul_f32 v[30:31], v[30:31], v[186:187]
	v_lshlrev_b32_e32 v187, 16, v196
	v_rcp_f32_e32 v186, v3
	v_add_f32_e32 v3, v150, v187
	v_mul_f32_e32 v3, 0xbfb8aa3b, v3
	v_exp_f32_e32 v3, v3
	v_pk_add_f32 v[4:5], v[204:205], 1.0 op_sel_hi:[1,0]
	s_waitcnt vmcnt(4)
	v_lshlrev_b32_e32 v188, 16, v200
	v_pk_mul_f32 v[4:5], v[4:5], v[206:207]
	v_add_f32_e32 v3, 1.0, v3
	v_pk_mul_f32 v[32:33], v[32:33], v[4:5]
	v_and_b32_e32 v5, 0xffff0000, v194
	v_rcp_f32_e32 v190, v3
	v_add_f32_e32 v3, v159, v5
	v_mul_f32_e32 v3, 0xbfb8aa3b, v3
	v_exp_f32_e32 v3, v3
	v_add_f32_e32 v187, v154, v188
	v_and_b32_e32 v189, 0xffff0000, v196
	v_mul_f32_e32 v187, 0xbfb8aa3b, v187
	v_add_f32_e32 v3, 1.0, v3
	v_exp_f32_e32 v188, v187
	v_rcp_f32_e32 v187, v3
	v_add_f32_e32 v3, v151, v189
	v_mul_f32_e32 v3, 0xbfb8aa3b, v3
	v_exp_f32_e32 v3, v3
	v_lshlrev_b32_e32 v192, 16, v195
	v_and_b32_e32 v191, 0xffff0000, v198
	v_add_f32_e32 v5, v163, v191
	v_add_f32_e32 v3, 1.0, v3
	v_rcp_f32_e32 v191, v3
	v_add_f32_e32 v3, v160, v192
	v_mul_f32_e32 v3, 0xbfb8aa3b, v3
	v_exp_f32_e32 v3, v3
	v_and_b32_e32 v193, 0xffff0000, v195
	v_lshlrev_b32_e32 v195, 16, v197
	v_lshlrev_b32_e32 v194, 16, v199
	v_add_f32_e32 v3, 1.0, v3
	v_add_f32_e32 v192, v164, v194
	v_rcp_f32_e32 v194, v3
	v_add_f32_e32 v3, v152, v195
	v_mul_f32_e32 v3, 0xbfb8aa3b, v3
	v_add_f32_e32 v193, v161, v193
	v_lshlrev_b32_e32 v4, 16, v198
	v_and_b32_e32 v198, 0xffff0000, v199
	v_lshlrev_b32_e32 v199, 16, v201
	v_exp_f32_e32 v3, v3
	v_mul_f32_e32 v193, 0xbfb8aa3b, v193
	v_add_f32_e32 v195, v156, v199
	v_exp_f32_e32 v199, v193
	v_and_b32_e32 v196, 0xffff0000, v200
	v_mul_f32_e32 v195, 0xbfb8aa3b, v195
	v_add_f32_e32 v4, v162, v4
	v_add_f32_e32 v189, v155, v196
	v_exp_f32_e32 v196, v195
	v_add_f32_e32 v195, v165, v198
	v_mul_f32_e32 v4, 0xbfb8aa3b, v4
	v_mul_f32_e32 v5, 0xbfb8aa3b, v5
	v_mul_f32_e32 v192, 0xbfb8aa3b, v192
	v_add_f32_e32 v3, 1.0, v3
	v_mul_f32_e32 v193, 0xbfb8aa3b, v195
	v_exp_f32_e32 v4, v4
	v_exp_f32_e32 v5, v5
	v_exp_f32_e32 v192, v192
	v_exp_f32_e32 v193, v193
	v_rcp_f32_e32 v198, v3
	v_add_f32_e32 v3, 1.0, v199
	v_rcp_f32_e32 v195, v3
	v_pk_add_f32 v[192:193], v[192:193], 1.0 op_sel_hi:[1,0]
	v_pk_add_f32 v[4:5], v[4:5], 1.0 op_sel_hi:[1,0]
	v_and_b32_e32 v197, 0xffff0000, v197
	v_pk_mul_f32 v[4:5], v[4:5], v[186:187]
	v_pk_mul_f32 v[186:187], v[192:193], v[194:195]
	v_and_b32_e32 v200, 0xffff0000, v201
	v_pk_mul_f32 v[28:29], v[28:29], v[186:187]
	v_add_f32_e32 v186, v153, v197
	v_mul_f32_e32 v186, 0xbfb8aa3b, v186
	v_exp_f32_e32 v186, v186
	v_add_f32_e32 v3, v157, v200
	v_mul_f32_e32 v3, 0xbfb8aa3b, v3
	v_exp_f32_e32 v197, v3
	v_add_f32_e32 v3, 1.0, v186
	v_rcp_f32_e32 v199, v3
	s_waitcnt vmcnt(3)
; __device__ __forceinline__ void unpack8(const u32x4 w, float (&v)[8]) { v[0] = bf_lo(w.x); v[1] = bf_hi(w.x); v[2] = bf_lo(w.y); v[3] = bf_hi(w.y); v[4] = bf_lo(w.z); v[5] = bf_hi(w.z); v[6] = bf_lo(w.w); v[7] = bf_hi(w.w); }
;     __device__ __forceinline__ void after(int te, f32x4 (&acc)[2][2][4][2], const Unit& u, int wr, int wc, int fr, int fq) const {
;     ...
;                     for (int m = 0; m < 4; ++m) { float vs[8], va[8]; unpack8(gs[m], vs); unpack8(ga[m], va);
; #pragma unroll
;                         for (int e = 0; e < 4; ++e) {
;                             acc[ai][bj][m][0][e] *= (1.f + __expf(-(va[e] + a0[e]))) * __builtin_amdgcn_rcpf(1.f + __expf(-(vs[e] + s0[e])));
;                             acc[ai][bj][m][1][e] *= (1.f + __expf(-(va[4 + e] + a1[e]))) * __builtin_amdgcn_rcpf(1.f + __expf(-(vs[4 + e] + s1[e]))); } }
	v_lshlrev_b32_e32 v3, 16, v146
	v_mul_f32_e32 v189, 0xbfb8aa3b, v189
	v_add_f32_e32 v3, v158, v3
	v_exp_f32_e32 v189, v189
	v_mul_f32_e32 v3, 0xbfb8aa3b, v3
	v_exp_f32_e32 v3, v3
	v_pk_mul_f32 v[26:27], v[26:27], v[4:5]
	v_pk_add_f32 v[4:5], v[196:197], 1.0 op_sel_hi:[1,0]
	v_pk_add_f32 v[186:187], v[188:189], 1.0 op_sel_hi:[1,0]
	v_pk_mul_f32 v[4:5], v[4:5], v[198:199]
	v_pk_mul_f32 v[186:187], v[186:187], v[190:191]
	v_pk_mul_f32 v[24:25], v[24:25], v[4:5]
	v_and_b32_e32 v5, 0xffff0000, v146
	v_lshlrev_b32_e32 v146, 16, v148
	v_add_f32_e32 v3, 1.0, v3
	v_pk_mul_f32 v[22:23], v[22:23], v[186:187]
	v_lshlrev_b32_e32 v186, 16, v147
	v_and_b32_e32 v187, 0xffff0000, v147
	v_and_b32_e32 v147, 0xffff0000, v148
	s_waitcnt vmcnt(2)
	v_lshlrev_b32_e32 v4, 16, v142
	v_and_b32_e32 v148, 0xffff0000, v142
	v_rcp_f32_e32 v142, v3
	v_add_f32_e32 v3, v150, v146
	v_mul_f32_e32 v3, 0xbfb8aa3b, v3
	v_exp_f32_e32 v3, v3
	v_lshlrev_b32_e32 v188, 16, v149
	v_and_b32_e32 v189, 0xffff0000, v149
	v_lshlrev_b32_e32 v149, 16, v143
	v_add_f32_e32 v3, 1.0, v3
	v_rcp_f32_e32 v146, v3
	v_add_f32_e32 v3, v159, v5
	v_mul_f32_e32 v3, 0xbfb8aa3b, v3
	v_exp_f32_e32 v3, v3
	v_and_b32_e32 v190, 0xffff0000, v143
	v_lshlrev_b32_e32 v143, 16, v144
	v_add_f32_e32 v143, v154, v143
	v_mul_f32_e32 v143, 0xbfb8aa3b, v143
	v_add_f32_e32 v3, 1.0, v3
	v_and_b32_e32 v191, 0xffff0000, v144
	v_exp_f32_e32 v144, v143
	v_rcp_f32_e32 v143, v3
	v_add_f32_e32 v3, v151, v147
	v_mul_f32_e32 v3, 0xbfb8aa3b, v3
	v_exp_f32_e32 v3, v3
	v_add_f32_e32 v187, v161, v187
	v_lshlrev_b32_e32 v192, 16, v145
	v_mul_f32_e32 v187, 0xbfb8aa3b, v187
	v_add_f32_e32 v3, 1.0, v3
	v_rcp_f32_e32 v147, v3
	v_add_f32_e32 v3, v160, v186
	v_mul_f32_e32 v3, 0xbfb8aa3b, v3
	v_exp_f32_e32 v3, v3
	v_add_f32_e32 v5, v163, v148
	v_add_f32_e32 v148, v164, v149
	v_add_f32_e32 v149, v156, v192
	v_add_f32_e32 v3, 1.0, v3
	v_rcp_f32_e32 v186, v3
	v_add_f32_e32 v3, v152, v188
	v_mul_f32_e32 v3, 0xbfb8aa3b, v3
	v_exp_f32_e32 v3, v3
	v_exp_f32_e32 v187, v187
	v_mul_f32_e32 v149, 0xbfb8aa3b, v149
	v_add_f32_e32 v4, v162, v4
	v_exp_f32_e32 v188, v149
	v_add_f32_e32 v149, v165, v190
	v_mul_f32_e32 v4, 0xbfb8aa3b, v4
	v_mul_f32_e32 v5, 0xbfb8aa3b, v5
	v_mul_f32_e32 v148, 0xbfb8aa3b, v148
	v_add_f32_e32 v3, 1.0, v3
	v_mul_f32_e32 v149, 0xbfb8aa3b, v149
	v_exp_f32_e32 v4, v4
	v_exp_f32_e32 v5, v5
	v_exp_f32_e32 v148, v148
	v_exp_f32_e32 v149, v149
	v_rcp_f32_e32 v190, v3
	v_add_f32_e32 v3, 1.0, v187
	v_rcp_f32_e32 v187, v3
	v_pk_add_f32 v[148:149], v[148:149], 1.0 op_sel_hi:[1,0]
	v_pk_add_f32 v[4:5], v[4:5], 1.0 op_sel_hi:[1,0]
	v_and_b32_e32 v193, 0xffff0000, v145
	v_pk_mul_f32 v[4:5], v[4:5], v[142:143]
	v_pk_mul_f32 v[142:143], v[148:149], v[186:187]
	v_add_f32_e32 v3, v157, v193
	v_pk_mul_f32 v[20:21], v[20:21], v[142:143]
	v_add_f32_e32 v142, v153, v189
	v_mul_f32_e32 v142, 0xbfb8aa3b, v142
	v_exp_f32_e32 v142, v142
	v_mul_f32_e32 v3, 0xbfb8aa3b, v3
	v_exp_f32_e32 v189, v3
	v_add_f32_e32 v145, v155, v191
	v_add_f32_e32 v3, 1.0, v142
	v_rcp_f32_e32 v191, v3
	s_waitcnt vmcnt(1)
	v_lshlrev_b32_e32 v3, 16, v130
	v_mul_f32_e32 v145, 0xbfb8aa3b, v145
	v_add_f32_e32 v3, v158, v3
	v_exp_f32_e32 v145, v145
	v_mul_f32_e32 v3, 0xbfb8aa3b, v3
	v_exp_f32_e32 v3, v3
	v_pk_mul_f32 v[18:19], v[18:19], v[4:5]
	v_pk_add_f32 v[4:5], v[188:189], 1.0 op_sel_hi:[1,0]
	v_pk_add_f32 v[142:143], v[144:145], 1.0 op_sel_hi:[1,0]
	v_pk_mul_f32 v[4:5], v[4:5], v[190:191]
	v_pk_mul_f32 v[142:143], v[142:143], v[146:147]
	v_pk_mul_f32 v[16:17], v[16:17], v[4:5]
	v_and_b32_e32 v5, 0xffff0000, v130
	v_lshlrev_b32_e32 v130, 16, v132
	v_add_f32_e32 v3, 1.0, v3
	v_pk_mul_f32 v[14:15], v[14:15], v[142:143]
	v_lshlrev_b32_e32 v142, 16, v131
	v_and_b32_e32 v143, 0xffff0000, v131
	v_and_b32_e32 v131, 0xffff0000, v132
	s_waitcnt vmcnt(0)
	v_lshlrev_b32_e32 v4, 16, v126
	v_and_b32_e32 v132, 0xffff0000, v126
	v_rcp_f32_e32 v126, v3
	v_add_f32_e32 v3, v150, v130
	v_mul_f32_e32 v3, 0xbfb8aa3b, v3
	v_exp_f32_e32 v3, v3
	v_lshlrev_b32_e32 v144, 16, v133
	v_and_b32_e32 v145, 0xffff0000, v133
	v_lshlrev_b32_e32 v133, 16, v127
	v_add_f32_e32 v3, 1.0, v3
	v_rcp_f32_e32 v130, v3
	v_add_f32_e32 v3, v159, v5
	v_mul_f32_e32 v3, 0xbfb8aa3b, v3
	v_exp_f32_e32 v3, v3
	v_and_b32_e32 v146, 0xffff0000, v127
	v_lshlrev_b32_e32 v127, 16, v128
	v_add_f32_e32 v127, v154, v127
	v_mul_f32_e32 v127, 0xbfb8aa3b, v127
	v_add_f32_e32 v3, 1.0, v3
	v_and_b32_e32 v147, 0xffff0000, v128
	v_exp_f32_e32 v128, v127
	v_rcp_f32_e32 v127, v3
	v_add_f32_e32 v3, v151, v131
	v_mul_f32_e32 v3, 0xbfb8aa3b, v3
	v_exp_f32_e32 v3, v3
	v_add_f32_e32 v143, v161, v143
	v_lshlrev_b32_e32 v148, 16, v129
	v_mul_f32_e32 v143, 0xbfb8aa3b, v143
	v_add_f32_e32 v3, 1.0, v3
	v_rcp_f32_e32 v131, v3
	v_add_f32_e32 v3, v160, v142
	v_mul_f32_e32 v3, 0xbfb8aa3b, v3
	v_exp_f32_e32 v3, v3
	v_add_f32_e32 v5, v163, v132
	v_add_f32_e32 v132, v164, v133
	v_add_f32_e32 v133, v156, v148
	v_add_f32_e32 v3, 1.0, v3
	v_rcp_f32_e32 v142, v3
	v_add_f32_e32 v3, v152, v144
	v_mul_f32_e32 v3, 0xbfb8aa3b, v3
	v_exp_f32_e32 v3, v3
	v_exp_f32_e32 v143, v143
	v_mul_f32_e32 v133, 0xbfb8aa3b, v133
	v_add_f32_e32 v4, v162, v4
	v_exp_f32_e32 v144, v133
	v_add_f32_e32 v133, v165, v146
	v_mul_f32_e32 v4, 0xbfb8aa3b, v4
	v_mul_f32_e32 v5, 0xbfb8aa3b, v5
	v_mul_f32_e32 v132, 0xbfb8aa3b, v132
	v_add_f32_e32 v3, 1.0, v3
	v_mul_f32_e32 v133, 0xbfb8aa3b, v133
	v_exp_f32_e32 v4, v4
	v_exp_f32_e32 v5, v5
	v_exp_f32_e32 v132, v132
	v_exp_f32_e32 v133, v133
	v_rcp_f32_e32 v146, v3
	v_add_f32_e32 v3, 1.0, v143
	v_rcp_f32_e32 v143, v3
	v_pk_add_f32 v[132:133], v[132:133], 1.0 op_sel_hi:[1,0]
	v_pk_add_f32 v[4:5], v[4:5], 1.0 op_sel_hi:[1,0]
	v_and_b32_e32 v149, 0xffff0000, v129
	v_pk_mul_f32 v[4:5], v[4:5], v[126:127]
	v_pk_mul_f32 v[126:127], v[132:133], v[142:143]
	v_add_f32_e32 v129, v155, v147
	v_pk_mul_f32 v[12:13], v[12:13], v[126:127]
	v_add_f32_e32 v126, v153, v145
	v_mul_f32_e32 v126, 0xbfb8aa3b, v126
	v_exp_f32_e32 v126, v126
	v_add_f32_e32 v3, v157, v149
	v_mul_f32_e32 v129, 0xbfb8aa3b, v129
	v_mul_f32_e32 v3, 0xbfb8aa3b, v3
	v_exp_f32_e32 v129, v129
	v_exp_f32_e32 v145, v3
	v_add_f32_e32 v3, 1.0, v126
	v_rcp_f32_e32 v147, v3
	v_pk_mul_f32 v[10:11], v[10:11], v[4:5]
	v_pk_add_f32 v[4:5], v[144:145], 1.0 op_sel_hi:[1,0]
	v_pk_add_f32 v[126:127], v[128:129], 1.0 op_sel_hi:[1,0]
	v_pk_mul_f32 v[4:5], v[4:5], v[146:147]
	v_pk_mul_f32 v[126:127], v[126:127], v[130:131]
	v_pk_mul_f32 v[8:9], v[8:9], v[4:5]
	v_pk_mul_f32 v[6:7], v[6:7], v[126:127]

; #define PG8_STAGE(bufoff, gbase, voff) do { _Pragma("unroll") for (int _i = 0; _i < 2; ++_i) \
;         __builtin_amdgcn_global_load_lds((const unsigned*)((const char*)(gbase) + (voff)[_i]), (LAS unsigned*)(lds + (bufoff) + ldsw + _i * 8192), 16, 0, 0); } while (0)
; #define PG8_LDA(dst, b, h) do { _Pragma("unroll") for (int m = 0; m < 4; ++m) _Pragma("unroll") for (int k = 0; k < 2; ++k) dst[m][k] = *(const LAS bf16x8*)(lds + PG8_SA(b, h) + aoff + m * 2048 + k * 1024); } while (0)
; #define PG8_LDB(dst, b, h) do { _Pragma("unroll") for (int n = 0; n < 2; ++n) _Pragma("unroll") for (int k = 0; k < 2; ++k) dst[n][k] = *(const LAS bf16x8*)(lds + PG8_SB(b, h) + boff + n * 2048 + k * 1024); } while (0)
; #define PG8_MMA(ai, bj, At, Bt) do { __builtin_amdgcn_s_setprio(1); _Pragma("unroll") for (int m = 0; m < 4; ++m) _Pragma("unroll") for (int n = 0; n < 2; ++n) _Pragma("unroll") for (int k = 0; k < 2; ++k) \
;         acc[ai][bj][m][n] = __builtin_amdgcn_mfma_f32_16x16x32_bf16(Bt[n][k], At[m][k], acc[ai][bj][m][n], 0, 0, 0); __builtin_amdgcn_s_setprio(0); } while (0)
; #define PG8_WAIT_V(n) asm volatile("s_waitcnt vmcnt(" #n ")" ::: "memory")
; #define PG8_WAIT_L(n) asm volatile("s_waitcnt lgkmcnt(" #n ")" ::: "memory")
; #define PG8_BAR __builtin_amdgcn_s_barrier()
; template <class Epi, class Sched, bool ALIGN_EPI, class Hook = NoHook>
; __device__ __forceinline__ void gemm_phase(LAS unsigned char* lds, const Gemm g, const Sched& S, const Epi& E, const Hook& H = Hook()) {
;     ...
;             const bool last = (t == nt - 2);
;             const char* a1 = cA + (size_t)(t + 1) * kstep;
;             const char* a2 = last ? nA : cA + (size_t)(t + 2) * kstep; const char* b2 = last ? nB : cB + (size_t)(t + 2) * kstep;
;             const char* a3 = a2 + kstep; const char* b3 = b2 + kstep;
;             if (last && has_next) S.a_ready(nxt);
;             PG8_LDB(B0, 0, 0); PG8_LDB(B1, 0, 1); PG8_SCHED; PG8_LDA(At, 0, 0); PG8_STAGE(PG8_SA(1, 1), a1 + hA, voffA);
;             PG8_WAIT_V(8); PG8_WAIT_L(0); PG8_BAR; PG8_MMA(0, 0, At, B0); PG8_MMA(0, 1, At, B1); PG8_BAR; PG8_SCHED;
;             PG8_LDA(At, 0, 1); PG8_STAGE(PG8_SB(0, 0), b2, voffB); PG8_STAGE(PG8_SB(0, 1), b2 + hB, voffB); PG8_STAGE(PG8_SA(0, 0), a2, voffA);
;             PG8_WAIT_V(8); PG8_WAIT_L(0); PG8_BAR; PG8_MMA(1, 0, At, B0); PG8_MMA(1, 1, At, B1); PG8_BAR; PG8_SCHED;
.LBB0_850:
	ds_read_b128 v[146:149], v1
	ds_read_b128 v[150:153], v1 offset:1024
	s_add_u32 s20, s6, 0x87c00080
	s_addc_u32 s21, s7, -1
	s_cmp_lg_u32 s42, 60
	s_cselect_b32 s20, s20, 0
	s_cselect_b32 s21, s21, 0
	s_add_u32 s22, s2, s20
	s_addc_u32 s23, s3, s21
	s_add_u32 s20, s14, s20
	s_addc_u32 s21, s15, s21
	s_mov_b32 m0, s43
	ds_read_b128 v[154:157], v1 offset:2048
	ds_read_b128 v[158:161], v1 offset:3072
	ds_read_b128 v[162:165], v142
	ds_read_b128 v[166:169], v142 offset:1024
	ds_read_b128 v[170:173], v142 offset:2048
	ds_read_b128 v[174:177], v142 offset:3072
	v_lshl_add_u64 v[178:179], v[138:139], 0, s[6:7]
	global_load_lds_dwordx4 v[178:179], off
	ds_read_b128 v[186:189], v143
	ds_read_b128 v[190:193], v143 offset:1024
	ds_read_b128 v[194:197], v143 offset:2048
	ds_read_b128 v[198:201], v143 offset:3072
	ds_read_b128 v[202:205], v143 offset:4096
	ds_read_b128 v[206:209], v143 offset:5120
	ds_read_b128 v[210:213], v143 offset:6144
	ds_read_b128 v[214:217], v143 offset:7168
	v_lshl_add_u64 v[178:179], v[140:141], 0, s[6:7]
	s_mov_b32 m0, s44
	s_nop 0
	global_load_lds_dwordx4 v[178:179], off
	s_waitcnt vmcnt(8) lgkmcnt(0)
	s_barrier
	s_setprio 1
	v_mfma_f32_16x16x32_bf16 v[54:57], v[146:149], v[186:189], v[54:57]
	v_mfma_f32_16x16x32_bf16 v[34:37], v[154:157], v[186:189], v[34:37]
	v_mfma_f32_16x16x32_bf16 v[42:45], v[146:149], v[194:197], v[42:45]
	v_mfma_f32_16x16x32_bf16 v[30:33], v[154:157], v[194:197], v[30:33]
	v_mfma_f32_16x16x32_bf16 v[62:65], v[146:149], v[202:205], v[62:65]
	v_mfma_f32_16x16x32_bf16 v[50:53], v[154:157], v[202:205], v[50:53]
	v_mfma_f32_16x16x32_bf16 v[78:81], v[146:149], v[210:213], v[78:81]
	v_mfma_f32_16x16x32_bf16 v[70:73], v[154:157], v[210:213], v[70:73]
	v_mfma_f32_16x16x32_bf16 v[54:57], v[150:153], v[190:193], v[54:57]
	v_mfma_f32_16x16x32_bf16 v[34:37], v[158:161], v[190:193], v[34:37]
	v_mfma_f32_16x16x32_bf16 v[42:45], v[150:153], v[198:201], v[42:45]
	v_mfma_f32_16x16x32_bf16 v[30:33], v[158:161], v[198:201], v[30:33]
	v_mfma_f32_16x16x32_bf16 v[62:65], v[150:153], v[206:209], v[62:65]
	v_mfma_f32_16x16x32_bf16 v[50:53], v[158:161], v[206:209], v[50:53]
	v_mfma_f32_16x16x32_bf16 v[78:81], v[150:153], v[214:217], v[78:81]
	v_mfma_f32_16x16x32_bf16 v[70:73], v[158:161], v[214:217], v[70:73]
	s_setprio 0
	s_setprio 1
	v_mfma_f32_16x16x32_bf16 v[10:13], v[162:165], v[186:189], v[10:13]
	v_mfma_f32_16x16x32_bf16 v[2:5], v[170:173], v[186:189], v[2:5]
	v_mfma_f32_16x16x32_bf16 v[14:17], v[162:165], v[194:197], v[14:17]
	v_mfma_f32_16x16x32_bf16 v[6:9], v[170:173], v[194:197], v[6:9]
	v_mfma_f32_16x16x32_bf16 v[22:25], v[162:165], v[202:205], v[22:25]
	v_mfma_f32_16x16x32_bf16 v[18:21], v[170:173], v[202:205], v[18:21]
	v_mfma_f32_16x16x32_bf16 v[38:41], v[162:165], v[210:213], v[38:41]
	v_mfma_f32_16x16x32_bf16 v[26:29], v[170:173], v[210:213], v[26:29]
	v_mfma_f32_16x16x32_bf16 v[10:13], v[166:169], v[190:193], v[10:13]
	v_mfma_f32_16x16x32_bf16 v[2:5], v[174:177], v[190:193], v[2:5]
	v_mfma_f32_16x16x32_bf16 v[14:17], v[166:169], v[198:201], v[14:17]
	v_mfma_f32_16x16x32_bf16 v[6:9], v[174:177], v[198:201], v[6:9]
	v_mfma_f32_16x16x32_bf16 v[22:25], v[166:169], v[206:209], v[22:25]
	v_mfma_f32_16x16x32_bf16 v[18:21], v[174:177], v[206:209], v[18:21]
	v_mfma_f32_16x16x32_bf16 v[38:41], v[166:169], v[214:217], v[38:41]
	v_mfma_f32_16x16x32_bf16 v[26:29], v[174:177], v[214:217], v[26:29]
	s_barrier
	s_setprio 0
	s_mov_b32 m0, s45
	s_add_u32 s54, s20, 0x100000
	ds_read_b128 v[186:189], v143 offset:16384
	ds_read_b128 v[190:193], v143 offset:17408
	global_load_lds_dwordx4 v132, s[20:21]
	ds_read_b128 v[194:197], v143 offset:18432
	s_mov_b32 m0, s46
	s_addc_u32 s55, s21, 0
	global_load_lds_dwordx4 v136, s[20:21]
	ds_read_b128 v[198:201], v143 offset:19456
	s_mov_b32 m0, s47
	s_nop 0
	global_load_lds_dwordx4 v132, s[54:55]
	ds_read_b128 v[202:205], v143 offset:20480
	s_mov_b32 m0, s48
	s_nop 0
	global_load_lds_dwordx4 v136, s[54:55]
	ds_read_b128 v[206:209], v143 offset:21504
	s_add_u32 s58, s22, s4
	s_addc_u32 s59, s23, s5
	s_mov_b32 m0, s28
	s_nop 0
	global_load_lds_dwordx4 v130, s[22:23]
	ds_read_b128 v[210:213], v143 offset:22528
	s_mov_b32 m0, s29
	s_nop 0
	global_load_lds_dwordx4 v134, s[22:23]
	ds_read_b128 v[214:217], v143 offset:23552
	s_waitcnt vmcnt(8) lgkmcnt(0)
	s_barrier
	s_setprio 1
	v_mfma_f32_16x16x32_bf16 v[94:97], v[146:149], v[186:189], v[94:97]
	v_mfma_f32_16x16x32_bf16 v[86:89], v[154:157], v[186:189], v[86:89]
	v_mfma_f32_16x16x32_bf16 v[102:105], v[146:149], v[194:197], v[102:105]
	v_mfma_f32_16x16x32_bf16 v[98:101], v[154:157], v[194:197], v[98:101]
	v_mfma_f32_16x16x32_bf16 v[110:113], v[146:149], v[202:205], v[110:113]
	v_mfma_f32_16x16x32_bf16 v[106:109], v[154:157], v[202:205], v[106:109]
	v_mfma_f32_16x16x32_bf16 v[126:129], v[146:149], v[210:213], v[126:129]
	v_mfma_f32_16x16x32_bf16 v[122:125], v[154:157], v[210:213], v[122:125]
	v_mfma_f32_16x16x32_bf16 v[94:97], v[150:153], v[190:193], v[94:97]
	v_mfma_f32_16x16x32_bf16 v[86:89], v[158:161], v[190:193], v[86:89]
	v_mfma_f32_16x16x32_bf16 v[102:105], v[150:153], v[198:201], v[102:105]
	v_mfma_f32_16x16x32_bf16 v[98:101], v[158:161], v[198:201], v[98:101]
	v_mfma_f32_16x16x32_bf16 v[110:113], v[150:153], v[206:209], v[110:113]
	v_mfma_f32_16x16x32_bf16 v[106:109], v[158:161], v[206:209], v[106:109]
	v_mfma_f32_16x16x32_bf16 v[126:129], v[150:153], v[214:217], v[126:129]
	v_mfma_f32_16x16x32_bf16 v[122:125], v[158:161], v[214:217], v[122:125]
	s_setprio 0
	s_setprio 1
	v_mfma_f32_16x16x32_bf16 v[58:61], v[162:165], v[186:189], v[58:61]
	v_mfma_f32_16x16x32_bf16 v[46:49], v[170:173], v[186:189], v[46:49]
	v_mfma_f32_16x16x32_bf16 v[74:77], v[162:165], v[194:197], v[74:77]
	v_mfma_f32_16x16x32_bf16 v[66:69], v[170:173], v[194:197], v[66:69]
	v_mfma_f32_16x16x32_bf16 v[90:93], v[162:165], v[202:205], v[90:93]
	v_mfma_f32_16x16x32_bf16 v[82:85], v[170:173], v[202:205], v[82:85]
	v_mfma_f32_16x16x32_bf16 v[118:121], v[162:165], v[210:213], v[118:121]
	v_mfma_f32_16x16x32_bf16 v[114:117], v[170:173], v[210:213], v[114:117]
	v_mfma_f32_16x16x32_bf16 v[58:61], v[166:169], v[190:193], v[58:61]
	v_mfma_f32_16x16x32_bf16 v[46:49], v[174:177], v[190:193], v[46:49]
	v_mfma_f32_16x16x32_bf16 v[74:77], v[166:169], v[198:201], v[74:77]
	v_mfma_f32_16x16x32_bf16 v[66:69], v[174:177], v[198:201], v[66:69]
	v_mfma_f32_16x16x32_bf16 v[90:93], v[166:169], v[206:209], v[90:93]
	v_mfma_f32_16x16x32_bf16 v[82:85], v[174:177], v[206:209], v[82:85]
	v_mfma_f32_16x16x32_bf16 v[118:121], v[166:169], v[214:217], v[118:121]
	v_mfma_f32_16x16x32_bf16 v[114:117], v[174:177], v[214:217], v[114:117]
	s_barrier
; #define PG8_STAGE(bufoff, gbase, voff) do { _Pragma("unroll") for (int _i = 0; _i < 2; ++_i) \
;         __builtin_amdgcn_global_load_lds((const unsigned*)((const char*)(gbase) + (voff)[_i]), (LAS unsigned*)(lds + (bufoff) + ldsw + _i * 8192), 16, 0, 0); } while (0)
; #define PG8_LDA(dst, b, h) do { _Pragma("unroll") for (int m = 0; m < 4; ++m) _Pragma("unroll") for (int k = 0; k < 2; ++k) dst[m][k] = *(const LAS bf16x8*)(lds + PG8_SA(b, h) + aoff + m * 2048 + k * 1024); } while (0)
; #define PG8_LDB(dst, b, h) do { _Pragma("unroll") for (int n = 0; n < 2; ++n) _Pragma("unroll") for (int k = 0; k < 2; ++k) dst[n][k] = *(const LAS bf16x8*)(lds + PG8_SB(b, h) + boff + n * 2048 + k * 1024); } while (0)
; #define PG8_MMA(ai, bj, At, Bt) do { __builtin_amdgcn_s_setprio(1); _Pragma("unroll") for (int m = 0; m < 4; ++m) _Pragma("unroll") for (int n = 0; n < 2; ++n) _Pragma("unroll") for (int k = 0; k < 2; ++k) \
;         acc[ai][bj][m][n] = __builtin_amdgcn_mfma_f32_16x16x32_bf16(Bt[n][k], At[m][k], acc[ai][bj][m][n], 0, 0, 0); __builtin_amdgcn_s_setprio(0); } while (0)
; #define PG8_WAIT_V(n) asm volatile("s_waitcnt vmcnt(" #n ")" ::: "memory")
; #define PG8_WAIT_L(n) asm volatile("s_waitcnt lgkmcnt(" #n ")" ::: "memory")
; #define PG8_BAR __builtin_amdgcn_s_barrier()
; #define PG8_SCHED __builtin_amdgcn_sched_barrier(0)
; template <class Epi, class Sched, bool ALIGN_EPI, class Hook = NoHook>
; __device__ __forceinline__ void gemm_phase(LAS unsigned char* lds, const Gemm g, const Sched& S, const Epi& E, const Hook& H = Hook()) {
;     ...
;             PG8_LDB(B0, 1, 0); PG8_LDB(B1, 1, 1); PG8_SCHED; PG8_LDA(At, 1, 0); PG8_STAGE(PG8_SA(0, 1), a2 + hA, voffA);
;             PG8_WAIT_V(8); PG8_WAIT_L(0); PG8_BAR; PG8_MMA(0, 0, At, B0); PG8_MMA(0, 1, At, B1); PG8_BAR; PG8_SCHED;
;             PG8_LDA(At, 1, 1); PG8_STAGE(PG8_SB(1, 0), b3, voffB); PG8_STAGE(PG8_SB(1, 1), b3 + hB, voffB); PG8_STAGE(PG8_SA(1, 0), a3, voffA);
;             PG8_WAIT_V(8); PG8_WAIT_L(0); PG8_BAR; PG8_MMA(1, 0, At, B0); PG8_MMA(1, 1, At, B1); PG8_BAR; PG8_SCHED;
	s_setprio 0
	ds_read_b128 v[146:149], v144
	ds_read_b128 v[150:153], v144 offset:1024
	s_add_u32 s22, s22, 0x100000
	s_addc_u32 s23, s23, 0
	s_mov_b32 m0, s38
	s_nop 0
	global_load_lds_dwordx4 v130, s[22:23]
	ds_read_b128 v[154:157], v144 offset:2048
	ds_read_b128 v[158:161], v144 offset:3072
	ds_read_b128 v[162:165], v145
	ds_read_b128 v[166:169], v145 offset:1024
	ds_read_b128 v[170:173], v145 offset:2048
	ds_read_b128 v[174:177], v145 offset:3072
	ds_read_b128 v[186:189], v143 offset:32768
	s_mov_b32 m0, s39
	s_nop 0
	global_load_lds_dwordx4 v134, s[22:23]
	ds_read_b128 v[190:193], v143 offset:33792
	ds_read_b128 v[194:197], v143 offset:34816
	ds_read_b128 v[198:201], v143 offset:35840
	ds_read_b128 v[202:205], v143 offset:36864
	ds_read_b128 v[206:209], v143 offset:37888
	ds_read_b128 v[210:213], v143 offset:38912
	ds_read_b128 v[214:217], v143 offset:39936
	s_waitcnt vmcnt(8) lgkmcnt(0)
	s_barrier
	s_setprio 1
	v_mfma_f32_16x16x32_bf16 v[54:57], v[146:149], v[186:189], v[54:57]
	v_mfma_f32_16x16x32_bf16 v[34:37], v[154:157], v[186:189], v[34:37]
	v_mfma_f32_16x16x32_bf16 v[42:45], v[146:149], v[194:197], v[42:45]
	v_mfma_f32_16x16x32_bf16 v[30:33], v[154:157], v[194:197], v[30:33]
	v_mfma_f32_16x16x32_bf16 v[62:65], v[146:149], v[202:205], v[62:65]
	v_mfma_f32_16x16x32_bf16 v[50:53], v[154:157], v[202:205], v[50:53]
	v_mfma_f32_16x16x32_bf16 v[78:81], v[146:149], v[210:213], v[78:81]
	v_mfma_f32_16x16x32_bf16 v[70:73], v[154:157], v[210:213], v[70:73]
	v_mfma_f32_16x16x32_bf16 v[54:57], v[150:153], v[190:193], v[54:57]
	v_mfma_f32_16x16x32_bf16 v[34:37], v[158:161], v[190:193], v[34:37]
	v_mfma_f32_16x16x32_bf16 v[42:45], v[150:153], v[198:201], v[42:45]
	v_mfma_f32_16x16x32_bf16 v[30:33], v[158:161], v[198:201], v[30:33]
	v_mfma_f32_16x16x32_bf16 v[62:65], v[150:153], v[206:209], v[62:65]
	v_mfma_f32_16x16x32_bf16 v[50:53], v[158:161], v[206:209], v[50:53]
	v_mfma_f32_16x16x32_bf16 v[78:81], v[150:153], v[214:217], v[78:81]
	v_mfma_f32_16x16x32_bf16 v[70:73], v[158:161], v[214:217], v[70:73]
	s_setprio 0
	s_setprio 1
	v_mfma_f32_16x16x32_bf16 v[10:13], v[162:165], v[186:189], v[10:13]
	v_mfma_f32_16x16x32_bf16 v[2:5], v[170:173], v[186:189], v[2:5]
	v_mfma_f32_16x16x32_bf16 v[14:17], v[162:165], v[194:197], v[14:17]
	v_mfma_f32_16x16x32_bf16 v[6:9], v[170:173], v[194:197], v[6:9]
	v_mfma_f32_16x16x32_bf16 v[22:25], v[162:165], v[202:205], v[22:25]
	v_mfma_f32_16x16x32_bf16 v[18:21], v[170:173], v[202:205], v[18:21]
	v_mfma_f32_16x16x32_bf16 v[38:41], v[162:165], v[210:213], v[38:41]
	v_mfma_f32_16x16x32_bf16 v[26:29], v[170:173], v[210:213], v[26:29]
	v_mfma_f32_16x16x32_bf16 v[10:13], v[166:169], v[190:193], v[10:13]
	v_mfma_f32_16x16x32_bf16 v[2:5], v[174:177], v[190:193], v[2:5]
	v_mfma_f32_16x16x32_bf16 v[14:17], v[166:169], v[198:201], v[14:17]
	v_mfma_f32_16x16x32_bf16 v[6:9], v[174:177], v[198:201], v[6:9]
	v_mfma_f32_16x16x32_bf16 v[22:25], v[166:169], v[206:209], v[22:25]
	v_mfma_f32_16x16x32_bf16 v[18:21], v[174:177], v[206:209], v[18:21]
	v_mfma_f32_16x16x32_bf16 v[38:41], v[166:169], v[214:217], v[38:41]
	v_mfma_f32_16x16x32_bf16 v[26:29], v[174:177], v[214:217], v[26:29]
	s_barrier
	s_setprio 0
	s_mov_b32 m0, s49
	s_add_u32 s56, s20, s4
	s_addc_u32 s57, s21, s5
	s_add_u32 s20, s20, 0x100080
	ds_read_b128 v[186:189], v143 offset:49152
	ds_read_b128 v[190:193], v143 offset:50176
	global_load_lds_dwordx4 v132, s[56:57]
	ds_read_b128 v[194:197], v143 offset:51200
	s_mov_b32 m0, s50
	s_addc_u32 s21, s21, 0
	global_load_lds_dwordx4 v136, s[56:57]
	ds_read_b128 v[198:201], v143 offset:52224
	s_mov_b32 m0, s51
	s_nop 0
	global_load_lds_dwordx4 v132, s[20:21]
	ds_read_b128 v[202:205], v143 offset:53248
	s_mov_b32 m0, s52
	s_nop 0
	global_load_lds_dwordx4 v136, s[20:21]
	ds_read_b128 v[206:209], v143 offset:54272
	s_mov_b32 m0, s40
	s_nop 0
	global_load_lds_dwordx4 v130, s[58:59]
	ds_read_b128 v[210:213], v143 offset:55296
	s_mov_b32 m0, s41
	s_nop 0
	global_load_lds_dwordx4 v134, s[58:59]
	s_add_i32 s42, s42, 2
	s_add_u32 s6, s6, 0x100
	s_addc_u32 s7, s7, 0
	s_cmp_gt_u32 s42, 61
	ds_read_b128 v[214:217], v143 offset:56320
	s_waitcnt vmcnt(8) lgkmcnt(0)
	s_barrier
	s_setprio 1
	v_mfma_f32_16x16x32_bf16 v[94:97], v[146:149], v[186:189], v[94:97]
	v_mfma_f32_16x16x32_bf16 v[86:89], v[154:157], v[186:189], v[86:89]
	v_mfma_f32_16x16x32_bf16 v[102:105], v[146:149], v[194:197], v[102:105]
	v_mfma_f32_16x16x32_bf16 v[98:101], v[154:157], v[194:197], v[98:101]
	v_mfma_f32_16x16x32_bf16 v[110:113], v[146:149], v[202:205], v[110:113]
	v_mfma_f32_16x16x32_bf16 v[106:109], v[154:157], v[202:205], v[106:109]
	v_mfma_f32_16x16x32_bf16 v[126:129], v[146:149], v[210:213], v[126:129]
	v_mfma_f32_16x16x32_bf16 v[122:125], v[154:157], v[210:213], v[122:125]
	v_mfma_f32_16x16x32_bf16 v[94:97], v[150:153], v[190:193], v[94:97]
	v_mfma_f32_16x16x32_bf16 v[86:89], v[158:161], v[190:193], v[86:89]
	v_mfma_f32_16x16x32_bf16 v[102:105], v[150:153], v[198:201], v[102:105]
	v_mfma_f32_16x16x32_bf16 v[98:101], v[158:161], v[198:201], v[98:101]
	v_mfma_f32_16x16x32_bf16 v[110:113], v[150:153], v[206:209], v[110:113]
	v_mfma_f32_16x16x32_bf16 v[106:109], v[158:161], v[206:209], v[106:109]
	v_mfma_f32_16x16x32_bf16 v[126:129], v[150:153], v[214:217], v[126:129]
	v_mfma_f32_16x16x32_bf16 v[122:125], v[158:161], v[214:217], v[122:125]
	s_setprio 0
	s_setprio 1
	v_mfma_f32_16x16x32_bf16 v[58:61], v[162:165], v[186:189], v[58:61]
	v_mfma_f32_16x16x32_bf16 v[46:49], v[170:173], v[186:189], v[46:49]
	v_mfma_f32_16x16x32_bf16 v[74:77], v[162:165], v[194:197], v[74:77]
	v_mfma_f32_16x16x32_bf16 v[66:69], v[170:173], v[194:197], v[66:69]
	v_mfma_f32_16x16x32_bf16 v[90:93], v[162:165], v[202:205], v[90:93]
	v_mfma_f32_16x16x32_bf16 v[82:85], v[170:173], v[202:205], v[82:85]
	v_mfma_f32_16x16x32_bf16 v[118:121], v[162:165], v[210:213], v[118:121]
	v_mfma_f32_16x16x32_bf16 v[114:117], v[170:173], v[210:213], v[114:117]
	v_mfma_f32_16x16x32_bf16 v[58:61], v[166:169], v[190:193], v[58:61]
	v_mfma_f32_16x16x32_bf16 v[46:49], v[174:177], v[190:193], v[46:49]
	v_mfma_f32_16x16x32_bf16 v[74:77], v[166:169], v[198:201], v[74:77]
	v_mfma_f32_16x16x32_bf16 v[66:69], v[174:177], v[198:201], v[66:69]
	v_mfma_f32_16x16x32_bf16 v[90:93], v[166:169], v[206:209], v[90:93]
	v_mfma_f32_16x16x32_bf16 v[82:85], v[174:177], v[206:209], v[82:85]
	v_mfma_f32_16x16x32_bf16 v[118:121], v[166:169], v[214:217], v[118:121]
	v_mfma_f32_16x16x32_bf16 v[114:117], v[174:177], v[214:217], v[114:117]
	s_barrier
	s_setprio 0
	s_cbranch_scc0 .LBB0_850
	s_cmpk_lt_u32 s26, 0x100
	s_cbranch_scc0 .LBB0_853
	s_barrier

; #define PG8_STAGE(bufoff, gbase, voff) do { _Pragma("unroll") for (int _i = 0; _i < 2; ++_i) \
;         __builtin_amdgcn_global_load_lds((const unsigned*)((const char*)(gbase) + (voff)[_i]), (LAS unsigned*)(lds + (bufoff) + ldsw + _i * 8192), 16, 0, 0); } while (0)
; #define PG8_LDA(dst, b, h) do { _Pragma("unroll") for (int m = 0; m < 4; ++m) _Pragma("unroll") for (int k = 0; k < 2; ++k) dst[m][k] = *(const LAS bf16x8*)(lds + PG8_SA(b, h) + aoff + m * 2048 + k * 1024); } while (0)
; #define PG8_LDB(dst, b, h) do { _Pragma("unroll") for (int n = 0; n < 2; ++n) _Pragma("unroll") for (int k = 0; k < 2; ++k) dst[n][k] = *(const LAS bf16x8*)(lds + PG8_SB(b, h) + boff + n * 2048 + k * 1024); } while (0)
; #define PG8_MMA(ai, bj, At, Bt) do { __builtin_amdgcn_s_setprio(1); _Pragma("unroll") for (int m = 0; m < 4; ++m) _Pragma("unroll") for (int n = 0; n < 2; ++n) _Pragma("unroll") for (int k = 0; k < 2; ++k) \
;         acc[ai][bj][m][n] = __builtin_amdgcn_mfma_f32_16x16x32_bf16(Bt[n][k], At[m][k], acc[ai][bj][m][n], 0, 0, 0); __builtin_amdgcn_s_setprio(0); } while (0)
; #define PG8_WAIT_V(n) asm volatile("s_waitcnt vmcnt(" #n ")" ::: "memory")
; #define PG8_WAIT_L(n) asm volatile("s_waitcnt lgkmcnt(" #n ")" ::: "memory")
; #define PG8_BAR __builtin_amdgcn_s_barrier()
; template <class Epi, class Sched, bool ALIGN_EPI, class Hook = NoHook>
; __device__ __forceinline__ void gemm_phase(LAS unsigned char* lds, const Gemm g, const Sched& S, const Epi& E, const Hook& H = Hook()) {
;     ...
;             const bool last = (t == nt - 2);
;             const char* a1 = cA + (size_t)(t + 1) * kstep;
;             const char* a2 = last ? nA : cA + (size_t)(t + 2) * kstep; const char* b2 = last ? nB : cB + (size_t)(t + 2) * kstep;
;             const char* a3 = a2 + kstep; const char* b3 = b2 + kstep;
;             if (last && has_next) S.a_ready(nxt);
;             PG8_LDB(B0, 0, 0); PG8_LDB(B1, 0, 1); PG8_SCHED; PG8_LDA(At, 0, 0); PG8_STAGE(PG8_SA(1, 1), a1 + hA, voffA);
;             PG8_WAIT_V(8); PG8_WAIT_L(0); PG8_BAR; PG8_MMA(0, 0, At, B0); PG8_MMA(0, 1, At, B1); PG8_BAR; PG8_SCHED;
;             PG8_LDA(At, 0, 1); PG8_STAGE(PG8_SB(0, 0), b2, voffB); PG8_STAGE(PG8_SB(0, 1), b2 + hB, voffB); PG8_STAGE(PG8_SA(0, 0), a2, voffA);
;             PG8_WAIT_V(8); PG8_WAIT_L(0); PG8_BAR; PG8_MMA(1, 0, At, B0); PG8_MMA(1, 1, At, B1); PG8_BAR; PG8_SCHED;
.LBB0_896:
	ds_read_b128 v[146:149], v140
	ds_read_b128 v[150:153], v140 offset:1024
	s_add_u32 s10, s6, 0x87c00080
	s_addc_u32 s11, s7, -1
	s_cmp_lg_u32 s18, 60
	s_cselect_b32 s10, s10, 0
	s_cselect_b32 s11, s11, 0
	s_add_u32 s16, s2, s10
	s_addc_u32 s17, s3, s11
	s_add_u32 s10, s14, s10
	s_addc_u32 s11, s15, s11
	s_mov_b32 m0, s19
	ds_read_b128 v[154:157], v140 offset:2048
	ds_read_b128 v[158:161], v140 offset:3072
	ds_read_b128 v[162:165], v141
	ds_read_b128 v[166:169], v141 offset:1024
	ds_read_b128 v[170:173], v141 offset:2048
	ds_read_b128 v[174:177], v141 offset:3072
	v_lshl_add_u64 v[178:179], v[136:137], 0, s[6:7]
	global_load_lds_dwordx4 v[178:179], off
	ds_read_b128 v[186:189], v142
	ds_read_b128 v[190:193], v142 offset:1024
	ds_read_b128 v[194:197], v142 offset:2048
	ds_read_b128 v[198:201], v142 offset:3072
	ds_read_b128 v[202:205], v142 offset:4096
	ds_read_b128 v[206:209], v142 offset:5120
	ds_read_b128 v[210:213], v142 offset:6144
	ds_read_b128 v[214:217], v142 offset:7168
	v_lshl_add_u64 v[178:179], v[138:139], 0, s[6:7]
	s_mov_b32 m0, s31
	s_nop 0
	global_load_lds_dwordx4 v[178:179], off
	s_waitcnt vmcnt(8) lgkmcnt(0)
	s_barrier
	s_setprio 1
	v_mfma_f32_16x16x32_bf16 v[54:57], v[146:149], v[186:189], v[54:57]
	v_mfma_f32_16x16x32_bf16 v[34:37], v[154:157], v[186:189], v[34:37]
	v_mfma_f32_16x16x32_bf16 v[42:45], v[146:149], v[194:197], v[42:45]
	v_mfma_f32_16x16x32_bf16 v[30:33], v[154:157], v[194:197], v[30:33]
	v_mfma_f32_16x16x32_bf16 v[62:65], v[146:149], v[202:205], v[62:65]
	v_mfma_f32_16x16x32_bf16 v[50:53], v[154:157], v[202:205], v[50:53]
	v_mfma_f32_16x16x32_bf16 v[78:81], v[146:149], v[210:213], v[78:81]
	v_mfma_f32_16x16x32_bf16 v[70:73], v[154:157], v[210:213], v[70:73]
	v_mfma_f32_16x16x32_bf16 v[54:57], v[150:153], v[190:193], v[54:57]
	v_mfma_f32_16x16x32_bf16 v[34:37], v[158:161], v[190:193], v[34:37]
	v_mfma_f32_16x16x32_bf16 v[42:45], v[150:153], v[198:201], v[42:45]
	v_mfma_f32_16x16x32_bf16 v[30:33], v[158:161], v[198:201], v[30:33]
	v_mfma_f32_16x16x32_bf16 v[62:65], v[150:153], v[206:209], v[62:65]
	v_mfma_f32_16x16x32_bf16 v[50:53], v[158:161], v[206:209], v[50:53]
	v_mfma_f32_16x16x32_bf16 v[78:81], v[150:153], v[214:217], v[78:81]
	v_mfma_f32_16x16x32_bf16 v[70:73], v[158:161], v[214:217], v[70:73]
	s_setprio 0
	s_setprio 1
	v_mfma_f32_16x16x32_bf16 v[10:13], v[162:165], v[186:189], v[10:13]
	v_mfma_f32_16x16x32_bf16 v[2:5], v[170:173], v[186:189], v[2:5]
	v_mfma_f32_16x16x32_bf16 v[14:17], v[162:165], v[194:197], v[14:17]
	v_mfma_f32_16x16x32_bf16 v[6:9], v[170:173], v[194:197], v[6:9]
	v_mfma_f32_16x16x32_bf16 v[22:25], v[162:165], v[202:205], v[22:25]
	v_mfma_f32_16x16x32_bf16 v[18:21], v[170:173], v[202:205], v[18:21]
	v_mfma_f32_16x16x32_bf16 v[38:41], v[162:165], v[210:213], v[38:41]
	v_mfma_f32_16x16x32_bf16 v[26:29], v[170:173], v[210:213], v[26:29]
	v_mfma_f32_16x16x32_bf16 v[10:13], v[166:169], v[190:193], v[10:13]
	v_mfma_f32_16x16x32_bf16 v[2:5], v[174:177], v[190:193], v[2:5]
	v_mfma_f32_16x16x32_bf16 v[14:17], v[166:169], v[198:201], v[14:17]
	v_mfma_f32_16x16x32_bf16 v[6:9], v[174:177], v[198:201], v[6:9]
	v_mfma_f32_16x16x32_bf16 v[22:25], v[166:169], v[206:209], v[22:25]
	v_mfma_f32_16x16x32_bf16 v[18:21], v[174:177], v[206:209], v[18:21]
	v_mfma_f32_16x16x32_bf16 v[38:41], v[166:169], v[214:217], v[38:41]
	v_mfma_f32_16x16x32_bf16 v[26:29], v[174:177], v[214:217], v[26:29]
	s_barrier
	s_setprio 0
	s_mov_b32 m0, s33
	s_add_u32 s46, s10, 0x100000
	ds_read_b128 v[186:189], v142 offset:16384
	ds_read_b128 v[190:193], v142 offset:17408
	global_load_lds_dwordx4 v180, s[10:11]
	ds_read_b128 v[194:197], v142 offset:18432
	s_mov_b32 m0, s34
	s_addc_u32 s47, s11, 0
	global_load_lds_dwordx4 v134, s[10:11]
	ds_read_b128 v[198:201], v142 offset:19456
	s_mov_b32 m0, s35
	s_nop 0
	global_load_lds_dwordx4 v180, s[46:47]
	ds_read_b128 v[202:205], v142 offset:20480
	s_mov_b32 m0, s42
	s_nop 0
	global_load_lds_dwordx4 v134, s[46:47]
	ds_read_b128 v[206:209], v142 offset:21504
	s_add_u32 s50, s16, s4
	s_addc_u32 s51, s17, s5
	s_mov_b32 m0, s27
	s_nop 0
	global_load_lds_dwordx4 v130, s[16:17]
	ds_read_b128 v[210:213], v142 offset:22528
	s_mov_b32 m0, s28
	s_nop 0
	global_load_lds_dwordx4 v132, s[16:17]
	ds_read_b128 v[214:217], v142 offset:23552
	s_waitcnt vmcnt(8) lgkmcnt(0)
	s_barrier
	s_setprio 1
	v_mfma_f32_16x16x32_bf16 v[94:97], v[146:149], v[186:189], v[94:97]
	v_mfma_f32_16x16x32_bf16 v[86:89], v[154:157], v[186:189], v[86:89]
	v_mfma_f32_16x16x32_bf16 v[102:105], v[146:149], v[194:197], v[102:105]
	v_mfma_f32_16x16x32_bf16 v[98:101], v[154:157], v[194:197], v[98:101]
	v_mfma_f32_16x16x32_bf16 v[110:113], v[146:149], v[202:205], v[110:113]
	v_mfma_f32_16x16x32_bf16 v[106:109], v[154:157], v[202:205], v[106:109]
	v_mfma_f32_16x16x32_bf16 v[126:129], v[146:149], v[210:213], v[126:129]
	v_mfma_f32_16x16x32_bf16 v[122:125], v[154:157], v[210:213], v[122:125]
	v_mfma_f32_16x16x32_bf16 v[94:97], v[150:153], v[190:193], v[94:97]
	v_mfma_f32_16x16x32_bf16 v[86:89], v[158:161], v[190:193], v[86:89]
	v_mfma_f32_16x16x32_bf16 v[102:105], v[150:153], v[198:201], v[102:105]
	v_mfma_f32_16x16x32_bf16 v[98:101], v[158:161], v[198:201], v[98:101]
	v_mfma_f32_16x16x32_bf16 v[110:113], v[150:153], v[206:209], v[110:113]
	v_mfma_f32_16x16x32_bf16 v[106:109], v[158:161], v[206:209], v[106:109]
	v_mfma_f32_16x16x32_bf16 v[126:129], v[150:153], v[214:217], v[126:129]
	v_mfma_f32_16x16x32_bf16 v[122:125], v[158:161], v[214:217], v[122:125]
	s_setprio 0
	s_setprio 1
	v_mfma_f32_16x16x32_bf16 v[58:61], v[162:165], v[186:189], v[58:61]
	v_mfma_f32_16x16x32_bf16 v[46:49], v[170:173], v[186:189], v[46:49]
	v_mfma_f32_16x16x32_bf16 v[74:77], v[162:165], v[194:197], v[74:77]
	v_mfma_f32_16x16x32_bf16 v[66:69], v[170:173], v[194:197], v[66:69]
	v_mfma_f32_16x16x32_bf16 v[90:93], v[162:165], v[202:205], v[90:93]
	v_mfma_f32_16x16x32_bf16 v[82:85], v[170:173], v[202:205], v[82:85]
	v_mfma_f32_16x16x32_bf16 v[118:121], v[162:165], v[210:213], v[118:121]
	v_mfma_f32_16x16x32_bf16 v[114:117], v[170:173], v[210:213], v[114:117]
	v_mfma_f32_16x16x32_bf16 v[58:61], v[166:169], v[190:193], v[58:61]
	v_mfma_f32_16x16x32_bf16 v[46:49], v[174:177], v[190:193], v[46:49]
	v_mfma_f32_16x16x32_bf16 v[74:77], v[166:169], v[198:201], v[74:77]
	v_mfma_f32_16x16x32_bf16 v[66:69], v[174:177], v[198:201], v[66:69]
	v_mfma_f32_16x16x32_bf16 v[90:93], v[166:169], v[206:209], v[90:93]
	v_mfma_f32_16x16x32_bf16 v[82:85], v[174:177], v[206:209], v[82:85]
	v_mfma_f32_16x16x32_bf16 v[118:121], v[166:169], v[214:217], v[118:121]
	v_mfma_f32_16x16x32_bf16 v[114:117], v[174:177], v[214:217], v[114:117]
	s_barrier
; #define PG8_STAGE(bufoff, gbase, voff) do { _Pragma("unroll") for (int _i = 0; _i < 2; ++_i) \
;         __builtin_amdgcn_global_load_lds((const unsigned*)((const char*)(gbase) + (voff)[_i]), (LAS unsigned*)(lds + (bufoff) + ldsw + _i * 8192), 16, 0, 0); } while (0)
; #define PG8_LDA(dst, b, h) do { _Pragma("unroll") for (int m = 0; m < 4; ++m) _Pragma("unroll") for (int k = 0; k < 2; ++k) dst[m][k] = *(const LAS bf16x8*)(lds + PG8_SA(b, h) + aoff + m * 2048 + k * 1024); } while (0)
; #define PG8_LDB(dst, b, h) do { _Pragma("unroll") for (int n = 0; n < 2; ++n) _Pragma("unroll") for (int k = 0; k < 2; ++k) dst[n][k] = *(const LAS bf16x8*)(lds + PG8_SB(b, h) + boff + n * 2048 + k * 1024); } while (0)
; #define PG8_MMA(ai, bj, At, Bt) do { __builtin_amdgcn_s_setprio(1); _Pragma("unroll") for (int m = 0; m < 4; ++m) _Pragma("unroll") for (int n = 0; n < 2; ++n) _Pragma("unroll") for (int k = 0; k < 2; ++k) \
;         acc[ai][bj][m][n] = __builtin_amdgcn_mfma_f32_16x16x32_bf16(Bt[n][k], At[m][k], acc[ai][bj][m][n], 0, 0, 0); __builtin_amdgcn_s_setprio(0); } while (0)
; #define PG8_WAIT_V(n) asm volatile("s_waitcnt vmcnt(" #n ")" ::: "memory")
; #define PG8_WAIT_L(n) asm volatile("s_waitcnt lgkmcnt(" #n ")" ::: "memory")
; #define PG8_BAR __builtin_amdgcn_s_barrier()
; #define PG8_SCHED __builtin_amdgcn_sched_barrier(0)
; template <class Epi, class Sched, bool ALIGN_EPI, class Hook = NoHook>
; __device__ __forceinline__ void gemm_phase(LAS unsigned char* lds, const Gemm g, const Sched& S, const Epi& E, const Hook& H = Hook()) {
;     ...
;             PG8_LDB(B0, 1, 0); PG8_LDB(B1, 1, 1); PG8_SCHED; PG8_LDA(At, 1, 0); PG8_STAGE(PG8_SA(0, 1), a2 + hA, voffA);
;             PG8_WAIT_V(8); PG8_WAIT_L(0); PG8_BAR; PG8_MMA(0, 0, At, B0); PG8_MMA(0, 1, At, B1); PG8_BAR; PG8_SCHED;
;             PG8_LDA(At, 1, 1); PG8_STAGE(PG8_SB(1, 0), b3, voffB); PG8_STAGE(PG8_SB(1, 1), b3 + hB, voffB); PG8_STAGE(PG8_SA(1, 0), a3, voffA);
;             PG8_WAIT_V(8); PG8_WAIT_L(0); PG8_BAR; PG8_MMA(1, 0, At, B0); PG8_MMA(1, 1, At, B1); PG8_BAR; PG8_SCHED;
	s_setprio 0
	ds_read_b128 v[146:149], v143
	ds_read_b128 v[150:153], v143 offset:1024
	s_add_u32 s16, s16, 0x100000
	s_addc_u32 s17, s17, 0
	s_mov_b32 m0, s29
	s_nop 0
	global_load_lds_dwordx4 v130, s[16:17]
	ds_read_b128 v[154:157], v143 offset:2048
	ds_read_b128 v[158:161], v143 offset:3072
	ds_read_b128 v[162:165], v144
	ds_read_b128 v[166:169], v144 offset:1024
	ds_read_b128 v[170:173], v144 offset:2048
	ds_read_b128 v[174:177], v144 offset:3072
	ds_read_b128 v[186:189], v142 offset:32768
	s_mov_b32 m0, s39
	s_nop 0
	global_load_lds_dwordx4 v132, s[16:17]
	ds_read_b128 v[190:193], v142 offset:33792
	ds_read_b128 v[194:197], v142 offset:34816
	ds_read_b128 v[198:201], v142 offset:35840
	ds_read_b128 v[202:205], v142 offset:36864
	ds_read_b128 v[206:209], v142 offset:37888
	ds_read_b128 v[210:213], v142 offset:38912
	ds_read_b128 v[214:217], v142 offset:39936
	s_waitcnt vmcnt(8) lgkmcnt(0)
	s_barrier
	s_setprio 1
	v_mfma_f32_16x16x32_bf16 v[54:57], v[146:149], v[186:189], v[54:57]
	v_mfma_f32_16x16x32_bf16 v[34:37], v[154:157], v[186:189], v[34:37]
	v_mfma_f32_16x16x32_bf16 v[42:45], v[146:149], v[194:197], v[42:45]
	v_mfma_f32_16x16x32_bf16 v[30:33], v[154:157], v[194:197], v[30:33]
	v_mfma_f32_16x16x32_bf16 v[62:65], v[146:149], v[202:205], v[62:65]
	v_mfma_f32_16x16x32_bf16 v[50:53], v[154:157], v[202:205], v[50:53]
	v_mfma_f32_16x16x32_bf16 v[78:81], v[146:149], v[210:213], v[78:81]
	v_mfma_f32_16x16x32_bf16 v[70:73], v[154:157], v[210:213], v[70:73]
	v_mfma_f32_16x16x32_bf16 v[54:57], v[150:153], v[190:193], v[54:57]
	v_mfma_f32_16x16x32_bf16 v[34:37], v[158:161], v[190:193], v[34:37]
	v_mfma_f32_16x16x32_bf16 v[42:45], v[150:153], v[198:201], v[42:45]
	v_mfma_f32_16x16x32_bf16 v[30:33], v[158:161], v[198:201], v[30:33]
	v_mfma_f32_16x16x32_bf16 v[62:65], v[150:153], v[206:209], v[62:65]
	v_mfma_f32_16x16x32_bf16 v[50:53], v[158:161], v[206:209], v[50:53]
	v_mfma_f32_16x16x32_bf16 v[78:81], v[150:153], v[214:217], v[78:81]
	v_mfma_f32_16x16x32_bf16 v[70:73], v[158:161], v[214:217], v[70:73]
	s_setprio 0
	s_setprio 1
	v_mfma_f32_16x16x32_bf16 v[10:13], v[162:165], v[186:189], v[10:13]
	v_mfma_f32_16x16x32_bf16 v[2:5], v[170:173], v[186:189], v[2:5]
	v_mfma_f32_16x16x32_bf16 v[14:17], v[162:165], v[194:197], v[14:17]
	v_mfma_f32_16x16x32_bf16 v[6:9], v[170:173], v[194:197], v[6:9]
	v_mfma_f32_16x16x32_bf16 v[22:25], v[162:165], v[202:205], v[22:25]
	v_mfma_f32_16x16x32_bf16 v[18:21], v[170:173], v[202:205], v[18:21]
	v_mfma_f32_16x16x32_bf16 v[38:41], v[162:165], v[210:213], v[38:41]
	v_mfma_f32_16x16x32_bf16 v[26:29], v[170:173], v[210:213], v[26:29]
	v_mfma_f32_16x16x32_bf16 v[10:13], v[166:169], v[190:193], v[10:13]
	v_mfma_f32_16x16x32_bf16 v[2:5], v[174:177], v[190:193], v[2:5]
	v_mfma_f32_16x16x32_bf16 v[14:17], v[166:169], v[198:201], v[14:17]
	v_mfma_f32_16x16x32_bf16 v[6:9], v[174:177], v[198:201], v[6:9]
	v_mfma_f32_16x16x32_bf16 v[22:25], v[166:169], v[206:209], v[22:25]
	v_mfma_f32_16x16x32_bf16 v[18:21], v[174:177], v[206:209], v[18:21]
	v_mfma_f32_16x16x32_bf16 v[38:41], v[166:169], v[214:217], v[38:41]
	v_mfma_f32_16x16x32_bf16 v[26:29], v[174:177], v[214:217], v[26:29]
	s_barrier
	s_setprio 0
	s_mov_b32 m0, s36
	s_add_u32 s48, s10, s4
	s_addc_u32 s49, s11, s5
	s_add_u32 s10, s10, 0x100080
	ds_read_b128 v[186:189], v142 offset:49152
	ds_read_b128 v[190:193], v142 offset:50176
	global_load_lds_dwordx4 v180, s[48:49]
	ds_read_b128 v[194:197], v142 offset:51200
	s_mov_b32 m0, s43
	s_addc_u32 s11, s11, 0
	global_load_lds_dwordx4 v134, s[48:49]
	ds_read_b128 v[198:201], v142 offset:52224
	s_mov_b32 m0, s37
	s_nop 0
	global_load_lds_dwordx4 v180, s[10:11]
	ds_read_b128 v[202:205], v142 offset:53248
	s_mov_b32 m0, s44
	s_nop 0
	global_load_lds_dwordx4 v134, s[10:11]
	ds_read_b128 v[206:209], v142 offset:54272
	s_mov_b32 m0, s40
	s_nop 0
	global_load_lds_dwordx4 v130, s[50:51]
	ds_read_b128 v[210:213], v142 offset:55296
	s_mov_b32 m0, s41
	s_nop 0
	global_load_lds_dwordx4 v132, s[50:51]
	s_add_i32 s18, s18, 2
	s_add_u32 s6, s6, 0x100
	s_addc_u32 s7, s7, 0
	s_cmp_gt_u32 s18, 61
	ds_read_b128 v[214:217], v142 offset:56320
	s_waitcnt vmcnt(8) lgkmcnt(0)
	s_barrier
	s_setprio 1
	v_mfma_f32_16x16x32_bf16 v[94:97], v[146:149], v[186:189], v[94:97]
	v_mfma_f32_16x16x32_bf16 v[86:89], v[154:157], v[186:189], v[86:89]
	v_mfma_f32_16x16x32_bf16 v[102:105], v[146:149], v[194:197], v[102:105]
	v_mfma_f32_16x16x32_bf16 v[98:101], v[154:157], v[194:197], v[98:101]
	v_mfma_f32_16x16x32_bf16 v[110:113], v[146:149], v[202:205], v[110:113]
	v_mfma_f32_16x16x32_bf16 v[106:109], v[154:157], v[202:205], v[106:109]
	v_mfma_f32_16x16x32_bf16 v[126:129], v[146:149], v[210:213], v[126:129]
	v_mfma_f32_16x16x32_bf16 v[122:125], v[154:157], v[210:213], v[122:125]
	v_mfma_f32_16x16x32_bf16 v[94:97], v[150:153], v[190:193], v[94:97]
	v_mfma_f32_16x16x32_bf16 v[86:89], v[158:161], v[190:193], v[86:89]
	v_mfma_f32_16x16x32_bf16 v[102:105], v[150:153], v[198:201], v[102:105]
	v_mfma_f32_16x16x32_bf16 v[98:101], v[158:161], v[198:201], v[98:101]
	v_mfma_f32_16x16x32_bf16 v[110:113], v[150:153], v[206:209], v[110:113]
	v_mfma_f32_16x16x32_bf16 v[106:109], v[158:161], v[206:209], v[106:109]
	v_mfma_f32_16x16x32_bf16 v[126:129], v[150:153], v[214:217], v[126:129]
	v_mfma_f32_16x16x32_bf16 v[122:125], v[158:161], v[214:217], v[122:125]
	s_setprio 0
	s_setprio 1
	v_mfma_f32_16x16x32_bf16 v[58:61], v[162:165], v[186:189], v[58:61]
	v_mfma_f32_16x16x32_bf16 v[46:49], v[170:173], v[186:189], v[46:49]
	v_mfma_f32_16x16x32_bf16 v[74:77], v[162:165], v[194:197], v[74:77]
	v_mfma_f32_16x16x32_bf16 v[66:69], v[170:173], v[194:197], v[66:69]
	v_mfma_f32_16x16x32_bf16 v[90:93], v[162:165], v[202:205], v[90:93]
	v_mfma_f32_16x16x32_bf16 v[82:85], v[170:173], v[202:205], v[82:85]
	v_mfma_f32_16x16x32_bf16 v[118:121], v[162:165], v[210:213], v[118:121]
	v_mfma_f32_16x16x32_bf16 v[114:117], v[170:173], v[210:213], v[114:117]
	v_mfma_f32_16x16x32_bf16 v[58:61], v[166:169], v[190:193], v[58:61]
	v_mfma_f32_16x16x32_bf16 v[46:49], v[174:177], v[190:193], v[46:49]
	v_mfma_f32_16x16x32_bf16 v[74:77], v[166:169], v[198:201], v[74:77]
	v_mfma_f32_16x16x32_bf16 v[66:69], v[174:177], v[198:201], v[66:69]
	v_mfma_f32_16x16x32_bf16 v[90:93], v[166:169], v[206:209], v[90:93]
	v_mfma_f32_16x16x32_bf16 v[82:85], v[174:177], v[206:209], v[82:85]
	v_mfma_f32_16x16x32_bf16 v[118:121], v[166:169], v[214:217], v[118:121]
	v_mfma_f32_16x16x32_bf16 v[114:117], v[174:177], v[214:217], v[114:117]
	s_barrier
	s_setprio 0
	s_cbranch_scc0 .LBB0_896
	s_cmpk_lt_u32 s22, 0x100
	s_cbranch_scc0 .LBB0_899
	s_barrier

; #define PG8_STAGE(bufoff, gbase, voff) do { _Pragma("unroll") for (int _i = 0; _i < 2; ++_i) \
;         __builtin_amdgcn_global_load_lds((const unsigned*)((const char*)(gbase) + (voff)[_i]), (LAS unsigned*)(lds + (bufoff) + ldsw + _i * 8192), 16, 0, 0); } while (0)
; #define PG8_LDA(dst, b, h) do { _Pragma("unroll") for (int m = 0; m < 4; ++m) _Pragma("unroll") for (int k = 0; k < 2; ++k) dst[m][k] = *(const LAS bf16x8*)(lds + PG8_SA(b, h) + aoff + m * 2048 + k * 1024); } while (0)
; #define PG8_LDB(dst, b, h) do { _Pragma("unroll") for (int n = 0; n < 2; ++n) _Pragma("unroll") for (int k = 0; k < 2; ++k) dst[n][k] = *(const LAS bf16x8*)(lds + PG8_SB(b, h) + boff + n * 2048 + k * 1024); } while (0)
; #define PG8_MMA(ai, bj, At, Bt) do { __builtin_amdgcn_s_setprio(1); _Pragma("unroll") for (int m = 0; m < 4; ++m) _Pragma("unroll") for (int n = 0; n < 2; ++n) _Pragma("unroll") for (int k = 0; k < 2; ++k) \
;         acc[ai][bj][m][n] = __builtin_amdgcn_mfma_f32_16x16x32_bf16(Bt[n][k], At[m][k], acc[ai][bj][m][n], 0, 0, 0); __builtin_amdgcn_s_setprio(0); } while (0)
; #define PG8_WAIT_V(n) asm volatile("s_waitcnt vmcnt(" #n ")" ::: "memory")
; #define PG8_WAIT_L(n) asm volatile("s_waitcnt lgkmcnt(" #n ")" ::: "memory")
; #define PG8_BAR __builtin_amdgcn_s_barrier()
; template <class Epi, class Sched, bool ALIGN_EPI, class Hook = NoHook>
; __device__ __forceinline__ void gemm_phase(LAS unsigned char* lds, const Gemm g, const Sched& S, const Epi& E, const Hook& H = Hook()) {
;     ...
;             const bool last = (t == nt - 2);
;             const char* a1 = cA + (size_t)(t + 1) * kstep;
;             const char* a2 = last ? nA : cA + (size_t)(t + 2) * kstep; const char* b2 = last ? nB : cB + (size_t)(t + 2) * kstep;
;             const char* a3 = a2 + kstep; const char* b3 = b2 + kstep;
;             if (last && has_next) S.a_ready(nxt);
;             PG8_LDB(B0, 0, 0); PG8_LDB(B1, 0, 1); PG8_SCHED; PG8_LDA(At, 0, 0); PG8_STAGE(PG8_SA(1, 1), a1 + hA, voffA);
;             PG8_WAIT_V(8); PG8_WAIT_L(0); PG8_BAR; PG8_MMA(0, 0, At, B0); PG8_MMA(0, 1, At, B1); PG8_BAR; PG8_SCHED;
;             PG8_LDA(At, 0, 1); PG8_STAGE(PG8_SB(0, 0), b2, voffB); PG8_STAGE(PG8_SB(0, 1), b2 + hB, voffB); PG8_STAGE(PG8_SA(0, 0), a2, voffA);
;             PG8_WAIT_V(8); PG8_WAIT_L(0); PG8_BAR; PG8_MMA(1, 0, At, B0); PG8_MMA(1, 1, At, B1); PG8_BAR; PG8_SCHED;
.LBB0_1001:
	ds_read_b128 v[106:109], v246
	ds_read_b128 v[110:113], v246 offset:1024
	s_add_u32 s42, s6, 0x100
	s_addc_u32 s43, s7, 0
	s_cmp_eq_u32 s70, 60
	s_cselect_b32 s47, s35, s43
	s_cselect_b32 s46, s66, s42
	s_cselect_b32 s45, s31, s69
	s_cselect_b32 s44, s67, s68
	s_add_i32 m0, s51, 0xc000
	s_nop 0
	global_load_lds_dwordx4 v236, s[6:7]
	ds_read_b128 v[114:117], v246 offset:2048
	ds_read_b128 v[118:121], v246 offset:3072
	ds_read_b128 v[122:125], v247
	ds_read_b128 v[126:129], v247 offset:1024
	ds_read_b128 v[130:133], v247 offset:2048
	ds_read_b128 v[134:137], v247 offset:3072
	ds_read_b128 v[138:141], v248
	s_add_i32 m0, s51, 0xe000
	s_nop 0
	global_load_lds_dwordx4 v238, s[6:7]
	ds_read_b128 v[142:145], v248 offset:1024
	ds_read_b128 v[146:149], v248 offset:2048
	ds_read_b128 v[150:153], v248 offset:3072
	ds_read_b128 v[154:157], v248 offset:4096
	ds_read_b128 v[158:161], v248 offset:5120
	ds_read_b128 v[162:165], v248 offset:6144
	ds_read_b128 v[170:173], v248 offset:7168
	s_waitcnt vmcnt(8) lgkmcnt(0)
	s_barrier
	s_setprio 1
	v_mfma_f32_16x16x32_bf16 v[190:193], v[106:109], v[138:141], v[190:193]
	v_mfma_f32_16x16x32_bf16 v[178:181], v[114:117], v[138:141], v[178:181]
	v_mfma_f32_16x16x32_bf16 v[182:185], v[106:109], v[146:149], v[182:185]
	v_mfma_f32_16x16x32_bf16 v[98:101], v[114:117], v[146:149], v[98:101]
	v_mfma_f32_16x16x32_bf16 v[102:105], v[106:109], v[154:157], v[102:105]
	v_mfma_f32_16x16x32_bf16 v[86:89], v[114:117], v[154:157], v[86:89]
	v_mfma_f32_16x16x32_bf16 v[78:81], v[106:109], v[162:165], v[78:81]
	v_mfma_f32_16x16x32_bf16 v[70:73], v[114:117], v[162:165], v[70:73]
	v_mfma_f32_16x16x32_bf16 v[190:193], v[110:113], v[142:145], v[190:193]
	v_mfma_f32_16x16x32_bf16 v[178:181], v[118:121], v[142:145], v[178:181]
	v_mfma_f32_16x16x32_bf16 v[182:185], v[110:113], v[150:153], v[182:185]
	v_mfma_f32_16x16x32_bf16 v[98:101], v[118:121], v[150:153], v[98:101]
	v_mfma_f32_16x16x32_bf16 v[102:105], v[110:113], v[158:161], v[102:105]
	v_mfma_f32_16x16x32_bf16 v[86:89], v[118:121], v[158:161], v[86:89]
	v_mfma_f32_16x16x32_bf16 v[78:81], v[110:113], v[170:173], v[78:81]
	v_mfma_f32_16x16x32_bf16 v[70:73], v[118:121], v[170:173], v[70:73]
	s_setprio 0
	s_setprio 1
	v_mfma_f32_16x16x32_bf16 v[186:189], v[122:125], v[138:141], v[186:189]
	v_mfma_f32_16x16x32_bf16 v[138:141], v[130:133], v[138:141], v[174:177]
	v_mfma_f32_16x16x32_bf16 v[94:97], v[130:133], v[146:149], v[94:97]
	v_mfma_f32_16x16x32_bf16 v[90:93], v[122:125], v[154:157], v[90:93]
	v_mfma_f32_16x16x32_bf16 v[82:85], v[130:133], v[154:157], v[82:85]
	v_mfma_f32_16x16x32_bf16 v[74:77], v[122:125], v[162:165], v[74:77]
	v_mfma_f32_16x16x32_bf16 v[66:69], v[130:133], v[162:165], v[66:69]
	v_mfma_f32_16x16x32_bf16 v[186:189], v[126:129], v[142:145], v[186:189]
	v_mfma_f32_16x16x32_bf16 v[138:141], v[134:137], v[142:145], v[138:141]
	v_mfma_f32_16x16x32_bf16 v[142:145], v[122:125], v[146:149], v[166:169]
	v_mfma_f32_16x16x32_bf16 v[94:97], v[134:137], v[150:153], v[94:97]
	v_mfma_f32_16x16x32_bf16 v[90:93], v[126:129], v[158:161], v[90:93]
	v_mfma_f32_16x16x32_bf16 v[82:85], v[134:137], v[158:161], v[82:85]
	v_mfma_f32_16x16x32_bf16 v[74:77], v[126:129], v[170:173], v[74:77]
	v_mfma_f32_16x16x32_bf16 v[66:69], v[134:137], v[170:173], v[66:69]
	v_mfma_f32_16x16x32_bf16 v[142:145], v[126:129], v[150:153], v[142:145]
	s_barrier
	s_setprio 0
	s_add_i32 s6, s63, s29
	s_mov_b32 m0, s6
	ds_read_b128 v[146:149], v248 offset:16384
	ds_read_b128 v[150:153], v248 offset:17408
	global_load_lds_dwordx4 v232, s[44:45]
	ds_read_b128 v[154:157], v248 offset:18432
	s_add_i32 m0, s6, 0x2000
	s_add_u32 s6, s44, 0x100000
	s_addc_u32 s7, s45, 0
	s_add_i32 s71, s64, s29
	global_load_lds_dwordx4 v228, s[44:45]
	ds_read_b128 v[158:161], v248 offset:19456
	s_mov_b32 m0, s71
	s_nop 0
	global_load_lds_dwordx4 v232, s[6:7]
	ds_read_b128 v[162:165], v248 offset:20480
	s_add_i32 m0, s71, 0x2000
	s_nop 0
	global_load_lds_dwordx4 v228, s[6:7]
	ds_read_b128 v[166:169], v248 offset:21504
	s_mov_b32 m0, s51
	s_nop 0
	global_load_lds_dwordx4 v234, s[46:47]
	ds_read_b128 v[170:173], v248 offset:22528
	s_mov_b32 m0, s52
	s_nop 0
	global_load_lds_dwordx4 v230, s[46:47]
	ds_read_b128 v[174:177], v248 offset:23552
	s_waitcnt vmcnt(8) lgkmcnt(0)
	s_barrier
	s_setprio 1
	v_mfma_f32_16x16x32_bf16 v[62:65], v[106:109], v[146:149], v[62:65]
	v_mfma_f32_16x16x32_bf16 v[54:57], v[114:117], v[146:149], v[54:57]
	v_mfma_f32_16x16x32_bf16 v[46:49], v[106:109], v[154:157], v[46:49]
	v_mfma_f32_16x16x32_bf16 v[22:25], v[114:117], v[154:157], v[22:25]
	v_mfma_f32_16x16x32_bf16 v[42:45], v[106:109], v[162:165], v[42:45]
	v_mfma_f32_16x16x32_bf16 v[10:13], v[114:117], v[162:165], v[10:13]
	v_mfma_f32_16x16x32_bf16 v[38:41], v[106:109], v[170:173], v[38:41]
	v_mfma_f32_16x16x32_bf16 v[14:17], v[114:117], v[170:173], v[14:17]
	v_mfma_f32_16x16x32_bf16 v[62:65], v[110:113], v[150:153], v[62:65]
	v_mfma_f32_16x16x32_bf16 v[54:57], v[118:121], v[150:153], v[54:57]
	v_mfma_f32_16x16x32_bf16 v[46:49], v[110:113], v[158:161], v[46:49]
	v_mfma_f32_16x16x32_bf16 v[22:25], v[118:121], v[158:161], v[22:25]
	v_mfma_f32_16x16x32_bf16 v[42:45], v[110:113], v[166:169], v[42:45]
	v_mfma_f32_16x16x32_bf16 v[10:13], v[118:121], v[166:169], v[10:13]
	v_mfma_f32_16x16x32_bf16 v[38:41], v[110:113], v[174:177], v[38:41]
	v_mfma_f32_16x16x32_bf16 v[14:17], v[118:121], v[174:177], v[14:17]
	s_setprio 0
	s_setprio 1
	v_mfma_f32_16x16x32_bf16 v[58:61], v[122:125], v[146:149], v[58:61]
	v_mfma_f32_16x16x32_bf16 v[50:53], v[130:133], v[146:149], v[50:53]
	v_mfma_f32_16x16x32_bf16 v[34:37], v[122:125], v[154:157], v[34:37]
	v_mfma_f32_16x16x32_bf16 v[18:21], v[130:133], v[154:157], v[18:21]
	v_mfma_f32_16x16x32_bf16 v[30:33], v[122:125], v[162:165], v[30:33]
	v_mfma_f32_16x16x32_bf16 v[2:5], v[130:133], v[162:165], v[2:5]
	v_mfma_f32_16x16x32_bf16 v[26:29], v[122:125], v[170:173], v[26:29]
	v_mfma_f32_16x16x32_bf16 v[6:9], v[130:133], v[170:173], v[6:9]
	v_mfma_f32_16x16x32_bf16 v[58:61], v[126:129], v[150:153], v[58:61]
	v_mfma_f32_16x16x32_bf16 v[50:53], v[134:137], v[150:153], v[50:53]
	v_mfma_f32_16x16x32_bf16 v[34:37], v[126:129], v[158:161], v[34:37]
	v_mfma_f32_16x16x32_bf16 v[18:21], v[134:137], v[158:161], v[18:21]
	v_mfma_f32_16x16x32_bf16 v[30:33], v[126:129], v[166:169], v[30:33]
	v_mfma_f32_16x16x32_bf16 v[2:5], v[134:137], v[166:169], v[2:5]
	v_mfma_f32_16x16x32_bf16 v[26:29], v[126:129], v[174:177], v[26:29]
	v_mfma_f32_16x16x32_bf16 v[6:9], v[134:137], v[174:177], v[6:9]
	s_barrier
; #define PG8_STAGE(bufoff, gbase, voff) do { _Pragma("unroll") for (int _i = 0; _i < 2; ++_i) \
;         __builtin_amdgcn_global_load_lds((const unsigned*)((const char*)(gbase) + (voff)[_i]), (LAS unsigned*)(lds + (bufoff) + ldsw + _i * 8192), 16, 0, 0); } while (0)
; #define PG8_LDA(dst, b, h) do { _Pragma("unroll") for (int m = 0; m < 4; ++m) _Pragma("unroll") for (int k = 0; k < 2; ++k) dst[m][k] = *(const LAS bf16x8*)(lds + PG8_SA(b, h) + aoff + m * 2048 + k * 1024); } while (0)
; #define PG8_LDB(dst, b, h) do { _Pragma("unroll") for (int n = 0; n < 2; ++n) _Pragma("unroll") for (int k = 0; k < 2; ++k) dst[n][k] = *(const LAS bf16x8*)(lds + PG8_SB(b, h) + boff + n * 2048 + k * 1024); } while (0)
; #define PG8_MMA(ai, bj, At, Bt) do { __builtin_amdgcn_s_setprio(1); _Pragma("unroll") for (int m = 0; m < 4; ++m) _Pragma("unroll") for (int n = 0; n < 2; ++n) _Pragma("unroll") for (int k = 0; k < 2; ++k) \
;         acc[ai][bj][m][n] = __builtin_amdgcn_mfma_f32_16x16x32_bf16(Bt[n][k], At[m][k], acc[ai][bj][m][n], 0, 0, 0); __builtin_amdgcn_s_setprio(0); } while (0)
; #define PG8_WAIT_V(n) asm volatile("s_waitcnt vmcnt(" #n ")" ::: "memory")
; #define PG8_WAIT_L(n) asm volatile("s_waitcnt lgkmcnt(" #n ")" ::: "memory")
; #define PG8_BAR __builtin_amdgcn_s_barrier()
; #define PG8_SCHED __builtin_amdgcn_sched_barrier(0)
; template <class Epi, class Sched, bool ALIGN_EPI, class Hook = NoHook>
; __device__ __forceinline__ void gemm_phase(LAS unsigned char* lds, const Gemm g, const Sched& S, const Epi& E, const Hook& H = Hook()) {
;     ...
;             PG8_LDB(B0, 1, 0); PG8_LDB(B1, 1, 1); PG8_SCHED; PG8_LDA(At, 1, 0); PG8_STAGE(PG8_SA(0, 1), a2 + hA, voffA);
;             PG8_WAIT_V(8); PG8_WAIT_L(0); PG8_BAR; PG8_MMA(0, 0, At, B0); PG8_MMA(0, 1, At, B1); PG8_BAR; PG8_SCHED;
;             PG8_LDA(At, 1, 1); PG8_STAGE(PG8_SB(1, 0), b3, voffB); PG8_STAGE(PG8_SB(1, 1), b3 + hB, voffB); PG8_STAGE(PG8_SA(1, 0), a3, voffA);
;             PG8_WAIT_V(8); PG8_WAIT_L(0); PG8_BAR; PG8_MMA(1, 0, At, B0); PG8_MMA(1, 1, At, B1); PG8_BAR; PG8_SCHED;
	s_setprio 0
	s_add_i32 s71, 0, 0x18000
	s_add_i32 s72, 0, 0x1c000
	v_add_u32_e32 v118, s71, v245
	v_add_u32_e32 v134, s72, v245
	ds_read_b128 v[106:109], v118
	ds_read_b128 v[110:113], v118 offset:1024
	s_add_u32 s6, s46, 0x8000
	s_addc_u32 s7, s47, 0
	s_mov_b32 m0, s53
	s_nop 0
	global_load_lds_dwordx4 v234, s[6:7]
	ds_read_b128 v[114:117], v118 offset:2048
	ds_read_b128 v[118:121], v118 offset:3072
	ds_read_b128 v[122:125], v134
	ds_read_b128 v[126:129], v134 offset:1024
	ds_read_b128 v[130:133], v134 offset:2048
	ds_read_b128 v[134:137], v134 offset:3072
	ds_read_b128 v[146:149], v248 offset:32768
	s_mov_b32 m0, s54
	s_nop 0
	global_load_lds_dwordx4 v230, s[6:7]
	ds_read_b128 v[150:153], v248 offset:33792
	ds_read_b128 v[154:157], v248 offset:34816
	ds_read_b128 v[158:161], v248 offset:35840
	ds_read_b128 v[162:165], v248 offset:36864
	ds_read_b128 v[170:173], v248 offset:37888
	ds_read_b128 v[194:197], v248 offset:38912
	ds_read_b128 v[198:201], v248 offset:39936
	s_waitcnt vmcnt(8) lgkmcnt(0)
	s_barrier
	s_setprio 1
	v_mfma_f32_16x16x32_bf16 v[166:169], v[106:109], v[146:149], v[190:193]
	v_mfma_f32_16x16x32_bf16 v[190:193], v[110:113], v[150:153], v[166:169]
	v_mfma_f32_16x16x32_bf16 v[166:169], v[114:117], v[146:149], v[178:181]
	v_mfma_f32_16x16x32_bf16 v[178:181], v[118:121], v[150:153], v[166:169]
	v_mfma_f32_16x16x32_bf16 v[166:169], v[106:109], v[154:157], v[182:185]
	v_mfma_f32_16x16x32_bf16 v[98:101], v[114:117], v[154:157], v[98:101]
	v_mfma_f32_16x16x32_bf16 v[102:105], v[106:109], v[162:165], v[102:105]
	v_mfma_f32_16x16x32_bf16 v[86:89], v[114:117], v[162:165], v[86:89]
	v_mfma_f32_16x16x32_bf16 v[78:81], v[106:109], v[194:197], v[78:81]
	v_mfma_f32_16x16x32_bf16 v[70:73], v[114:117], v[194:197], v[70:73]
	v_mfma_f32_16x16x32_bf16 v[182:185], v[110:113], v[158:161], v[166:169]
	v_mfma_f32_16x16x32_bf16 v[98:101], v[118:121], v[158:161], v[98:101]
	v_mfma_f32_16x16x32_bf16 v[102:105], v[110:113], v[170:173], v[102:105]
	v_mfma_f32_16x16x32_bf16 v[86:89], v[118:121], v[170:173], v[86:89]
	v_mfma_f32_16x16x32_bf16 v[78:81], v[110:113], v[198:201], v[78:81]
	v_mfma_f32_16x16x32_bf16 v[70:73], v[118:121], v[198:201], v[70:73]
	s_setprio 0
	s_setprio 1
	v_mfma_f32_16x16x32_bf16 v[138:141], v[130:133], v[146:149], v[138:141]
	v_mfma_f32_16x16x32_bf16 v[166:169], v[122:125], v[146:149], v[186:189]
	v_mfma_f32_16x16x32_bf16 v[174:177], v[134:137], v[150:153], v[138:141]
	v_mfma_f32_16x16x32_bf16 v[138:141], v[122:125], v[154:157], v[142:145]
	v_mfma_f32_16x16x32_bf16 v[94:97], v[130:133], v[154:157], v[94:97]
	v_mfma_f32_16x16x32_bf16 v[90:93], v[122:125], v[162:165], v[90:93]
	v_mfma_f32_16x16x32_bf16 v[82:85], v[130:133], v[162:165], v[82:85]
	v_mfma_f32_16x16x32_bf16 v[74:77], v[122:125], v[194:197], v[74:77]
	v_mfma_f32_16x16x32_bf16 v[66:69], v[130:133], v[194:197], v[66:69]
	v_mfma_f32_16x16x32_bf16 v[186:189], v[126:129], v[150:153], v[166:169]
	v_mfma_f32_16x16x32_bf16 v[166:169], v[126:129], v[158:161], v[138:141]
	v_mfma_f32_16x16x32_bf16 v[94:97], v[134:137], v[158:161], v[94:97]
	v_mfma_f32_16x16x32_bf16 v[90:93], v[126:129], v[170:173], v[90:93]
	v_mfma_f32_16x16x32_bf16 v[82:85], v[134:137], v[170:173], v[82:85]
	v_mfma_f32_16x16x32_bf16 v[74:77], v[126:129], v[198:201], v[74:77]
	v_mfma_f32_16x16x32_bf16 v[66:69], v[134:137], v[198:201], v[66:69]
	s_barrier
	s_setprio 0
	s_add_i32 s6, s71, s29
	s_add_u32 s74, s44, s14
	s_addc_u32 s75, s45, s15
	s_mov_b32 m0, s6
	ds_read_b128 v[138:141], v248 offset:49152
	ds_read_b128 v[142:145], v248 offset:50176
	global_load_lds_dwordx4 v232, s[74:75]
	ds_read_b128 v[146:149], v248 offset:51200
	s_add_i32 m0, s6, 0x2000
	s_add_u32 s6, s44, 0x100080
	s_addc_u32 s7, s45, 0
	s_add_i32 s44, s72, s29
	global_load_lds_dwordx4 v228, s[74:75]
	ds_read_b128 v[150:153], v248 offset:52224
	s_mov_b32 m0, s44
	s_nop 0
	global_load_lds_dwordx4 v232, s[6:7]
	ds_read_b128 v[154:157], v248 offset:53248
	s_add_i32 m0, s44, 0x2000
	s_nop 0
	global_load_lds_dwordx4 v228, s[6:7]
	ds_read_b128 v[158:161], v248 offset:54272
	s_add_u32 s78, s46, s14
	s_addc_u32 s79, s47, s15
	s_mov_b32 m0, s57
	s_nop 0
	global_load_lds_dwordx4 v234, s[78:79]
	ds_read_b128 v[162:165], v248 offset:55296
	s_mov_b32 m0, s58
	s_nop 0
	global_load_lds_dwordx4 v230, s[78:79]
	s_add_i32 s70, s70, 2
	s_add_u32 s68, s68, 0x100
	s_addc_u32 s69, s69, 0
	s_cmp_gt_u32 s70, 61
	s_mov_b64 s[6:7], s[42:43]
	ds_read_b128 v[170:173], v248 offset:56320
	s_waitcnt vmcnt(8) lgkmcnt(0)
	s_barrier
	s_setprio 1
	v_mfma_f32_16x16x32_bf16 v[62:65], v[106:109], v[138:141], v[62:65]
	v_mfma_f32_16x16x32_bf16 v[54:57], v[114:117], v[138:141], v[54:57]
	v_mfma_f32_16x16x32_bf16 v[46:49], v[106:109], v[146:149], v[46:49]
	v_mfma_f32_16x16x32_bf16 v[22:25], v[114:117], v[146:149], v[22:25]
	v_mfma_f32_16x16x32_bf16 v[42:45], v[106:109], v[154:157], v[42:45]
	v_mfma_f32_16x16x32_bf16 v[10:13], v[114:117], v[154:157], v[10:13]
	v_mfma_f32_16x16x32_bf16 v[38:41], v[106:109], v[162:165], v[38:41]
	v_mfma_f32_16x16x32_bf16 v[14:17], v[114:117], v[162:165], v[14:17]
	v_mfma_f32_16x16x32_bf16 v[62:65], v[110:113], v[142:145], v[62:65]
	v_mfma_f32_16x16x32_bf16 v[54:57], v[118:121], v[142:145], v[54:57]
	v_mfma_f32_16x16x32_bf16 v[46:49], v[110:113], v[150:153], v[46:49]
	v_mfma_f32_16x16x32_bf16 v[22:25], v[118:121], v[150:153], v[22:25]
	v_mfma_f32_16x16x32_bf16 v[42:45], v[110:113], v[158:161], v[42:45]
	v_mfma_f32_16x16x32_bf16 v[10:13], v[118:121], v[158:161], v[10:13]
	v_mfma_f32_16x16x32_bf16 v[38:41], v[110:113], v[170:173], v[38:41]
	v_mfma_f32_16x16x32_bf16 v[14:17], v[118:121], v[170:173], v[14:17]
	s_setprio 0
	s_setprio 1
	v_mfma_f32_16x16x32_bf16 v[58:61], v[122:125], v[138:141], v[58:61]
	v_mfma_f32_16x16x32_bf16 v[50:53], v[130:133], v[138:141], v[50:53]
	v_mfma_f32_16x16x32_bf16 v[34:37], v[122:125], v[146:149], v[34:37]
	v_mfma_f32_16x16x32_bf16 v[18:21], v[130:133], v[146:149], v[18:21]
	v_mfma_f32_16x16x32_bf16 v[30:33], v[122:125], v[154:157], v[30:33]
	v_mfma_f32_16x16x32_bf16 v[2:5], v[130:133], v[154:157], v[2:5]
	v_mfma_f32_16x16x32_bf16 v[26:29], v[122:125], v[162:165], v[26:29]
	v_mfma_f32_16x16x32_bf16 v[6:9], v[130:133], v[162:165], v[6:9]
	v_mfma_f32_16x16x32_bf16 v[58:61], v[126:129], v[142:145], v[58:61]
	v_mfma_f32_16x16x32_bf16 v[50:53], v[134:137], v[142:145], v[50:53]
	v_mfma_f32_16x16x32_bf16 v[34:37], v[126:129], v[150:153], v[34:37]
	v_mfma_f32_16x16x32_bf16 v[18:21], v[134:137], v[150:153], v[18:21]
	v_mfma_f32_16x16x32_bf16 v[30:33], v[126:129], v[158:161], v[30:33]
	v_mfma_f32_16x16x32_bf16 v[2:5], v[134:137], v[158:161], v[2:5]
	v_mfma_f32_16x16x32_bf16 v[26:29], v[126:129], v[170:173], v[26:29]
	v_mfma_f32_16x16x32_bf16 v[6:9], v[134:137], v[170:173], v[6:9]
	s_barrier
	s_setprio 0
	s_cbranch_scc0 .LBB0_1001
	s_and_b64 vcc, exec, s[2:3]
	s_cbranch_vccz .LBB0_1004
	s_barrier

; #define PG8_STAGE(bufoff, gbase, voff) do { _Pragma("unroll") for (int _i = 0; _i < 2; ++_i) \
;         __builtin_amdgcn_global_load_lds((const unsigned*)((const char*)(gbase) + (voff)[_i]), (LAS unsigned*)(lds + (bufoff) + ldsw + _i * 8192), 16, 0, 0); } while (0)
; #define PG8_LDA(dst, b, h) do { _Pragma("unroll") for (int m = 0; m < 4; ++m) _Pragma("unroll") for (int k = 0; k < 2; ++k) dst[m][k] = *(const LAS bf16x8*)(lds + PG8_SA(b, h) + aoff + m * 2048 + k * 1024); } while (0)
; #define PG8_LDB(dst, b, h) do { _Pragma("unroll") for (int n = 0; n < 2; ++n) _Pragma("unroll") for (int k = 0; k < 2; ++k) dst[n][k] = *(const LAS bf16x8*)(lds + PG8_SB(b, h) + boff + n * 2048 + k * 1024); } while (0)
; #define PG8_MMA(ai, bj, At, Bt) do { __builtin_amdgcn_s_setprio(1); _Pragma("unroll") for (int m = 0; m < 4; ++m) _Pragma("unroll") for (int n = 0; n < 2; ++n) _Pragma("unroll") for (int k = 0; k < 2; ++k) \
;         acc[ai][bj][m][n] = __builtin_amdgcn_mfma_f32_16x16x32_bf16(Bt[n][k], At[m][k], acc[ai][bj][m][n], 0, 0, 0); __builtin_amdgcn_s_setprio(0); } while (0)
; #define PG8_WAIT_V(n) asm volatile("s_waitcnt vmcnt(" #n ")" ::: "memory")
; #define PG8_WAIT_L(n) asm volatile("s_waitcnt lgkmcnt(" #n ")" ::: "memory")
; #define PG8_BAR __builtin_amdgcn_s_barrier()
; template <class Epi, class Sched, bool ALIGN_EPI, class Hook = NoHook>
; __device__ __forceinline__ void gemm_phase(LAS unsigned char* lds, const Gemm g, const Sched& S, const Epi& E, const Hook& H = Hook()) {
;     ...
;             const bool last = (t == nt - 2);
;             const char* a1 = cA + (size_t)(t + 1) * kstep;
;             const char* a2 = last ? nA : cA + (size_t)(t + 2) * kstep; const char* b2 = last ? nB : cB + (size_t)(t + 2) * kstep;
;             const char* a3 = a2 + kstep; const char* b3 = b2 + kstep;
;             if (last && has_next) S.a_ready(nxt);
;             PG8_LDB(B0, 0, 0); PG8_LDB(B1, 0, 1); PG8_SCHED; PG8_LDA(At, 0, 0); PG8_STAGE(PG8_SA(1, 1), a1 + hA, voffA);
;             PG8_WAIT_V(8); PG8_WAIT_L(0); PG8_BAR; PG8_MMA(0, 0, At, B0); PG8_MMA(0, 1, At, B1); PG8_BAR; PG8_SCHED;
;             PG8_LDA(At, 0, 1); PG8_STAGE(PG8_SB(0, 0), b2, voffB); PG8_STAGE(PG8_SB(0, 1), b2 + hB, voffB); PG8_STAGE(PG8_SA(0, 0), a2, voffA);
;             PG8_WAIT_V(8); PG8_WAIT_L(0); PG8_BAR; PG8_MMA(1, 0, At, B0); PG8_MMA(1, 1, At, B1); PG8_BAR; PG8_SCHED;
.LBB0_1360:
	ds_read_b128 v[146:149], v1
	ds_read_b128 v[150:153], v1 offset:1024
	s_add_u32 s14, s4, 0xbb050080
	s_addc_u32 s15, s5, -1
	s_cmpk_lg_i32 s41, 0xa8
	s_cselect_b32 s14, s14, 0
	s_cselect_b32 s15, s15, 0
	s_add_u32 s20, s0, s14
	s_addc_u32 s21, s1, s15
	s_add_u32 s14, s12, s14
	s_addc_u32 s15, s13, s15
	s_mov_b32 m0, s42
	ds_read_b128 v[154:157], v1 offset:2048
	ds_read_b128 v[158:161], v1 offset:3072
	ds_read_b128 v[164:167], v142
	ds_read_b128 v[170:173], v142 offset:1024
	ds_read_b128 v[174:177], v142 offset:2048
	ds_read_b128 v[178:181], v142 offset:3072
	v_lshl_add_u64 v[214:215], v[138:139], 0, s[4:5]
	global_load_lds_dwordx4 v[214:215], off
	ds_read_b128 v[182:185], v143
	ds_read_b128 v[186:189], v143 offset:1024
	ds_read_b128 v[190:193], v143 offset:2048
	ds_read_b128 v[194:197], v143 offset:3072
	ds_read_b128 v[198:201], v143 offset:4096
	ds_read_b128 v[202:205], v143 offset:5120
	ds_read_b128 v[206:209], v143 offset:6144
	ds_read_b128 v[210:213], v143 offset:7168
	v_lshl_add_u64 v[214:215], v[140:141], 0, s[4:5]
	s_mov_b32 m0, s43
	s_nop 0
	global_load_lds_dwordx4 v[214:215], off
	s_waitcnt vmcnt(8) lgkmcnt(0)
	s_barrier
	s_setprio 1
	v_mfma_f32_16x16x32_bf16 v[82:85], v[146:149], v[182:185], v[82:85]
	v_mfma_f32_16x16x32_bf16 v[54:57], v[154:157], v[182:185], v[54:57]
	v_mfma_f32_16x16x32_bf16 v[58:61], v[146:149], v[190:193], v[58:61]
	v_mfma_f32_16x16x32_bf16 v[42:45], v[154:157], v[190:193], v[42:45]
	v_mfma_f32_16x16x32_bf16 v[70:73], v[146:149], v[198:201], v[70:73]
	v_mfma_f32_16x16x32_bf16 v[50:53], v[154:157], v[198:201], v[50:53]
	v_mfma_f32_16x16x32_bf16 v[86:89], v[146:149], v[206:209], v[86:89]
	v_mfma_f32_16x16x32_bf16 v[74:77], v[154:157], v[206:209], v[74:77]
	v_mfma_f32_16x16x32_bf16 v[82:85], v[150:153], v[186:189], v[82:85]
	v_mfma_f32_16x16x32_bf16 v[54:57], v[158:161], v[186:189], v[54:57]
	v_mfma_f32_16x16x32_bf16 v[58:61], v[150:153], v[194:197], v[58:61]
	v_mfma_f32_16x16x32_bf16 v[42:45], v[158:161], v[194:197], v[42:45]
	v_mfma_f32_16x16x32_bf16 v[70:73], v[150:153], v[202:205], v[70:73]
	v_mfma_f32_16x16x32_bf16 v[50:53], v[158:161], v[202:205], v[50:53]
	v_mfma_f32_16x16x32_bf16 v[86:89], v[150:153], v[210:213], v[86:89]
	v_mfma_f32_16x16x32_bf16 v[74:77], v[158:161], v[210:213], v[74:77]
	s_setprio 0
	s_setprio 1
	v_mfma_f32_16x16x32_bf16 v[14:17], v[164:167], v[182:185], v[14:17]
	v_mfma_f32_16x16x32_bf16 v[2:5], v[174:177], v[182:185], v[2:5]
	v_mfma_f32_16x16x32_bf16 v[18:21], v[164:167], v[190:193], v[18:21]
	v_mfma_f32_16x16x32_bf16 v[6:9], v[174:177], v[190:193], v[6:9]
	v_mfma_f32_16x16x32_bf16 v[22:25], v[164:167], v[198:201], v[22:25]
	v_mfma_f32_16x16x32_bf16 v[10:13], v[174:177], v[198:201], v[10:13]
	v_mfma_f32_16x16x32_bf16 v[30:33], v[164:167], v[206:209], v[30:33]
	v_mfma_f32_16x16x32_bf16 v[26:29], v[174:177], v[206:209], v[26:29]
	v_mfma_f32_16x16x32_bf16 v[14:17], v[170:173], v[186:189], v[14:17]
	v_mfma_f32_16x16x32_bf16 v[2:5], v[178:181], v[186:189], v[2:5]
	v_mfma_f32_16x16x32_bf16 v[18:21], v[170:173], v[194:197], v[18:21]
	v_mfma_f32_16x16x32_bf16 v[6:9], v[178:181], v[194:197], v[6:9]
	v_mfma_f32_16x16x32_bf16 v[22:25], v[170:173], v[202:205], v[22:25]
	v_mfma_f32_16x16x32_bf16 v[10:13], v[178:181], v[202:205], v[10:13]
	v_mfma_f32_16x16x32_bf16 v[30:33], v[170:173], v[210:213], v[30:33]
	v_mfma_f32_16x16x32_bf16 v[26:29], v[178:181], v[210:213], v[26:29]
	s_barrier
	s_setprio 0
	s_mov_b32 m0, s44
	s_add_u32 s52, s14, 0x2b0000
	ds_read_b128 v[182:185], v143 offset:16384
	ds_read_b128 v[186:189], v143 offset:17408
	global_load_lds_dwordx4 v132, s[14:15]
	ds_read_b128 v[190:193], v143 offset:18432
	s_mov_b32 m0, s45
	s_addc_u32 s53, s15, 0
	global_load_lds_dwordx4 v136, s[14:15]
	ds_read_b128 v[194:197], v143 offset:19456
	s_mov_b32 m0, s46
	s_nop 0
	global_load_lds_dwordx4 v132, s[52:53]
	ds_read_b128 v[198:201], v143 offset:20480
	s_mov_b32 m0, s47
	s_nop 0
	global_load_lds_dwordx4 v136, s[52:53]
	ds_read_b128 v[202:205], v143 offset:21504
	s_add_u32 s56, s20, s2
	s_addc_u32 s57, s21, s3
	s_mov_b32 m0, s25
	s_nop 0
	global_load_lds_dwordx4 v130, s[20:21]
	ds_read_b128 v[206:209], v143 offset:22528
	s_mov_b32 m0, s27
	s_nop 0
	global_load_lds_dwordx4 v134, s[20:21]
	ds_read_b128 v[210:213], v143 offset:23552
	s_waitcnt vmcnt(8) lgkmcnt(0)
	s_barrier
	s_setprio 1
	v_mfma_f32_16x16x32_bf16 v[94:97], v[146:149], v[182:185], v[94:97]
	v_mfma_f32_16x16x32_bf16 v[90:93], v[154:157], v[182:185], v[90:93]
	v_mfma_f32_16x16x32_bf16 v[106:109], v[146:149], v[190:193], v[106:109]
	v_mfma_f32_16x16x32_bf16 v[98:101], v[154:157], v[190:193], v[98:101]
	v_mfma_f32_16x16x32_bf16 v[110:113], v[146:149], v[198:201], v[110:113]
	v_mfma_f32_16x16x32_bf16 v[102:105], v[154:157], v[198:201], v[102:105]
	v_mfma_f32_16x16x32_bf16 v[126:129], v[146:149], v[206:209], v[126:129]
	v_mfma_f32_16x16x32_bf16 v[122:125], v[154:157], v[206:209], v[122:125]
	v_mfma_f32_16x16x32_bf16 v[94:97], v[150:153], v[186:189], v[94:97]
	v_mfma_f32_16x16x32_bf16 v[90:93], v[158:161], v[186:189], v[90:93]
	v_mfma_f32_16x16x32_bf16 v[106:109], v[150:153], v[194:197], v[106:109]
	v_mfma_f32_16x16x32_bf16 v[98:101], v[158:161], v[194:197], v[98:101]
	v_mfma_f32_16x16x32_bf16 v[110:113], v[150:153], v[202:205], v[110:113]
	v_mfma_f32_16x16x32_bf16 v[102:105], v[158:161], v[202:205], v[102:105]
	v_mfma_f32_16x16x32_bf16 v[126:129], v[150:153], v[210:213], v[126:129]
	v_mfma_f32_16x16x32_bf16 v[122:125], v[158:161], v[210:213], v[122:125]
	s_setprio 0
	s_setprio 1
	v_mfma_f32_16x16x32_bf16 v[38:41], v[164:167], v[182:185], v[38:41]
	v_mfma_f32_16x16x32_bf16 v[34:37], v[174:177], v[182:185], v[34:37]
	v_mfma_f32_16x16x32_bf16 v[66:69], v[164:167], v[190:193], v[66:69]
	v_mfma_f32_16x16x32_bf16 v[46:49], v[174:177], v[190:193], v[46:49]
	v_mfma_f32_16x16x32_bf16 v[78:81], v[164:167], v[198:201], v[78:81]
	v_mfma_f32_16x16x32_bf16 v[62:65], v[174:177], v[198:201], v[62:65]
	v_mfma_f32_16x16x32_bf16 v[118:121], v[164:167], v[206:209], v[118:121]
	v_mfma_f32_16x16x32_bf16 v[114:117], v[174:177], v[206:209], v[114:117]
	v_mfma_f32_16x16x32_bf16 v[38:41], v[170:173], v[186:189], v[38:41]
	v_mfma_f32_16x16x32_bf16 v[34:37], v[178:181], v[186:189], v[34:37]
	v_mfma_f32_16x16x32_bf16 v[66:69], v[170:173], v[194:197], v[66:69]
	v_mfma_f32_16x16x32_bf16 v[46:49], v[178:181], v[194:197], v[46:49]
	v_mfma_f32_16x16x32_bf16 v[78:81], v[170:173], v[202:205], v[78:81]
	v_mfma_f32_16x16x32_bf16 v[62:65], v[178:181], v[202:205], v[62:65]
	v_mfma_f32_16x16x32_bf16 v[118:121], v[170:173], v[210:213], v[118:121]
	v_mfma_f32_16x16x32_bf16 v[114:117], v[178:181], v[210:213], v[114:117]
	s_barrier
; #define PG8_STAGE(bufoff, gbase, voff) do { _Pragma("unroll") for (int _i = 0; _i < 2; ++_i) \
;         __builtin_amdgcn_global_load_lds((const unsigned*)((const char*)(gbase) + (voff)[_i]), (LAS unsigned*)(lds + (bufoff) + ldsw + _i * 8192), 16, 0, 0); } while (0)
; #define PG8_LDA(dst, b, h) do { _Pragma("unroll") for (int m = 0; m < 4; ++m) _Pragma("unroll") for (int k = 0; k < 2; ++k) dst[m][k] = *(const LAS bf16x8*)(lds + PG8_SA(b, h) + aoff + m * 2048 + k * 1024); } while (0)
; #define PG8_LDB(dst, b, h) do { _Pragma("unroll") for (int n = 0; n < 2; ++n) _Pragma("unroll") for (int k = 0; k < 2; ++k) dst[n][k] = *(const LAS bf16x8*)(lds + PG8_SB(b, h) + boff + n * 2048 + k * 1024); } while (0)
; #define PG8_MMA(ai, bj, At, Bt) do { __builtin_amdgcn_s_setprio(1); _Pragma("unroll") for (int m = 0; m < 4; ++m) _Pragma("unroll") for (int n = 0; n < 2; ++n) _Pragma("unroll") for (int k = 0; k < 2; ++k) \
;         acc[ai][bj][m][n] = __builtin_amdgcn_mfma_f32_16x16x32_bf16(Bt[n][k], At[m][k], acc[ai][bj][m][n], 0, 0, 0); __builtin_amdgcn_s_setprio(0); } while (0)
; #define PG8_WAIT_V(n) asm volatile("s_waitcnt vmcnt(" #n ")" ::: "memory")
; #define PG8_WAIT_L(n) asm volatile("s_waitcnt lgkmcnt(" #n ")" ::: "memory")
; #define PG8_BAR __builtin_amdgcn_s_barrier()
; #define PG8_SCHED __builtin_amdgcn_sched_barrier(0)
; template <class Epi, class Sched, bool ALIGN_EPI, class Hook = NoHook>
; __device__ __forceinline__ void gemm_phase(LAS unsigned char* lds, const Gemm g, const Sched& S, const Epi& E, const Hook& H = Hook()) {
;     ...
;             PG8_LDB(B0, 1, 0); PG8_LDB(B1, 1, 1); PG8_SCHED; PG8_LDA(At, 1, 0); PG8_STAGE(PG8_SA(0, 1), a2 + hA, voffA);
;             PG8_WAIT_V(8); PG8_WAIT_L(0); PG8_BAR; PG8_MMA(0, 0, At, B0); PG8_MMA(0, 1, At, B1); PG8_BAR; PG8_SCHED;
;             PG8_LDA(At, 1, 1); PG8_STAGE(PG8_SB(1, 0), b3, voffB); PG8_STAGE(PG8_SB(1, 1), b3 + hB, voffB); PG8_STAGE(PG8_SA(1, 0), a3, voffA);
;             PG8_WAIT_V(8); PG8_WAIT_L(0); PG8_BAR; PG8_MMA(1, 0, At, B0); PG8_MMA(1, 1, At, B1); PG8_BAR; PG8_SCHED;
	s_setprio 0
	ds_read_b128 v[146:149], v144
	ds_read_b128 v[150:153], v144 offset:1024
	s_add_u32 s20, s20, 0x2b0000
	s_addc_u32 s21, s21, 0
	s_mov_b32 m0, s28
	s_nop 0
	global_load_lds_dwordx4 v130, s[20:21]
	ds_read_b128 v[154:157], v144 offset:2048
	ds_read_b128 v[158:161], v144 offset:3072
	ds_read_b128 v[164:167], v145
	ds_read_b128 v[170:173], v145 offset:1024
	ds_read_b128 v[174:177], v145 offset:2048
	ds_read_b128 v[178:181], v145 offset:3072
	ds_read_b128 v[182:185], v143 offset:32768
	s_mov_b32 m0, s38
	s_nop 0
	global_load_lds_dwordx4 v134, s[20:21]
	ds_read_b128 v[186:189], v143 offset:33792
	ds_read_b128 v[190:193], v143 offset:34816
	ds_read_b128 v[194:197], v143 offset:35840
	ds_read_b128 v[198:201], v143 offset:36864
	ds_read_b128 v[202:205], v143 offset:37888
	ds_read_b128 v[206:209], v143 offset:38912
	ds_read_b128 v[210:213], v143 offset:39936
	s_waitcnt vmcnt(8) lgkmcnt(0)
	s_barrier
	s_setprio 1
	v_mfma_f32_16x16x32_bf16 v[82:85], v[146:149], v[182:185], v[82:85]
	v_mfma_f32_16x16x32_bf16 v[54:57], v[154:157], v[182:185], v[54:57]
	v_mfma_f32_16x16x32_bf16 v[58:61], v[146:149], v[190:193], v[58:61]
	v_mfma_f32_16x16x32_bf16 v[42:45], v[154:157], v[190:193], v[42:45]
	v_mfma_f32_16x16x32_bf16 v[70:73], v[146:149], v[198:201], v[70:73]
	v_mfma_f32_16x16x32_bf16 v[50:53], v[154:157], v[198:201], v[50:53]
	v_mfma_f32_16x16x32_bf16 v[86:89], v[146:149], v[206:209], v[86:89]
	v_mfma_f32_16x16x32_bf16 v[74:77], v[154:157], v[206:209], v[74:77]
	v_mfma_f32_16x16x32_bf16 v[82:85], v[150:153], v[186:189], v[82:85]
	v_mfma_f32_16x16x32_bf16 v[54:57], v[158:161], v[186:189], v[54:57]
	v_mfma_f32_16x16x32_bf16 v[58:61], v[150:153], v[194:197], v[58:61]
	v_mfma_f32_16x16x32_bf16 v[42:45], v[158:161], v[194:197], v[42:45]
	v_mfma_f32_16x16x32_bf16 v[70:73], v[150:153], v[202:205], v[70:73]
	v_mfma_f32_16x16x32_bf16 v[50:53], v[158:161], v[202:205], v[50:53]
	v_mfma_f32_16x16x32_bf16 v[86:89], v[150:153], v[210:213], v[86:89]
	v_mfma_f32_16x16x32_bf16 v[74:77], v[158:161], v[210:213], v[74:77]
	s_setprio 0
	s_setprio 1
	v_mfma_f32_16x16x32_bf16 v[14:17], v[164:167], v[182:185], v[14:17]
	v_mfma_f32_16x16x32_bf16 v[2:5], v[174:177], v[182:185], v[2:5]
	v_mfma_f32_16x16x32_bf16 v[18:21], v[164:167], v[190:193], v[18:21]
	v_mfma_f32_16x16x32_bf16 v[6:9], v[174:177], v[190:193], v[6:9]
	v_mfma_f32_16x16x32_bf16 v[22:25], v[164:167], v[198:201], v[22:25]
	v_mfma_f32_16x16x32_bf16 v[10:13], v[174:177], v[198:201], v[10:13]
	v_mfma_f32_16x16x32_bf16 v[30:33], v[164:167], v[206:209], v[30:33]
	v_mfma_f32_16x16x32_bf16 v[26:29], v[174:177], v[206:209], v[26:29]
	v_mfma_f32_16x16x32_bf16 v[14:17], v[170:173], v[186:189], v[14:17]
	v_mfma_f32_16x16x32_bf16 v[2:5], v[178:181], v[186:189], v[2:5]
	v_mfma_f32_16x16x32_bf16 v[18:21], v[170:173], v[194:197], v[18:21]
	v_mfma_f32_16x16x32_bf16 v[6:9], v[178:181], v[194:197], v[6:9]
	v_mfma_f32_16x16x32_bf16 v[22:25], v[170:173], v[202:205], v[22:25]
	v_mfma_f32_16x16x32_bf16 v[10:13], v[178:181], v[202:205], v[10:13]
	v_mfma_f32_16x16x32_bf16 v[30:33], v[170:173], v[210:213], v[30:33]
	v_mfma_f32_16x16x32_bf16 v[26:29], v[178:181], v[210:213], v[26:29]
	s_barrier
	s_setprio 0
	s_mov_b32 m0, s48
	s_add_u32 s54, s14, s2
	s_addc_u32 s55, s15, s3
	s_add_u32 s14, s14, 0x2b0080
	ds_read_b128 v[182:185], v143 offset:49152
	ds_read_b128 v[186:189], v143 offset:50176
	global_load_lds_dwordx4 v132, s[54:55]
	ds_read_b128 v[190:193], v143 offset:51200
	s_mov_b32 m0, s49
	s_addc_u32 s15, s15, 0
	global_load_lds_dwordx4 v136, s[54:55]
	ds_read_b128 v[194:197], v143 offset:52224
	s_mov_b32 m0, s50
	s_nop 0
	global_load_lds_dwordx4 v132, s[14:15]
	ds_read_b128 v[198:201], v143 offset:53248
	s_mov_b32 m0, s51
	s_nop 0
	global_load_lds_dwordx4 v136, s[14:15]
	ds_read_b128 v[202:205], v143 offset:54272
	s_mov_b32 m0, s39
	s_nop 0
	global_load_lds_dwordx4 v130, s[56:57]
	ds_read_b128 v[206:209], v143 offset:55296
	s_mov_b32 m0, s40
	s_nop 0
	global_load_lds_dwordx4 v134, s[56:57]
	s_add_i32 s41, s41, 2
	s_add_u32 s4, s4, 0x100
	s_addc_u32 s5, s5, 0
	s_cmpk_gt_u32 s41, 0xa9
	ds_read_b128 v[210:213], v143 offset:56320
	s_waitcnt vmcnt(8) lgkmcnt(0)
	s_barrier
	s_setprio 1
	v_mfma_f32_16x16x32_bf16 v[94:97], v[146:149], v[182:185], v[94:97]
	v_mfma_f32_16x16x32_bf16 v[90:93], v[154:157], v[182:185], v[90:93]
	v_mfma_f32_16x16x32_bf16 v[106:109], v[146:149], v[190:193], v[106:109]
	v_mfma_f32_16x16x32_bf16 v[98:101], v[154:157], v[190:193], v[98:101]
	v_mfma_f32_16x16x32_bf16 v[110:113], v[146:149], v[198:201], v[110:113]
	v_mfma_f32_16x16x32_bf16 v[102:105], v[154:157], v[198:201], v[102:105]
	v_mfma_f32_16x16x32_bf16 v[126:129], v[146:149], v[206:209], v[126:129]
	v_mfma_f32_16x16x32_bf16 v[122:125], v[154:157], v[206:209], v[122:125]
	v_mfma_f32_16x16x32_bf16 v[94:97], v[150:153], v[186:189], v[94:97]
	v_mfma_f32_16x16x32_bf16 v[90:93], v[158:161], v[186:189], v[90:93]
	v_mfma_f32_16x16x32_bf16 v[106:109], v[150:153], v[194:197], v[106:109]
	v_mfma_f32_16x16x32_bf16 v[98:101], v[158:161], v[194:197], v[98:101]
	v_mfma_f32_16x16x32_bf16 v[110:113], v[150:153], v[202:205], v[110:113]
	v_mfma_f32_16x16x32_bf16 v[102:105], v[158:161], v[202:205], v[102:105]
	v_mfma_f32_16x16x32_bf16 v[126:129], v[150:153], v[210:213], v[126:129]
	v_mfma_f32_16x16x32_bf16 v[122:125], v[158:161], v[210:213], v[122:125]
	s_setprio 0
	s_setprio 1
	v_mfma_f32_16x16x32_bf16 v[38:41], v[164:167], v[182:185], v[38:41]
	v_mfma_f32_16x16x32_bf16 v[34:37], v[174:177], v[182:185], v[34:37]
	v_mfma_f32_16x16x32_bf16 v[66:69], v[164:167], v[190:193], v[66:69]
	v_mfma_f32_16x16x32_bf16 v[46:49], v[174:177], v[190:193], v[46:49]
	v_mfma_f32_16x16x32_bf16 v[78:81], v[164:167], v[198:201], v[78:81]
	v_mfma_f32_16x16x32_bf16 v[62:65], v[174:177], v[198:201], v[62:65]
	v_mfma_f32_16x16x32_bf16 v[118:121], v[164:167], v[206:209], v[118:121]
	v_mfma_f32_16x16x32_bf16 v[114:117], v[174:177], v[206:209], v[114:117]
	v_mfma_f32_16x16x32_bf16 v[38:41], v[170:173], v[186:189], v[38:41]
	v_mfma_f32_16x16x32_bf16 v[34:37], v[178:181], v[186:189], v[34:37]
	v_mfma_f32_16x16x32_bf16 v[66:69], v[170:173], v[194:197], v[66:69]
	v_mfma_f32_16x16x32_bf16 v[46:49], v[178:181], v[194:197], v[46:49]
	v_mfma_f32_16x16x32_bf16 v[78:81], v[170:173], v[202:205], v[78:81]
	v_mfma_f32_16x16x32_bf16 v[62:65], v[178:181], v[202:205], v[62:65]
	v_mfma_f32_16x16x32_bf16 v[118:121], v[170:173], v[210:213], v[118:121]
	v_mfma_f32_16x16x32_bf16 v[114:117], v[178:181], v[210:213], v[114:117]
	s_barrier
	s_setprio 0
	s_cbranch_scc0 .LBB0_1360
	s_cmpk_lt_u32 s26, 0x100
	s_cbranch_scc0 .LBB0_1363
	s_barrier

; #define PG8_STAGE(bufoff, gbase, voff) do { _Pragma("unroll") for (int _i = 0; _i < 2; ++_i) \
;         __builtin_amdgcn_global_load_lds((const unsigned*)((const char*)(gbase) + (voff)[_i]), (LAS unsigned*)(lds + (bufoff) + ldsw + _i * 8192), 16, 0, 0); } while (0)
; #define PG8_LDA(dst, b, h) do { _Pragma("unroll") for (int m = 0; m < 4; ++m) _Pragma("unroll") for (int k = 0; k < 2; ++k) dst[m][k] = *(const LAS bf16x8*)(lds + PG8_SA(b, h) + aoff + m * 2048 + k * 1024); } while (0)
; #define PG8_LDB(dst, b, h) do { _Pragma("unroll") for (int n = 0; n < 2; ++n) _Pragma("unroll") for (int k = 0; k < 2; ++k) dst[n][k] = *(const LAS bf16x8*)(lds + PG8_SB(b, h) + boff + n * 2048 + k * 1024); } while (0)
; #define PG8_MMA(ai, bj, At, Bt) do { __builtin_amdgcn_s_setprio(1); _Pragma("unroll") for (int m = 0; m < 4; ++m) _Pragma("unroll") for (int n = 0; n < 2; ++n) _Pragma("unroll") for (int k = 0; k < 2; ++k) \
;         acc[ai][bj][m][n] = __builtin_amdgcn_mfma_f32_16x16x32_bf16(Bt[n][k], At[m][k], acc[ai][bj][m][n], 0, 0, 0); __builtin_amdgcn_s_setprio(0); } while (0)
; #define PG8_WAIT_V(n) asm volatile("s_waitcnt vmcnt(" #n ")" ::: "memory")
; #define PG8_WAIT_L(n) asm volatile("s_waitcnt lgkmcnt(" #n ")" ::: "memory")
; #define PG8_BAR __builtin_amdgcn_s_barrier()
; template <class Epi, class Sched, bool ALIGN_EPI, class Hook = NoHook>
; __device__ __forceinline__ void gemm_phase(LAS unsigned char* lds, const Gemm g, const Sched& S, const Epi& E, const Hook& H = Hook()) {
;     ...
;             const bool last = (t == nt - 2);
;             const char* a1 = cA + (size_t)(t + 1) * kstep;
;             const char* a2 = last ? nA : cA + (size_t)(t + 2) * kstep; const char* b2 = last ? nB : cB + (size_t)(t + 2) * kstep;
;             const char* a3 = a2 + kstep; const char* b3 = b2 + kstep;
;             if (last && has_next) S.a_ready(nxt);
;             PG8_LDB(B0, 0, 0); PG8_LDB(B1, 0, 1); PG8_SCHED; PG8_LDA(At, 0, 0); PG8_STAGE(PG8_SA(1, 1), a1 + hA, voffA);
;             PG8_WAIT_V(8); PG8_WAIT_L(0); PG8_BAR; PG8_MMA(0, 0, At, B0); PG8_MMA(0, 1, At, B1); PG8_BAR; PG8_SCHED;
;             PG8_LDA(At, 0, 1); PG8_STAGE(PG8_SB(0, 0), b2, voffB); PG8_STAGE(PG8_SB(0, 1), b2 + hB, voffB); PG8_STAGE(PG8_SA(0, 0), a2, voffA);
;             PG8_WAIT_V(8); PG8_WAIT_L(0); PG8_BAR; PG8_MMA(1, 0, At, B0); PG8_MMA(1, 1, At, B1); PG8_BAR; PG8_SCHED;
.LBB0_1406:
	ds_read_b128 v[146:149], v140
	ds_read_b128 v[150:153], v140 offset:1024
	s_add_u32 s10, s4, 0xbb050080
	s_addc_u32 s11, s5, -1
	s_cmpk_lg_i32 s18, 0xa8
	s_cselect_b32 s10, s10, 0
	s_cselect_b32 s11, s11, 0
	s_add_u32 s16, s0, s10
	s_addc_u32 s17, s1, s11
	s_add_u32 s10, s12, s10
	s_addc_u32 s11, s13, s11
	s_mov_b32 m0, s19
	ds_read_b128 v[154:157], v140 offset:2048
	ds_read_b128 v[158:161], v140 offset:3072
	ds_read_b128 v[170:173], v141
	ds_read_b128 v[174:177], v141 offset:1024
	ds_read_b128 v[178:181], v141 offset:2048
	ds_read_b128 v[182:185], v141 offset:3072
	v_lshl_add_u64 v[218:219], v[136:137], 0, s[4:5]
	global_load_lds_dwordx4 v[218:219], off
	ds_read_b128 v[186:189], v142
	ds_read_b128 v[190:193], v142 offset:1024
	ds_read_b128 v[194:197], v142 offset:2048
	ds_read_b128 v[198:201], v142 offset:3072
	ds_read_b128 v[202:205], v142 offset:4096
	ds_read_b128 v[206:209], v142 offset:5120
	ds_read_b128 v[210:213], v142 offset:6144
	ds_read_b128 v[214:217], v142 offset:7168
	v_lshl_add_u64 v[218:219], v[138:139], 0, s[4:5]
	s_mov_b32 m0, s31
	s_nop 0
	global_load_lds_dwordx4 v[218:219], off
	s_waitcnt vmcnt(8) lgkmcnt(0)
	s_barrier
	s_setprio 1
	v_mfma_f32_16x16x32_bf16 v[82:85], v[146:149], v[186:189], v[82:85]
	v_mfma_f32_16x16x32_bf16 v[54:57], v[154:157], v[186:189], v[54:57]
	v_mfma_f32_16x16x32_bf16 v[58:61], v[146:149], v[194:197], v[58:61]
	v_mfma_f32_16x16x32_bf16 v[42:45], v[154:157], v[194:197], v[42:45]
	v_mfma_f32_16x16x32_bf16 v[70:73], v[146:149], v[202:205], v[70:73]
	v_mfma_f32_16x16x32_bf16 v[50:53], v[154:157], v[202:205], v[50:53]
	v_mfma_f32_16x16x32_bf16 v[86:89], v[146:149], v[210:213], v[86:89]
	v_mfma_f32_16x16x32_bf16 v[74:77], v[154:157], v[210:213], v[74:77]
	v_mfma_f32_16x16x32_bf16 v[82:85], v[150:153], v[190:193], v[82:85]
	v_mfma_f32_16x16x32_bf16 v[54:57], v[158:161], v[190:193], v[54:57]
	v_mfma_f32_16x16x32_bf16 v[58:61], v[150:153], v[198:201], v[58:61]
	v_mfma_f32_16x16x32_bf16 v[42:45], v[158:161], v[198:201], v[42:45]
	v_mfma_f32_16x16x32_bf16 v[70:73], v[150:153], v[206:209], v[70:73]
	v_mfma_f32_16x16x32_bf16 v[50:53], v[158:161], v[206:209], v[50:53]
	v_mfma_f32_16x16x32_bf16 v[86:89], v[150:153], v[214:217], v[86:89]
	v_mfma_f32_16x16x32_bf16 v[74:77], v[158:161], v[214:217], v[74:77]
	s_setprio 0
	s_setprio 1
	v_mfma_f32_16x16x32_bf16 v[14:17], v[170:173], v[186:189], v[14:17]
	v_mfma_f32_16x16x32_bf16 v[2:5], v[178:181], v[186:189], v[2:5]
	v_mfma_f32_16x16x32_bf16 v[18:21], v[170:173], v[194:197], v[18:21]
	v_mfma_f32_16x16x32_bf16 v[6:9], v[178:181], v[194:197], v[6:9]
	v_mfma_f32_16x16x32_bf16 v[22:25], v[170:173], v[202:205], v[22:25]
	v_mfma_f32_16x16x32_bf16 v[10:13], v[178:181], v[202:205], v[10:13]
	v_mfma_f32_16x16x32_bf16 v[30:33], v[170:173], v[210:213], v[30:33]
	v_mfma_f32_16x16x32_bf16 v[26:29], v[178:181], v[210:213], v[26:29]
	v_mfma_f32_16x16x32_bf16 v[14:17], v[174:177], v[190:193], v[14:17]
	v_mfma_f32_16x16x32_bf16 v[2:5], v[182:185], v[190:193], v[2:5]
	v_mfma_f32_16x16x32_bf16 v[18:21], v[174:177], v[198:201], v[18:21]
	v_mfma_f32_16x16x32_bf16 v[6:9], v[182:185], v[198:201], v[6:9]
	v_mfma_f32_16x16x32_bf16 v[22:25], v[174:177], v[206:209], v[22:25]
	v_mfma_f32_16x16x32_bf16 v[10:13], v[182:185], v[206:209], v[10:13]
	v_mfma_f32_16x16x32_bf16 v[30:33], v[174:177], v[214:217], v[30:33]
	v_mfma_f32_16x16x32_bf16 v[26:29], v[182:185], v[214:217], v[26:29]
	s_barrier
	s_setprio 0
	s_mov_b32 m0, s33
	s_add_u32 s46, s10, 0x2b0000
	ds_read_b128 v[186:189], v142 offset:16384
	ds_read_b128 v[190:193], v142 offset:17408
	global_load_lds_dwordx4 v162, s[10:11]
	ds_read_b128 v[194:197], v142 offset:18432
	s_mov_b32 m0, s34
	s_addc_u32 s47, s11, 0
	global_load_lds_dwordx4 v134, s[10:11]
	ds_read_b128 v[198:201], v142 offset:19456
	s_mov_b32 m0, s35
	s_nop 0
	global_load_lds_dwordx4 v162, s[46:47]
	ds_read_b128 v[202:205], v142 offset:20480
	s_mov_b32 m0, s43
	s_nop 0
	global_load_lds_dwordx4 v134, s[46:47]
	ds_read_b128 v[206:209], v142 offset:21504
	s_add_u32 s54, s16, s2
	s_addc_u32 s55, s17, s3
	s_mov_b32 m0, s27
	s_nop 0
	global_load_lds_dwordx4 v130, s[16:17]
	ds_read_b128 v[210:213], v142 offset:22528
	s_mov_b32 m0, s28
	s_nop 0
	global_load_lds_dwordx4 v132, s[16:17]
	ds_read_b128 v[214:217], v142 offset:23552
	s_waitcnt vmcnt(8) lgkmcnt(0)
	s_barrier
	s_setprio 1
	v_mfma_f32_16x16x32_bf16 v[94:97], v[146:149], v[186:189], v[94:97]
	v_mfma_f32_16x16x32_bf16 v[90:93], v[154:157], v[186:189], v[90:93]
	v_mfma_f32_16x16x32_bf16 v[118:121], v[146:149], v[194:197], v[118:121]
	v_mfma_f32_16x16x32_bf16 v[98:101], v[154:157], v[194:197], v[98:101]
	v_mfma_f32_16x16x32_bf16 v[126:129], v[146:149], v[202:205], v[126:129]
	v_mfma_f32_16x16x32_bf16 v[110:113], v[154:157], v[202:205], v[110:113]
	v_mfma_f32_16x16x32_bf16 v[122:125], v[146:149], v[210:213], v[122:125]
	v_mfma_f32_16x16x32_bf16 v[114:117], v[154:157], v[210:213], v[114:117]
	v_mfma_f32_16x16x32_bf16 v[94:97], v[150:153], v[190:193], v[94:97]
	v_mfma_f32_16x16x32_bf16 v[90:93], v[158:161], v[190:193], v[90:93]
	v_mfma_f32_16x16x32_bf16 v[118:121], v[150:153], v[198:201], v[118:121]
	v_mfma_f32_16x16x32_bf16 v[98:101], v[158:161], v[198:201], v[98:101]
	v_mfma_f32_16x16x32_bf16 v[126:129], v[150:153], v[206:209], v[126:129]
	v_mfma_f32_16x16x32_bf16 v[110:113], v[158:161], v[206:209], v[110:113]
	v_mfma_f32_16x16x32_bf16 v[122:125], v[150:153], v[214:217], v[122:125]
	v_mfma_f32_16x16x32_bf16 v[114:117], v[158:161], v[214:217], v[114:117]
	s_setprio 0
	s_setprio 1
	v_mfma_f32_16x16x32_bf16 v[38:41], v[170:173], v[186:189], v[38:41]
	v_mfma_f32_16x16x32_bf16 v[34:37], v[178:181], v[186:189], v[34:37]
	v_mfma_f32_16x16x32_bf16 v[66:69], v[170:173], v[194:197], v[66:69]
	v_mfma_f32_16x16x32_bf16 v[46:49], v[178:181], v[194:197], v[46:49]
	v_mfma_f32_16x16x32_bf16 v[78:81], v[170:173], v[202:205], v[78:81]
	v_mfma_f32_16x16x32_bf16 v[62:65], v[178:181], v[202:205], v[62:65]
	v_mfma_f32_16x16x32_bf16 v[106:109], v[170:173], v[210:213], v[106:109]
	v_mfma_f32_16x16x32_bf16 v[102:105], v[178:181], v[210:213], v[102:105]
	v_mfma_f32_16x16x32_bf16 v[38:41], v[174:177], v[190:193], v[38:41]
	v_mfma_f32_16x16x32_bf16 v[34:37], v[182:185], v[190:193], v[34:37]
	v_mfma_f32_16x16x32_bf16 v[66:69], v[174:177], v[198:201], v[66:69]
	v_mfma_f32_16x16x32_bf16 v[46:49], v[182:185], v[198:201], v[46:49]
	v_mfma_f32_16x16x32_bf16 v[78:81], v[174:177], v[206:209], v[78:81]
	v_mfma_f32_16x16x32_bf16 v[62:65], v[182:185], v[206:209], v[62:65]
	v_mfma_f32_16x16x32_bf16 v[106:109], v[174:177], v[214:217], v[106:109]
	v_mfma_f32_16x16x32_bf16 v[102:105], v[182:185], v[214:217], v[102:105]
	s_barrier
; #define PG8_STAGE(bufoff, gbase, voff) do { _Pragma("unroll") for (int _i = 0; _i < 2; ++_i) \
;         __builtin_amdgcn_global_load_lds((const unsigned*)((const char*)(gbase) + (voff)[_i]), (LAS unsigned*)(lds + (bufoff) + ldsw + _i * 8192), 16, 0, 0); } while (0)
; #define PG8_LDA(dst, b, h) do { _Pragma("unroll") for (int m = 0; m < 4; ++m) _Pragma("unroll") for (int k = 0; k < 2; ++k) dst[m][k] = *(const LAS bf16x8*)(lds + PG8_SA(b, h) + aoff + m * 2048 + k * 1024); } while (0)
; #define PG8_LDB(dst, b, h) do { _Pragma("unroll") for (int n = 0; n < 2; ++n) _Pragma("unroll") for (int k = 0; k < 2; ++k) dst[n][k] = *(const LAS bf16x8*)(lds + PG8_SB(b, h) + boff + n * 2048 + k * 1024); } while (0)
; #define PG8_BAR __builtin_amdgcn_s_barrier()
; template <class Epi, class Sched, bool ALIGN_EPI, class Hook = NoHook>
; __device__ __forceinline__ void gemm_phase(LAS unsigned char* lds, const Gemm g, const Sched& S, const Epi& E, const Hook& H = Hook()) {
;     ...
;         for (int t = tb; t < te; t += 2) {
;             const bool last = (t == nt - 2);
;             const char* a1 = cA + (size_t)(t + 1) * kstep;
;             const char* a2 = last ? nA : cA + (size_t)(t + 2) * kstep; const char* b2 = last ? nB : cB + (size_t)(t + 2) * kstep;
;             const char* a3 = a2 + kstep; const char* b3 = b2 + kstep;
;             if (last && has_next) S.a_ready(nxt);
;             PG8_LDB(B0, 0, 0); PG8_LDB(B1, 0, 1); PG8_SCHED; PG8_LDA(At, 0, 0); PG8_STAGE(PG8_SA(1, 1), a1 + hA, voffA);
;             PG8_WAIT_V(8); PG8_WAIT_L(0); PG8_BAR; PG8_MMA(0, 0, At, B0); PG8_MMA(0, 1, At, B1); PG8_BAR; PG8_SCHED;
;             PG8_LDA(At, 0, 1); PG8_STAGE(PG8_SB(0, 0), b2, voffB); PG8_STAGE(PG8_SB(0, 1), b2 + hB, voffB); PG8_STAGE(PG8_SA(0, 0), a2, voffA);
;             PG8_WAIT_V(8); PG8_WAIT_L(0); PG8_BAR; PG8_MMA(1, 0, At, B0); PG8_MMA(1, 1, At, B1); PG8_BAR; PG8_SCHED;
;             PG8_LDB(B0, 1, 0); PG8_LDB(B1, 1, 1); PG8_SCHED; PG8_LDA(At, 1, 0); PG8_STAGE(PG8_SA(0, 1), a2 + hA, voffA);
;             PG8_WAIT_V(8); PG8_WAIT_L(0); PG8_BAR; PG8_MMA(0, 0, At, B0); PG8_MMA(0, 1, At, B1); PG8_BAR; PG8_SCHED;
;             PG8_LDA(At, 1, 1); PG8_STAGE(PG8_SB(1, 0), b3, voffB); PG8_STAGE(PG8_SB(1, 1), b3 + hB, voffB); PG8_STAGE(PG8_SA(1, 0), a3, voffA);
;             PG8_WAIT_V(8); PG8_WAIT_L(0); PG8_BAR; PG8_MMA(1, 0, At, B0); PG8_MMA(1, 1, At, B1); PG8_BAR; PG8_SCHED;
	s_setprio 0
	ds_read_b128 v[146:149], v143
	ds_read_b128 v[150:153], v143 offset:1024
	s_add_u32 s16, s16, 0x2b0000
	s_addc_u32 s17, s17, 0
	s_mov_b32 m0, s29
	s_nop 0
	global_load_lds_dwordx4 v130, s[16:17]
	ds_read_b128 v[154:157], v143 offset:2048
	ds_read_b128 v[158:161], v143 offset:3072
	ds_read_b128 v[170:173], v144
	ds_read_b128 v[174:177], v144 offset:1024
	ds_read_b128 v[178:181], v144 offset:2048
	ds_read_b128 v[182:185], v144 offset:3072
	ds_read_b128 v[186:189], v142 offset:32768
	s_mov_b32 m0, s39
	s_nop 0
	global_load_lds_dwordx4 v132, s[16:17]
	ds_read_b128 v[190:193], v142 offset:33792
	ds_read_b128 v[194:197], v142 offset:34816
	ds_read_b128 v[198:201], v142 offset:35840
	ds_read_b128 v[202:205], v142 offset:36864
	ds_read_b128 v[206:209], v142 offset:37888
	ds_read_b128 v[210:213], v142 offset:38912
	ds_read_b128 v[214:217], v142 offset:39936
	s_waitcnt vmcnt(8) lgkmcnt(0)
	s_barrier
	s_setprio 1
	v_mfma_f32_16x16x32_bf16 v[82:85], v[146:149], v[186:189], v[82:85]
	v_mfma_f32_16x16x32_bf16 v[54:57], v[154:157], v[186:189], v[54:57]
	v_mfma_f32_16x16x32_bf16 v[58:61], v[146:149], v[194:197], v[58:61]
	v_mfma_f32_16x16x32_bf16 v[42:45], v[154:157], v[194:197], v[42:45]
	v_mfma_f32_16x16x32_bf16 v[70:73], v[146:149], v[202:205], v[70:73]
	v_mfma_f32_16x16x32_bf16 v[50:53], v[154:157], v[202:205], v[50:53]
	v_mfma_f32_16x16x32_bf16 v[86:89], v[146:149], v[210:213], v[86:89]
	v_mfma_f32_16x16x32_bf16 v[74:77], v[154:157], v[210:213], v[74:77]
	v_mfma_f32_16x16x32_bf16 v[82:85], v[150:153], v[190:193], v[82:85]
	v_mfma_f32_16x16x32_bf16 v[54:57], v[158:161], v[190:193], v[54:57]
	v_mfma_f32_16x16x32_bf16 v[58:61], v[150:153], v[198:201], v[58:61]
	v_mfma_f32_16x16x32_bf16 v[42:45], v[158:161], v[198:201], v[42:45]
	v_mfma_f32_16x16x32_bf16 v[70:73], v[150:153], v[206:209], v[70:73]
	v_mfma_f32_16x16x32_bf16 v[50:53], v[158:161], v[206:209], v[50:53]
	v_mfma_f32_16x16x32_bf16 v[86:89], v[150:153], v[214:217], v[86:89]
	v_mfma_f32_16x16x32_bf16 v[74:77], v[158:161], v[214:217], v[74:77]
	s_setprio 0
	s_setprio 1
	v_mfma_f32_16x16x32_bf16 v[14:17], v[170:173], v[186:189], v[14:17]
	v_mfma_f32_16x16x32_bf16 v[2:5], v[178:181], v[186:189], v[2:5]
	v_mfma_f32_16x16x32_bf16 v[18:21], v[170:173], v[194:197], v[18:21]
	v_mfma_f32_16x16x32_bf16 v[6:9], v[178:181], v[194:197], v[6:9]
	v_mfma_f32_16x16x32_bf16 v[22:25], v[170:173], v[202:205], v[22:25]
	v_mfma_f32_16x16x32_bf16 v[10:13], v[178:181], v[202:205], v[10:13]
	v_mfma_f32_16x16x32_bf16 v[30:33], v[170:173], v[210:213], v[30:33]
	v_mfma_f32_16x16x32_bf16 v[26:29], v[178:181], v[210:213], v[26:29]
	v_mfma_f32_16x16x32_bf16 v[14:17], v[174:177], v[190:193], v[14:17]
	v_mfma_f32_16x16x32_bf16 v[2:5], v[182:185], v[190:193], v[2:5]
	v_mfma_f32_16x16x32_bf16 v[18:21], v[174:177], v[198:201], v[18:21]
	v_mfma_f32_16x16x32_bf16 v[6:9], v[182:185], v[198:201], v[6:9]
	v_mfma_f32_16x16x32_bf16 v[22:25], v[174:177], v[206:209], v[22:25]
	v_mfma_f32_16x16x32_bf16 v[10:13], v[182:185], v[206:209], v[10:13]
	v_mfma_f32_16x16x32_bf16 v[30:33], v[174:177], v[214:217], v[30:33]
	v_mfma_f32_16x16x32_bf16 v[26:29], v[182:185], v[214:217], v[26:29]
	s_barrier
	s_setprio 0
	s_mov_b32 m0, s36
	s_add_u32 s52, s10, s2
	s_addc_u32 s53, s11, s3
	s_add_u32 s10, s10, 0x2b0080
	ds_read_b128 v[186:189], v142 offset:49152
	ds_read_b128 v[190:193], v142 offset:50176
	global_load_lds_dwordx4 v162, s[52:53]
	ds_read_b128 v[194:197], v142 offset:51200
	s_mov_b32 m0, s44
	s_addc_u32 s11, s11, 0
	global_load_lds_dwordx4 v134, s[52:53]
	ds_read_b128 v[198:201], v142 offset:52224
	s_mov_b32 m0, s37
	s_nop 0
	global_load_lds_dwordx4 v162, s[10:11]
	ds_read_b128 v[202:205], v142 offset:53248
	s_mov_b32 m0, s45
	s_nop 0
	global_load_lds_dwordx4 v134, s[10:11]
	ds_read_b128 v[206:209], v142 offset:54272
	s_mov_b32 m0, s41
	s_nop 0
	global_load_lds_dwordx4 v130, s[54:55]
	ds_read_b128 v[210:213], v142 offset:55296
	s_mov_b32 m0, s42
	s_nop 0
	global_load_lds_dwordx4 v132, s[54:55]
	s_add_i32 s18, s18, 2
	s_add_u32 s4, s4, 0x100
	s_addc_u32 s5, s5, 0
	s_cmpk_gt_u32 s18, 0xa9
	ds_read_b128 v[214:217], v142 offset:56320
	s_waitcnt vmcnt(8) lgkmcnt(0)
	s_barrier
	s_setprio 1
	v_mfma_f32_16x16x32_bf16 v[94:97], v[146:149], v[186:189], v[94:97]
	v_mfma_f32_16x16x32_bf16 v[90:93], v[154:157], v[186:189], v[90:93]
	v_mfma_f32_16x16x32_bf16 v[118:121], v[146:149], v[194:197], v[118:121]
	v_mfma_f32_16x16x32_bf16 v[98:101], v[154:157], v[194:197], v[98:101]
	v_mfma_f32_16x16x32_bf16 v[126:129], v[146:149], v[202:205], v[126:129]
	v_mfma_f32_16x16x32_bf16 v[110:113], v[154:157], v[202:205], v[110:113]
	v_mfma_f32_16x16x32_bf16 v[122:125], v[146:149], v[210:213], v[122:125]
	v_mfma_f32_16x16x32_bf16 v[114:117], v[154:157], v[210:213], v[114:117]
	v_mfma_f32_16x16x32_bf16 v[94:97], v[150:153], v[190:193], v[94:97]
	v_mfma_f32_16x16x32_bf16 v[90:93], v[158:161], v[190:193], v[90:93]
	v_mfma_f32_16x16x32_bf16 v[118:121], v[150:153], v[198:201], v[118:121]
	v_mfma_f32_16x16x32_bf16 v[98:101], v[158:161], v[198:201], v[98:101]
	v_mfma_f32_16x16x32_bf16 v[126:129], v[150:153], v[206:209], v[126:129]
	v_mfma_f32_16x16x32_bf16 v[110:113], v[158:161], v[206:209], v[110:113]
	v_mfma_f32_16x16x32_bf16 v[122:125], v[150:153], v[214:217], v[122:125]
	v_mfma_f32_16x16x32_bf16 v[114:117], v[158:161], v[214:217], v[114:117]
	s_setprio 0
	s_setprio 1
	v_mfma_f32_16x16x32_bf16 v[38:41], v[170:173], v[186:189], v[38:41]
	v_mfma_f32_16x16x32_bf16 v[34:37], v[178:181], v[186:189], v[34:37]
	v_mfma_f32_16x16x32_bf16 v[66:69], v[170:173], v[194:197], v[66:69]
	v_mfma_f32_16x16x32_bf16 v[46:49], v[178:181], v[194:197], v[46:49]
	v_mfma_f32_16x16x32_bf16 v[78:81], v[170:173], v[202:205], v[78:81]
	v_mfma_f32_16x16x32_bf16 v[62:65], v[178:181], v[202:205], v[62:65]
	v_mfma_f32_16x16x32_bf16 v[106:109], v[170:173], v[210:213], v[106:109]
	v_mfma_f32_16x16x32_bf16 v[102:105], v[178:181], v[210:213], v[102:105]
	v_mfma_f32_16x16x32_bf16 v[38:41], v[174:177], v[190:193], v[38:41]
	v_mfma_f32_16x16x32_bf16 v[34:37], v[182:185], v[190:193], v[34:37]
	v_mfma_f32_16x16x32_bf16 v[66:69], v[174:177], v[198:201], v[66:69]
	v_mfma_f32_16x16x32_bf16 v[46:49], v[182:185], v[198:201], v[46:49]
	v_mfma_f32_16x16x32_bf16 v[78:81], v[174:177], v[206:209], v[78:81]
	v_mfma_f32_16x16x32_bf16 v[62:65], v[182:185], v[206:209], v[62:65]
	v_mfma_f32_16x16x32_bf16 v[106:109], v[174:177], v[214:217], v[106:109]
	v_mfma_f32_16x16x32_bf16 v[102:105], v[182:185], v[214:217], v[102:105]
	s_barrier
	s_setprio 0
	s_cbranch_scc0 .LBB0_1406
	s_cmpk_lt_u32 s22, 0x100
	s_cbranch_scc0 .LBB0_1409
	s_barrier
